# combined version + P6 f32-MFMA result shadow filled with the block-3 B-fragment loads and their address math (one s_nop 3 removed)
# speedup vs baseline: 1.0004x; 1.0004x over previous
.LBB0_685:
	s_or_b64 exec, exec, s[62:63]
	s_waitcnt lgkmcnt(0)
	v_sub_f32_e32 v43, v131, v43
	v_mul_f32_e32 v43, 0x3fb8aa3b, v43
	v_sub_f32_e32 v42, v131, v42
	v_exp_f32_e32 v43, v43
	v_mul_f32_e32 v42, 0x3fb8aa3b, v42
	v_sub_f32_e32 v41, v131, v41
	v_exp_f32_e32 v42, v42
	v_mul_f32_e32 v41, 0x3fb8aa3b, v41
	v_sub_f32_e32 v40, v131, v40
	v_exp_f32_e32 v41, v41
	v_mul_f32_e32 v40, 0x3fb8aa3b, v40
	v_mul_f32_e32 v44, 0x3db504f3, v49
	v_exp_f32_e32 v40, v40
	v_mul_f32_e32 v43, v44, v43
	v_mul_f32_e32 v44, 0x3db504f3, v48
	v_mul_f32_e32 v42, v44, v42
	v_mul_f32_e32 v44, 0x3db504f3, v47
	v_mul_f32_e32 v41, v44, v41
	v_mul_f32_e32 v44, 0x3db504f3, v46
	v_sub_f32_e32 v45, v162, v131
	v_mul_f32_e32 v40, v44, v40
	v_sub_f32_e32 v44, v162, v130
	v_mul_f32_e32 v45, 0x3fb8aa3b, v45
	v_mul_f32_e32 v44, 0x3fb8aa3b, v44
	v_exp_f32_e32 v45, v45
	v_exp_f32_e32 v44, v44
	v_mul_f32_e32 v17, v17, v163
	v_mul_f32_e32 v33, v33, v163
	v_mul_f32_e32 v17, v17, v45
	v_mul_f32_e32 v211, v33, v44
	v_cndmask_b32_e64 v62, 0, v17, s[60:61]
	v_sub_f32_e32 v17, v160, v130
	v_sub_f32_e32 v33, v160, v131
	v_mul_f32_e32 v17, 0x3fb8aa3b, v17
	v_mul_f32_e32 v33, 0x3fb8aa3b, v33
	v_exp_f32_e32 v17, v17
	v_exp_f32_e32 v33, v33
	v_mul_f32_e32 v32, v32, v161
	v_mul_f32_e32 v16, v16, v161
	v_mul_f32_e32 v212, v32, v17
	v_mul_f32_e32 v16, v16, v33
	v_sub_f32_e32 v17, v158, v131
	v_cndmask_b32_e64 v66, 0, v16, s[58:59]
	v_sub_f32_e32 v16, v158, v130
	v_mul_f32_e32 v17, 0x3fb8aa3b, v17
	v_mul_f32_e32 v16, 0x3fb8aa3b, v16
	v_exp_f32_e32 v17, v17
	v_exp_f32_e32 v16, v16
	v_mul_f32_e32 v15, v15, v159
	v_mul_f32_e32 v31, v31, v159
	v_mul_f32_e32 v15, v15, v17
	v_mul_f32_e32 v213, v31, v16
	v_cndmask_b32_e64 v70, 0, v15, s[56:57]
	v_sub_f32_e32 v15, v156, v130
	v_sub_f32_e32 v16, v156, v131
	v_mul_f32_e32 v15, 0x3fb8aa3b, v15
	v_mul_f32_e32 v16, 0x3fb8aa3b, v16
	v_exp_f32_e32 v15, v15
	v_exp_f32_e32 v16, v16
	v_mul_f32_e32 v17, v30, v157
	v_mul_f32_e32 v14, v14, v157
	v_mul_f32_e32 v214, v17, v15
	v_mul_f32_e32 v14, v14, v16
	v_sub_f32_e32 v15, v154, v130
	v_sub_f32_e32 v16, v154, v131
	v_mul_f32_e32 v15, 0x3fb8aa3b, v15
	v_mul_f32_e32 v16, 0x3fb8aa3b, v16
	v_exp_f32_e32 v15, v15
	v_exp_f32_e32 v16, v16
	v_mul_f32_e32 v17, v29, v155
	v_mul_f32_e32 v13, v13, v155
	v_mul_f32_e32 v215, v17, v15
	v_mul_f32_e32 v13, v13, v16
	v_sub_f32_e32 v15, v152, v131
	v_cndmask_b32_e64 v74, 0, v13, s[52:53]
	v_sub_f32_e32 v13, v152, v130
	v_mul_f32_e32 v15, 0x3fb8aa3b, v15
	v_mul_f32_e32 v13, 0x3fb8aa3b, v13
	v_exp_f32_e32 v15, v15
	v_exp_f32_e32 v13, v13
	v_mul_f32_e32 v12, v12, v153
	v_mul_f32_e32 v16, v28, v153
	v_mul_f32_e32 v12, v12, v15
	v_mul_f32_e32 v216, v16, v13
	v_cndmask_b32_e64 v28, 0, v12, s[50:51]
	v_sub_f32_e32 v12, v150, v130
	v_sub_f32_e32 v13, v150, v131
	v_mul_f32_e32 v12, 0x3fb8aa3b, v12
	v_mul_f32_e32 v13, 0x3fb8aa3b, v13
	v_exp_f32_e32 v12, v12
	v_exp_f32_e32 v13, v13
	v_mul_f32_e32 v15, v27, v151
	v_mul_f32_e32 v11, v11, v151
	v_mul_f32_e32 v217, v15, v12
	v_mul_f32_e32 v11, v11, v13
	v_sub_f32_e32 v12, v148, v131
	v_cndmask_b32_e64 v78, 0, v11, s[48:49]
	v_sub_f32_e32 v11, v148, v130
	v_mul_f32_e32 v12, 0x3fb8aa3b, v12
	v_mul_f32_e32 v11, 0x3fb8aa3b, v11
	v_exp_f32_e32 v12, v12
	v_exp_f32_e32 v11, v11
	v_mul_f32_e32 v10, v10, v149
	v_mul_f32_e32 v13, v26, v149
	v_mul_f32_e32 v10, v10, v12
	v_mul_f32_e32 v218, v13, v11
	v_cndmask_b32_e64 v82, 0, v10, s[46:47]
	v_sub_f32_e32 v10, v146, v130
	v_sub_f32_e32 v11, v146, v131
	v_mul_f32_e32 v10, 0x3fb8aa3b, v10
	v_mul_f32_e32 v11, 0x3fb8aa3b, v11
	v_exp_f32_e32 v10, v10
	v_exp_f32_e32 v11, v11
	v_mul_f32_e32 v12, v25, v147
	v_mul_f32_e32 v9, v9, v147
	v_mul_f32_e32 v219, v12, v10
	v_mul_f32_e32 v9, v9, v11
	v_sub_f32_e32 v10, v144, v131
	v_cndmask_b32_e64 v84, 0, v9, s[44:45]
	v_sub_f32_e32 v9, v144, v130
	v_mul_f32_e32 v10, 0x3fb8aa3b, v10
	v_mul_f32_e32 v9, 0x3fb8aa3b, v9
	v_exp_f32_e32 v10, v10
	v_exp_f32_e32 v9, v9
	v_mul_f32_e32 v8, v8, v145
	v_mul_f32_e32 v11, v24, v145
	v_mul_f32_e32 v8, v8, v10
	v_mul_f32_e32 v220, v11, v9
	v_cndmask_b32_e64 v24, 0, v8, s[42:43]
	v_sub_f32_e32 v8, v142, v130
	v_sub_f32_e32 v9, v142, v131
	v_mul_f32_e32 v8, 0x3fb8aa3b, v8
	v_mul_f32_e32 v9, 0x3fb8aa3b, v9
	v_exp_f32_e32 v8, v8
	v_exp_f32_e32 v9, v9
	v_mul_f32_e32 v10, v23, v143
	v_mul_f32_e32 v7, v7, v143
	v_mul_f32_e32 v221, v10, v8
	v_mul_f32_e32 v7, v7, v9
	v_sub_f32_e32 v8, v140, v131
	v_cndmask_b32_e64 v142, 0, v7, s[40:41]
	v_sub_f32_e32 v7, v140, v130
	v_mul_f32_e32 v8, 0x3fb8aa3b, v8
	v_mul_f32_e32 v7, 0x3fb8aa3b, v7
	v_exp_f32_e32 v8, v8
	v_exp_f32_e32 v7, v7
	v_mul_f32_e32 v6, v6, v141
	v_mul_f32_e32 v9, v22, v141
	v_mul_f32_e32 v6, v6, v8
	v_sub_f32_e32 v8, v138, v131
	v_mul_f32_e32 v222, v9, v7
	v_sub_f32_e32 v7, v138, v130
	v_mul_f32_e32 v8, 0x3fb8aa3b, v8
	v_mul_f32_e32 v7, 0x3fb8aa3b, v7
	v_exp_f32_e32 v8, v8
	v_exp_f32_e32 v7, v7
	v_mul_f32_e32 v5, v5, v139
	v_mul_f32_e32 v9, v21, v139
	v_mul_f32_e32 v5, v5, v8
	v_mul_f32_e32 v223, v9, v7
	v_cndmask_b32_e64 v140, 0, v5, s[8:9]
	v_sub_f32_e32 v5, v136, v130
	v_sub_f32_e32 v7, v136, v131
	v_mul_f32_e32 v5, 0x3fb8aa3b, v5
	v_mul_f32_e32 v7, 0x3fb8aa3b, v7
	v_exp_f32_e32 v5, v5
	v_exp_f32_e32 v7, v7
	v_mul_f32_e32 v8, v20, v137
	v_mul_f32_e32 v4, v4, v137
	v_mul_f32_e32 v224, v8, v5
	v_mul_f32_e32 v4, v4, v7
	v_sub_f32_e32 v5, v134, v131
	v_cndmask_b32_e64 v144, 0, v4, s[6:7]
	v_sub_f32_e32 v4, v134, v130
	v_mul_f32_e32 v5, 0x3fb8aa3b, v5
	v_mul_f32_e32 v4, 0x3fb8aa3b, v4
	v_exp_f32_e32 v5, v5
	v_exp_f32_e32 v4, v4
	v_mul_f32_e32 v3, v3, v135
	v_mul_f32_e32 v7, v19, v135
	v_mul_f32_e32 v3, v3, v5
	v_mul_f32_e32 v225, v7, v4
	v_cndmask_b32_e64 v146, v3, 0, s[4:5]
	v_sub_f32_e32 v3, v132, v130
	v_sub_f32_e32 v4, v132, v131
	v_mul_f32_e32 v3, 0x3fb8aa3b, v3
	v_mul_f32_e32 v4, 0x3fb8aa3b, v4
	v_exp_f32_e32 v3, v3
	v_exp_f32_e32 v4, v4
	v_mul_f32_e32 v5, v18, v133
	v_mul_f32_e32 v2, v2, v133
	v_mul_f32_e32 v226, v5, v3
	v_mul_f32_e32 v2, v2, v4
	v_cvt_pk_bf16_f32 v4, v40, v41
	v_cvt_pk_bf16_f32 v5, v42, v43
	global_store_dwordx2 v[34:35], v[4:5], off offset:48
	v_cvt_pk_bf16_f32 v4, v36, v38
	v_cvt_pk_bf16_f32 v5, v37, v39
	global_store_dwordx2 v[34:35], v[4:5], off offset:112
	v_cndmask_b32_e64 v14, 0, v14, s[54:55]
	v_cndmask_b32_e64 v6, 0, v6, s[38:39]
	v_cndmask_b32_e64 v2, 0, v2, s[0:1]
	v_lshlrev_b64 v[86:87], 1, v[128:129]
	s_add_u32 s0, s94, s28
	v_lshl_add_u64 v[4:5], v[122:123], 0, v[86:87]
	s_addc_u32 s1, s95, s29
	v_lshl_add_u64 v[98:99], s[0:1], 0, v[4:5]
	s_mov_b32 s4, 0x9000000
	v_add_co_u32_e32 v4, vcc, s4, v98
	s_mov_b32 s4, 0x9001000
	s_nop 0
	v_addc_co_u32_e32 v5, vcc, 0, v99, vcc
	v_add_co_u32_e32 v8, vcc, s4, v98
	v_lshlrev_b32_e32 v90, 4, v126
	s_nop 0
	v_addc_co_u32_e32 v9, vcc, 0, v99, vcc
	v_cmp_eq_u32_e32 vcc, 63, v126
	global_load_dwordx4 v[58:61], v[4:5], off offset:32
	global_load_dwordx4 v[54:57], v[4:5], off offset:64
	global_load_dwordx4 v[18:21], v[8:9], off offset:-4096
	global_load_dwordx4 v[50:53], v[4:5], off offset:96
	global_load_dwordx4 v[46:49], v[8:9], off
	global_load_dwordx4 v[42:45], v[8:9], off offset:32
	global_load_dwordx4 v[38:41], v[8:9], off offset:64
	global_load_dwordx4 v[34:37], v[8:9], off offset:96
	v_cndmask_b32_e64 v89, 0, 1.0, vcc
	v_cmp_eq_u32_e32 vcc, 62, v126
	v_add_u32_e32 v92, 0x1000, v90
	v_ashrrev_i32_e32 v93, 31, v92
	v_cndmask_b32_e64 v3, 0, 1.0, vcc
	v_cmp_eq_u32_e32 vcc, 61, v126
	v_lshl_add_u64 v[120:121], v[92:93], 1, s[0:1]
	v_add_u32_e32 v92, 0x1400, v90
	v_cndmask_b32_e64 v4, 0, 1.0, vcc
	v_cmp_eq_u32_e32 vcc, 60, v126
	v_ashrrev_i32_e32 v93, 31, v92
	v_lshl_add_u64 v[112:113], v[92:93], 1, s[0:1]
	v_cndmask_b32_e64 v8, 0, 1.0, vcc
	v_cmp_eq_u32_e32 vcc, 59, v126
	v_add_u32_e32 v92, 0x800, v90
	v_ashrrev_i32_e32 v91, 31, v90
	v_cndmask_b32_e64 v5, 0, 1.0, vcc
	v_cmp_eq_u32_e32 vcc, 58, v126
	v_ashrrev_i32_e32 v93, 31, v92
	v_add_u32_e32 v100, 0x1800, v90
	v_cndmask_b32_e64 v9, 0, 1.0, vcc
	v_cmp_eq_u32_e32 vcc, 57, v126
	v_lshl_add_u64 v[108:109], v[92:93], 1, s[0:1]
	v_add_u32_e32 v92, 0xc00, v90
	v_cndmask_b32_e64 v95, 0, 1.0, vcc
	v_cmp_eq_u32_e32 vcc, 56, v126
	s_nop 7
	s_mov_b32 s54, 62
	s_nop 0
	v_readlane_b32 s4, v62, s54
	s_nop 1
	v_fma_f32 v3, -s4, v89, v3
	s_mov_b32 s55, 61
	v_cndmask_b32_e64 v181, 0, 1.0, vcc
	v_cmp_eq_u32_e32 vcc, 55, v126
	v_add_f32_e32 v88, 0, v3
	s_nop 0
	v_readlane_b32 s4, v66, s55
	s_nop 1
	v_fma_f32 v4, -s4, v88, v4
	v_ashrrev_i32_e32 v101, 31, v100
	v_cndmask_b32_e64 v11, 0, 1.0, vcc
	v_cmp_eq_u32_e32 vcc, 54, v126
	s_nop 0
	v_readlane_b32 s4, v62, s55
	s_nop 1
	v_fma_f32 v4, -s4, v89, v4
	v_lshl_add_u64 v[106:107], v[100:101], 1, s[0:1]
	v_ashrrev_i32_e32 v93, 31, v92
	v_cndmask_b32_e64 v97, 0, 1.0, vcc
	v_cmp_eq_u32_e32 vcc, 53, v126
	s_mov_b32 s56, 60
	v_lshl_add_u64 v[102:103], v[92:93], 1, s[0:1]
	v_cndmask_b32_e64 v13, 0, 1.0, vcc
	v_cmp_eq_u32_e32 vcc, 52, v126
	v_mov_b32_e32 v93, v123
	v_mov_b32_e32 v92, v123
	v_cndmask_b32_e64 v105, 0, 1.0, vcc
	v_cmp_eq_u32_e32 vcc, 51, v126
	s_mov_b32 s57, 59
	s_mov_b32 s53, 26
	v_cndmask_b32_e64 v17, 0, 1.0, vcc
	v_cmp_eq_u32_e32 vcc, 50, v126
	s_mov_b32 s58, 58
	v_mov_b32_e32 v94, v123
	v_cndmask_b32_e64 v111, 0, 1.0, vcc
	v_cmp_eq_u32_e32 vcc, 49, v126
	s_mov_b32 s52, 25
	s_mov_b32 s59, 57
	v_cndmask_b32_e64 v23, 0, 1.0, vcc
	v_cmp_eq_u32_e32 vcc, 48, v126
	v_mul_f32_e32 v10, 0x3fb8aa3b, v166
	v_mov_b32_e32 v180, v123
	v_cndmask_b32_e64 v115, 0, 1.0, vcc
	v_cmp_eq_u32_e32 vcc, 47, v126
	v_exp_f32_e32 v10, v10
	s_mov_b32 s51, 24
	v_cndmask_b32_e64 v27, 0, 1.0, vcc
	v_cmp_eq_u32_e32 vcc, 46, v126
	s_mov_b32 s60, 56
	v_mul_f32_e32 v210, v193, v10
	v_cndmask_b32_e64 v117, 0, 1.0, vcc
	v_cmp_eq_u32_e32 vcc, 45, v126
	v_mov_b32_e32 v10, v123
	s_mov_b32 s70, 23
	v_cndmask_b32_e64 v31, 0, 1.0, vcc
	v_cmp_eq_u32_e32 vcc, 44, v126
	s_mov_b32 s61, 55
	v_mov_b32_e32 v96, v123
	v_cndmask_b32_e64 v119, 0, 1.0, vcc
	v_cmp_eq_u32_e32 vcc, 43, v126
	s_mov_b32 s62, 54
	s_mov_b32 s71, 22
	v_cndmask_b32_e64 v33, 0, 1.0, vcc
	v_cmp_eq_u32_e32 vcc, 42, v126
	v_mov_b32_e32 v12, v123
	s_mov_b32 s63, 53
	v_cndmask_b32_e64 v129, 0, 1.0, vcc
	v_cmp_eq_u32_e32 vcc, 41, v126
	s_mov_b32 s72, 21
	v_mov_b32_e32 v104, v123
	v_cndmask_b32_e64 v65, 0, 1.0, vcc
	v_cmp_eq_u32_e32 vcc, 40, v126
	s_mov_b32 s73, 20
	v_mov_b32_e32 v16, v123
	v_cndmask_b32_e64 v131, 0, 1.0, vcc
	v_cmp_eq_u32_e32 vcc, 39, v126
	s_mov_b32 s64, 51
	s_mov_b32 s50, 19
	v_cndmask_b32_e64 v69, 0, 1.0, vcc
	v_cmp_eq_u32_e32 vcc, 38, v126
	v_mov_b32_e32 v110, v123
	s_mov_b32 s49, 18
	v_cndmask_b32_e64 v133, 0, 1.0, vcc
	v_cmp_eq_u32_e32 vcc, 37, v126
	s_mov_b32 s65, 50
	v_mov_b32_e32 v22, v123
	v_cndmask_b32_e64 v73, 0, 1.0, vcc
	v_cmp_eq_u32_e32 vcc, 36, v126
	s_mov_b32 s48, 17
	v_mov_b32_e32 v114, v123
	v_cndmask_b32_e64 v135, 0, 1.0, vcc
	v_cmp_eq_u32_e32 vcc, 35, v126
	s_mov_b32 s47, 16
	v_mov_b32_e32 v26, v123
	v_cndmask_b32_e64 v77, 0, 1.0, vcc
	v_cmp_eq_u32_e32 vcc, 34, v126
	s_mov_b32 s45, 15
	s_mov_b32 s66, 47
	v_cndmask_b32_e64 v137, 0, 1.0, vcc
	v_cmp_eq_u32_e32 vcc, 33, v126
	v_mov_b32_e32 v116, v123
	s_mov_b32 s39, 14
	v_cndmask_b32_e64 v81, 0, 1.0, vcc
	v_cmp_eq_u32_e32 vcc, 32, v126
	v_mov_b32_e32 v30, v123
	s_mov_b32 s38, 13
	v_cndmask_b32_e64 v139, 0, 1.0, vcc
	v_cmp_eq_u32_e32 vcc, 31, v126
	v_mov_b32_e32 v118, v123
	s_mov_b32 s43, 12
	v_cndmask_b32_e64 v153, 0, 1.0, vcc
	v_cmp_eq_u32_e32 vcc, 30, v126
	v_mov_b32_e32 v32, v123
	s_mov_b32 s67, 43
	v_cndmask_b32_e64 v141, 0, 1.0, vcc
	v_cmp_eq_u32_e32 vcc, 29, v126
	s_mov_b32 s42, 11
	v_mov_b32_e32 v128, v123
	v_cndmask_b32_e64 v159, 0, 1.0, vcc
	v_cmp_eq_u32_e32 vcc, 28, v126
	s_mov_b32 s46, 10
	s_lshl_b32 s4, s20, 4
	v_cndmask_b32_e64 v143, 0, 1.0, vcc
	v_cmp_eq_u32_e32 vcc, 27, v126
	v_mov_b32_e32 v64, v123
	s_or_b32 s4, s37, s4
	v_cndmask_b32_e64 v167, 0, 1.0, vcc
	v_cmp_eq_u32_e32 vcc, 26, v126
	s_mov_b32 s37, 9
	v_mov_b32_e32 v130, v123
	v_cndmask_b32_e64 v145, 0, 1.0, vcc
	v_cmp_eq_u32_e32 vcc, 25, v126
	s_mov_b32 s40, 8
	v_mov_b32_e32 v68, v123
	v_cndmask_b32_e64 v171, 0, 1.0, vcc
	v_cmp_eq_u32_e32 vcc, 24, v126
	s_mov_b32 s44, 7
	s_mov_b32 s68, 39
	v_cndmask_b32_e64 v147, 0, 1.0, vcc
	v_cmp_eq_u32_e32 vcc, 23, v126
	v_mov_b32_e32 v132, v123
	v_mov_b32_e32 v72, v123
	v_cndmask_b32_e64 v175, 0, 1.0, vcc
	v_cmp_eq_u32_e32 vcc, 22, v126
	v_mov_b32_e32 v134, v123
	v_mov_b32_e32 v76, v123
	v_cndmask_b32_e64 v149, 0, 1.0, vcc
	v_cmp_eq_u32_e32 vcc, 21, v126
	s_mov_b32 s69, 35
	s_mov_b32 s12, 3
	v_cndmask_b32_e64 v179, 0, 1.0, vcc
	v_cmp_eq_u32_e32 vcc, 20, v126
	v_mov_b32_e32 v136, v123
	v_mov_b32_e32 v80, v123
	v_cndmask_b32_e64 v151, 0, 1.0, vcc
	v_cmp_eq_u32_e32 vcc, 19, v126
	v_mov_b32_e32 v138, v123
	v_mov_b32_e32 v152, v123
	v_cndmask_b32_e64 v177, 0, 1.0, vcc
	v_cmp_eq_u32_e32 vcc, 18, v126
	s_mov_b32 s41, 31
	s_mov_b32 s20, 63
	v_cndmask_b32_e64 v157, 0, 1.0, vcc
	v_cmp_eq_u32_e32 vcc, 17, v126
	v_mov_b32_e32 v158, v123
	v_mov_b32_e32 v166, v123
	v_cndmask_b32_e64 v173, 0, 1.0, vcc
	v_cmp_eq_u32_e32 vcc, 16, v126
	v_mov_b32_e32 v170, v123
	v_mov_b32_e32 v174, v123
	v_cndmask_b32_e64 v165, 0, 1.0, vcc
	v_cmp_eq_u32_e32 vcc, 15, v126
	v_mov_b32_e32 v148, v123
	v_mov_b32_e32 v178, v123
	v_cndmask_b32_e64 v169, 0, 1.0, vcc
	v_cmp_eq_u32_e32 vcc, 14, v126
	v_mov_b32_e32 v150, v123
	v_mov_b32_e32 v176, v123
	v_cndmask_b32_e64 v163, 0, 1.0, vcc
	v_cmp_eq_u32_e32 vcc, 13, v126
	v_mov_b32_e32 v156, v123
	v_mov_b32_e32 v172, v123
	v_cndmask_b32_e64 v161, 0, 1.0, vcc
	v_cmp_eq_u32_e32 vcc, 12, v126
	v_mov_b32_e32 v164, v123
	v_mov_b32_e32 v168, v123
	v_cndmask_b32_e64 v155, 0, 1.0, vcc
	v_cmp_eq_u32_e32 vcc, 11, v126
	v_mov_b32_e32 v162, v123
	v_mov_b32_e32 v160, v123
	v_cndmask_b32_e64 v85, 0, 1.0, vcc
	v_cmp_eq_u32_e32 vcc, 10, v126
	v_mov_b32_e32 v154, v123
	s_ashr_i32 s5, s4, 31
	v_cndmask_b32_e64 v83, 0, 1.0, vcc
	v_cmp_eq_u32_e32 vcc, 9, v126
	s_nop 1
	v_cndmask_b32_e64 v79, 0, 1.0, vcc
	v_cmp_eq_u32_e32 vcc, 8, v126
	s_nop 1
	v_cndmask_b32_e64 v75, 0, 1.0, vcc
	v_cmp_eq_u32_e32 vcc, 7, v126
	s_nop 1
	v_cndmask_b32_e64 v71, 0, 1.0, vcc
	v_cmp_eq_u32_e32 vcc, 6, v126
	s_nop 1
	v_cndmask_b32_e64 v67, 0, 1.0, vcc
	v_cmp_eq_u32_e32 vcc, 5, v126
	s_nop 1
	v_cndmask_b32_e64 v63, 0, 1.0, vcc
	v_cmp_eq_u32_e32 vcc, 4, v126
	s_nop 1
	v_cndmask_b32_e64 v29, 0, 1.0, vcc
	v_cmp_eq_u32_e32 vcc, 3, v126
	s_nop 1
	v_cndmask_b32_e64 v25, 0, 1.0, vcc
	v_cmp_eq_u32_e32 vcc, 2, v126
	s_nop 1
	v_cndmask_b32_e64 v15, 0, 1.0, vcc
	v_cmp_eq_u32_e32 vcc, 1, v126
	s_nop 1
	v_cndmask_b32_e64 v7, 0, 1.0, vcc
	v_cmp_eq_u32_e32 vcc, 0, v126
	v_lshl_add_u64 v[126:127], v[90:91], 1, s[0:1]
	v_add_u32_e32 v90, 0x1c00, v90
	v_ashrrev_i32_e32 v91, 31, v90
	v_lshl_add_u64 v[100:101], v[90:91], 1, s[0:1]
	v_add_f32_e32 v91, 0, v4
	s_nop 0
	v_readlane_b32 s6, v70, s56
	s_nop 1
	v_fma_f32 v8, -s6, v91, v8
	v_mov_b32_e32 v4, v123
	s_nop 0
	v_readlane_b32 s6, v66, s56
	s_nop 1
	v_fma_f32 v8, -s6, v88, v8
	v_cndmask_b32_e64 v3, 0, 1.0, vcc
	s_nop 0
	v_readlane_b32 s6, v62, s56
	s_nop 1
	v_fma_f32 v8, -s6, v89, v8
	s_nop 0
	v_add_f32_e32 v90, 0, v8
	s_nop 0
	v_readlane_b32 s6, v14, s57
	v_readlane_b32 s7, v70, s57
	v_readlane_b32 s8, v66, s57
	v_readlane_b32 s9, v62, s57
	v_fma_f32 v5, -s6, v90, v5
	v_fma_f32 v93, -s7, v91, v93
	v_fma_f32 v92, -s8, v88, v92
	v_fma_f32 v4, -s9, v89, v4
	v_mov_b32_e32 v8, v123
	v_pk_add_f32 v[4:5], v[92:93], v[4:5]
	v_mov_b32_e32 v93, v123
	v_mov_b32_e32 v92, v123
	v_pk_add_f32 v[4:5], v[4:5], v[4:5] op_sel:[0,1] op_sel_hi:[1,0]
	s_nop 0
	s_nop 0
	v_readlane_b32 s6, v62, s53
	v_readlane_b32 s7, v14, s58
	v_readlane_b32 s8, v70, s58
	v_readlane_b32 s9, v66, s58
	v_fma_f32 v9, -s6, v4, v9
	v_fma_f32 v93, -s7, v90, v93
	v_fma_f32 v92, -s8, v91, v92
	v_fma_f32 v8, -s9, v88, v8
	s_nop 0
	s_nop 0
	v_readlane_b32 s6, v62, s58
	s_nop 1
	v_fma_f32 v9, -s6, v89, v9
	s_nop 0
	v_pk_add_f32 v[8:9], v[92:93], v[8:9]
	s_nop 0
	v_pk_add_f32 v[92:93], v[8:9], v[8:9] op_sel:[0,1] op_sel_hi:[1,0]
	v_mov_b32_e32 v9, v123
	v_mov_b32_e32 v8, v123
	s_nop 0
	v_readlane_b32 s6, v66, s52
	v_readlane_b32 s7, v62, s52
	v_readlane_b32 s8, v14, s59
	v_readlane_b32 s9, v70, s59
	v_fma_f32 v95, -s6, v92, v95
	v_fma_f32 v9, -s7, v4, v9
	v_fma_f32 v8, -s8, v90, v8
	v_fma_f32 v94, -s9, v91, v94
	v_mov_b32_e32 v93, v4
	s_nop 0
	v_readlane_b32 s6, v66, s59
	s_nop 1
	v_fma_f32 v95, -s6, v88, v95
	s_nop 0
	s_nop 0
	v_readlane_b32 s6, v62, s59
	s_nop 1
	v_fma_f32 v95, -s6, v89, v95
	s_nop 0
	v_pk_add_f32 v[8:9], v[8:9], v[94:95]
	v_mov_b32_e32 v95, v123
	v_mov_b32_e32 v94, v123
	v_pk_add_f32 v[8:9], v[8:9], v[8:9] op_sel:[0,1] op_sel_hi:[1,0]
	s_nop 0
	s_nop 0
	v_readlane_b32 s6, v70, s51
	v_readlane_b32 s7, v66, s51
	v_readlane_b32 s8, v62, s51
	v_readlane_b32 s9, v14, s60
	v_fma_f32 v181, -s6, v8, v181
	v_fma_f32 v95, -s7, v92, v95
	v_fma_f32 v94, -s8, v4, v94
	v_fma_f32 v180, -s9, v90, v180
	s_nop 0
	s_nop 0
	v_readlane_b32 s6, v70, s60
	s_nop 1
	v_fma_f32 v181, -s6, v91, v181
	s_nop 0
	s_nop 0
	v_readlane_b32 s6, v66, s60
	s_nop 1
	v_fma_f32 v181, -s6, v88, v181
	s_nop 0
	s_nop 0
	v_readlane_b32 s6, v62, s60
	s_nop 1
	v_fma_f32 v181, -s6, v89, v181
	s_nop 0
	v_pk_add_f32 v[94:95], v[94:95], v[180:181]
	v_mov_b32_e32 v181, v123
	v_mov_b32_e32 v180, v123
	v_pk_add_f32 v[94:95], v[94:95], v[94:95] op_sel:[0,1] op_sel_hi:[1,0]
	s_nop 0
	s_nop 0
	v_readlane_b32 s6, v14, s70
	v_readlane_b32 s7, v70, s70
	v_readlane_b32 s8, v66, s70
	v_readlane_b32 s9, v62, s70
	v_fma_f32 v11, -s6, v94, v11
	v_fma_f32 v181, -s7, v8, v181
	v_fma_f32 v180, -s8, v92, v180
	v_fma_f32 v10, -s9, v4, v10
	v_mov_b32_e32 v95, v8
	s_nop 0
	v_readlane_b32 s6, v14, s61
	v_readlane_b32 s7, v70, s61
	v_readlane_b32 s8, v66, s61
	v_readlane_b32 s9, v62, s61
	v_fma_f32 v11, -s6, v90, v11
	v_fma_f32 v181, -s7, v91, v181
	v_fma_f32 v180, -s8, v88, v180
	v_fma_f32 v10, -s9, v89, v10
	s_nop 0
	v_pk_add_f32 v[10:11], v[180:181], v[10:11]
	v_mov_b32_e32 v181, v123
	v_mov_b32_e32 v180, v123
	v_pk_add_f32 v[10:11], v[10:11], v[10:11] op_sel:[0,1] op_sel_hi:[1,0]
	s_nop 0
	s_nop 0
	v_readlane_b32 s6, v74, s62
	v_readlane_b32 s7, v14, s71
	v_readlane_b32 s8, v70, s71
	v_readlane_b32 s9, v66, s71
	v_fma_f32 v97, -s6, v10, v97
	v_fma_f32 v181, -s7, v94, v181
	v_fma_f32 v180, -s8, v8, v180
	v_fma_f32 v96, -s9, v92, v96
	s_nop 0
	s_nop 0
	v_readlane_b32 s6, v62, s71
	v_readlane_b32 s7, v14, s62
	v_readlane_b32 s8, v70, s62
	v_readlane_b32 s9, v66, s62
	v_fma_f32 v97, -s6, v4, v97
	v_fma_f32 v181, -s7, v90, v181
	v_fma_f32 v180, -s8, v91, v180
	v_fma_f32 v96, -s9, v88, v96
	s_nop 0
	s_nop 0
	v_readlane_b32 s6, v62, s62
	s_nop 1
	v_fma_f32 v97, -s6, v89, v97
	s_nop 0
	v_pk_add_f32 v[96:97], v[180:181], v[96:97]
	v_mov_b32_e32 v181, v123
	v_mov_b32_e32 v180, v123
	v_pk_add_f32 v[96:97], v[96:97], v[96:97] op_sel:[0,1] op_sel_hi:[1,0]
	s_nop 0
	s_nop 0
	v_readlane_b32 s6, v28, s63
	v_readlane_b32 s7, v74, s63
	v_readlane_b32 s8, v14, s72
	v_readlane_b32 s9, v70, s72
	v_fma_f32 v13, -s6, v96, v13
	v_fma_f32 v181, -s7, v10, v181
	v_fma_f32 v180, -s8, v94, v180
	v_fma_f32 v12, -s9, v8, v12
	v_mov_b32_e32 v97, v10
	s_nop 0
	v_readlane_b32 s6, v66, s72
	v_readlane_b32 s7, v62, s72
	v_readlane_b32 s8, v14, s63
	v_readlane_b32 s9, v70, s63
	v_fma_f32 v13, -s6, v92, v13
	v_fma_f32 v181, -s7, v4, v181
	v_fma_f32 v180, -s8, v90, v180
	v_fma_f32 v12, -s9, v91, v12
	s_nop 0
	s_nop 0
	v_readlane_b32 s6, v66, s63
	s_nop 1
	v_fma_f32 v13, -s6, v88, v13
	s_nop 0
	s_nop 0
	v_readlane_b32 s6, v62, s63
	s_nop 1
	v_fma_f32 v13, -s6, v89, v13
	s_nop 0
	v_pk_add_f32 v[12:13], v[180:181], v[12:13]
	v_mov_b32_e32 v181, v123
	v_mov_b32_e32 v180, v123
	v_pk_add_f32 v[12:13], v[12:13], v[12:13] op_sel:[0,1] op_sel_hi:[1,0]
	s_nop 0
	s_nop 0
	v_readlane_b32 s6, v78, s22
	v_readlane_b32 s7, v28, s22
	v_readlane_b32 s8, v74, s22
	v_readlane_b32 s9, v14, s73
	v_fma_f32 v105, -s6, v12, v105
	v_fma_f32 v181, -s7, v96, v181
	v_fma_f32 v180, -s8, v10, v180
	v_fma_f32 v104, -s9, v94, v104
	s_nop 0
	s_nop 0
	v_readlane_b32 s6, v70, s73
	v_readlane_b32 s7, v66, s73
	v_readlane_b32 s8, v62, s73
	v_readlane_b32 s9, v14, s22
	v_fma_f32 v105, -s6, v8, v105
	v_fma_f32 v181, -s7, v92, v181
	v_fma_f32 v180, -s8, v4, v180
	v_fma_f32 v104, -s9, v90, v104
	s_nop 0
	s_nop 0
	v_readlane_b32 s6, v70, s22
	s_nop 1
	v_fma_f32 v105, -s6, v91, v105
	s_nop 0
	s_nop 0
	v_readlane_b32 s6, v66, s22
	s_nop 1
	v_fma_f32 v105, -s6, v88, v105
	s_nop 0
	s_nop 0
	v_readlane_b32 s6, v62, s22
	s_nop 1
	v_fma_f32 v105, -s6, v89, v105
	s_nop 0
	v_pk_add_f32 v[104:105], v[180:181], v[104:105]
	v_mov_b32_e32 v181, v123
	v_mov_b32_e32 v180, v123
	v_pk_add_f32 v[104:105], v[104:105], v[104:105] op_sel:[0,1] op_sel_hi:[1,0]
	s_nop 0
	s_nop 0
	v_readlane_b32 s6, v82, s64
	v_readlane_b32 s7, v78, s64
	v_readlane_b32 s8, v28, s64
	v_readlane_b32 s9, v74, s64
	v_fma_f32 v17, -s6, v104, v17
	v_fma_f32 v181, -s7, v12, v181
	v_fma_f32 v180, -s8, v96, v180
	v_fma_f32 v16, -s9, v10, v16
	v_mov_b32_e32 v105, v12
	s_nop 0
	v_readlane_b32 s6, v14, s50
	v_readlane_b32 s7, v70, s50
	v_readlane_b32 s8, v66, s50
	v_readlane_b32 s9, v62, s50
	v_fma_f32 v17, -s6, v94, v17
	v_fma_f32 v181, -s7, v8, v181
	v_fma_f32 v180, -s8, v92, v180
	v_fma_f32 v16, -s9, v4, v16
	s_nop 0
	s_nop 0
	v_readlane_b32 s6, v14, s64
	v_readlane_b32 s7, v70, s64
	v_readlane_b32 s8, v66, s64
	v_readlane_b32 s9, v62, s64
	v_fma_f32 v17, -s6, v90, v17
	v_fma_f32 v181, -s7, v91, v181
	v_fma_f32 v180, -s8, v88, v180
	v_fma_f32 v16, -s9, v89, v16
	s_nop 0
	v_pk_add_f32 v[16:17], v[180:181], v[16:17]
	v_mov_b32_e32 v181, v123
	v_mov_b32_e32 v180, v123
	v_pk_add_f32 v[16:17], v[16:17], v[16:17] op_sel:[0,1] op_sel_hi:[1,0]
	s_nop 0
	s_nop 0
	v_readlane_b32 s6, v74, s49
	v_readlane_b32 s7, v82, s65
	v_readlane_b32 s8, v78, s65
	v_readlane_b32 s9, v28, s65
	v_fma_f32 v111, -s6, v16, v111
	v_fma_f32 v181, -s7, v104, v181
	v_fma_f32 v180, -s8, v12, v180
	v_fma_f32 v110, -s9, v96, v110
	s_nop 0
	s_nop 0
	v_readlane_b32 s6, v74, s65
	v_readlane_b32 s7, v14, s49
	v_readlane_b32 s8, v70, s49
	v_readlane_b32 s9, v66, s49
	v_fma_f32 v111, -s6, v10, v111
	v_fma_f32 v181, -s7, v94, v181
	v_fma_f32 v180, -s8, v8, v180
	v_fma_f32 v110, -s9, v92, v110
	s_nop 0
	s_nop 0
	v_readlane_b32 s6, v62, s49
	v_readlane_b32 s7, v14, s65
	v_readlane_b32 s8, v70, s65
	v_readlane_b32 s9, v66, s65
	v_fma_f32 v111, -s6, v4, v111
	v_fma_f32 v181, -s7, v90, v181
	v_fma_f32 v180, -s8, v91, v180
	v_fma_f32 v110, -s9, v88, v110
	s_nop 0
	s_nop 0
	v_readlane_b32 s6, v62, s65
	s_nop 1
	v_fma_f32 v111, -s6, v89, v111
	s_nop 0
	v_pk_add_f32 v[110:111], v[180:181], v[110:111]
	v_mov_b32_e32 v181, v123
	v_mov_b32_e32 v180, v123
	v_pk_add_f32 v[110:111], v[110:111], v[110:111] op_sel:[0,1] op_sel_hi:[1,0]
	s_nop 0
	s_nop 0
	v_readlane_b32 s6, v28, s48
	v_readlane_b32 s7, v74, s48
	v_readlane_b32 s8, v82, s21
	v_readlane_b32 s9, v78, s21
	v_fma_f32 v23, -s6, v110, v23
	v_fma_f32 v181, -s7, v16, v181
	v_fma_f32 v180, -s8, v104, v180
	v_fma_f32 v22, -s9, v12, v22
	v_mov_b32_e32 v111, v16
	s_nop 0
	v_readlane_b32 s6, v28, s21
	v_readlane_b32 s7, v74, s21
	v_readlane_b32 s8, v14, s48
	v_readlane_b32 s9, v70, s48
	v_fma_f32 v23, -s6, v96, v23
	v_fma_f32 v181, -s7, v10, v181
	v_fma_f32 v180, -s8, v94, v180
	v_fma_f32 v22, -s9, v8, v22
	s_nop 0
	s_nop 0
	v_readlane_b32 s6, v66, s48
	v_readlane_b32 s7, v62, s48
	v_readlane_b32 s8, v14, s21
	v_readlane_b32 s9, v70, s21
	v_fma_f32 v23, -s6, v92, v23
	v_fma_f32 v181, -s7, v4, v181
	v_fma_f32 v180, -s8, v90, v180
	v_fma_f32 v22, -s9, v91, v22
	s_nop 0
	s_nop 0
	v_readlane_b32 s6, v66, s21
	s_nop 1
	v_fma_f32 v23, -s6, v88, v23
	s_nop 0
	s_nop 0
	v_readlane_b32 s6, v62, s21
	s_nop 1
	v_fma_f32 v23, -s6, v89, v23
	s_nop 0
	v_pk_add_f32 v[22:23], v[180:181], v[22:23]
	v_mov_b32_e32 v181, v123
	v_mov_b32_e32 v180, v123
	v_pk_add_f32 v[22:23], v[22:23], v[22:23] op_sel:[0,1] op_sel_hi:[1,0]
	s_nop 0
	s_nop 0
	v_readlane_b32 s6, v78, s47
	v_readlane_b32 s7, v28, s47
	v_readlane_b32 s8, v74, s47
	v_readlane_b32 s9, v82, s34
	v_fma_f32 v115, -s6, v22, v115
	v_fma_f32 v181, -s7, v110, v181
	v_fma_f32 v180, -s8, v16, v180
	v_fma_f32 v114, -s9, v104, v114
	s_nop 0
	s_nop 0
	v_readlane_b32 s6, v78, s34
	v_readlane_b32 s7, v28, s34
	v_readlane_b32 s8, v74, s34
	v_readlane_b32 s9, v14, s47
	v_fma_f32 v115, -s6, v12, v115
	v_fma_f32 v181, -s7, v96, v181
	v_fma_f32 v180, -s8, v10, v180
	v_fma_f32 v114, -s9, v94, v114
	s_nop 0
	s_nop 0
	v_readlane_b32 s6, v70, s47
	v_readlane_b32 s7, v66, s47
	v_readlane_b32 s8, v62, s47
	v_readlane_b32 s9, v14, s34
	v_fma_f32 v115, -s6, v8, v115
	v_fma_f32 v181, -s7, v92, v181
	v_fma_f32 v180, -s8, v4, v180
	v_fma_f32 v114, -s9, v90, v114
	s_nop 0
	s_nop 0
	v_readlane_b32 s6, v70, s34
	s_nop 1
	v_fma_f32 v115, -s6, v91, v115
	s_nop 0
	s_nop 0
	v_readlane_b32 s6, v66, s34
	s_nop 1
	v_fma_f32 v115, -s6, v88, v115
	s_nop 0
	s_nop 0
	v_readlane_b32 s6, v62, s34
	s_nop 1
	v_fma_f32 v115, -s6, v89, v115
	s_nop 0
	v_pk_add_f32 v[114:115], v[180:181], v[114:115]
	v_mov_b32_e32 v181, v123
	v_mov_b32_e32 v180, v123
	v_pk_add_f32 v[114:115], v[114:115], v[114:115] op_sel:[0,1] op_sel_hi:[1,0]
	s_nop 0
	s_nop 0
	v_readlane_b32 s6, v82, s45
	v_readlane_b32 s7, v78, s45
	v_readlane_b32 s8, v28, s45
	v_readlane_b32 s9, v74, s45
	v_fma_f32 v27, -s6, v114, v27
	v_fma_f32 v181, -s7, v22, v181
	v_fma_f32 v180, -s8, v110, v180
	v_fma_f32 v26, -s9, v16, v26
	v_mov_b32_e32 v115, v22
	s_nop 0
	v_readlane_b32 s6, v82, s66
	v_readlane_b32 s7, v78, s66
	v_readlane_b32 s8, v28, s66
	v_readlane_b32 s9, v74, s66
	v_fma_f32 v27, -s6, v104, v27
	v_fma_f32 v181, -s7, v12, v181
	v_fma_f32 v180, -s8, v96, v180
	v_fma_f32 v26, -s9, v10, v26
	s_nop 0
	s_nop 0
	v_readlane_b32 s6, v14, s45
	v_readlane_b32 s7, v70, s45
	v_readlane_b32 s8, v66, s45
	v_readlane_b32 s9, v62, s45
	v_fma_f32 v27, -s6, v94, v27
	v_fma_f32 v181, -s7, v8, v181
	v_fma_f32 v180, -s8, v92, v180
	v_fma_f32 v26, -s9, v4, v26
	s_nop 0
	s_nop 0
	v_readlane_b32 s6, v14, s66
	v_readlane_b32 s7, v70, s66
	v_readlane_b32 s8, v66, s66
	v_readlane_b32 s9, v62, s66
	v_fma_f32 v27, -s6, v90, v27
	v_fma_f32 v181, -s7, v91, v181
	v_fma_f32 v180, -s8, v88, v180
	v_fma_f32 v26, -s9, v89, v26
	s_nop 0
	v_pk_add_f32 v[26:27], v[180:181], v[26:27]
	v_mov_b32_e32 v181, v123
	v_mov_b32_e32 v180, v123
	v_pk_add_f32 v[26:27], v[26:27], v[26:27] op_sel:[0,1] op_sel_hi:[1,0]
	s_nop 0
	s_nop 0
	v_readlane_b32 s6, v84, s14
	v_readlane_b32 s7, v82, s39
	v_readlane_b32 s8, v78, s39
	v_readlane_b32 s9, v28, s39
	v_fma_f32 v117, -s6, v26, v117
	v_fma_f32 v181, -s7, v114, v181
	v_fma_f32 v180, -s8, v22, v180
	v_fma_f32 v116, -s9, v110, v116
	s_nop 0
	s_nop 0
	v_readlane_b32 s6, v74, s39
	v_readlane_b32 s7, v82, s14
	v_readlane_b32 s8, v78, s14
	v_readlane_b32 s9, v28, s14
	v_fma_f32 v117, -s6, v16, v117
	v_fma_f32 v181, -s7, v104, v181
	v_fma_f32 v180, -s8, v12, v180
	v_fma_f32 v116, -s9, v96, v116
	s_nop 0
	s_nop 0
	v_readlane_b32 s6, v74, s14
	v_readlane_b32 s7, v14, s39
	v_readlane_b32 s8, v70, s39
	v_readlane_b32 s9, v66, s39
	v_fma_f32 v117, -s6, v10, v117
	v_fma_f32 v181, -s7, v94, v181
	v_fma_f32 v180, -s8, v8, v180
	v_fma_f32 v116, -s9, v92, v116
	s_nop 0
	s_nop 0
	v_readlane_b32 s6, v62, s39
	v_readlane_b32 s7, v14, s14
	v_readlane_b32 s8, v70, s14
	v_readlane_b32 s9, v66, s14
	v_fma_f32 v117, -s6, v4, v117
	v_fma_f32 v181, -s7, v90, v181
	v_fma_f32 v180, -s8, v91, v180
	v_fma_f32 v116, -s9, v88, v116
	s_nop 0
	s_nop 0
	v_readlane_b32 s6, v62, s14
	s_nop 1
	v_fma_f32 v117, -s6, v89, v117
	s_nop 0
	v_pk_add_f32 v[116:117], v[180:181], v[116:117]
	v_mov_b32_e32 v181, v123
	v_mov_b32_e32 v180, v123
	v_pk_add_f32 v[116:117], v[116:117], v[116:117] op_sel:[0,1] op_sel_hi:[1,0]
	s_nop 0
	s_nop 0
	v_readlane_b32 s6, v24, s11
	v_readlane_b32 s7, v84, s11
	v_readlane_b32 s8, v82, s38
	v_readlane_b32 s9, v78, s38
	v_fma_f32 v31, -s6, v116, v31
	v_fma_f32 v181, -s7, v26, v181
	v_fma_f32 v180, -s8, v114, v180
	v_fma_f32 v30, -s9, v22, v30
	v_mov_b32_e32 v117, v26
	s_nop 0
	v_readlane_b32 s6, v28, s38
	v_readlane_b32 s7, v74, s38
	v_readlane_b32 s8, v82, s11
	v_readlane_b32 s9, v78, s11
	v_fma_f32 v31, -s6, v110, v31
	v_fma_f32 v181, -s7, v16, v181
	v_fma_f32 v180, -s8, v104, v180
	v_fma_f32 v30, -s9, v12, v30
	s_nop 0
	s_nop 0
	v_readlane_b32 s6, v28, s11
	v_readlane_b32 s7, v74, s11
	v_readlane_b32 s8, v14, s38
	v_readlane_b32 s9, v70, s38
	v_fma_f32 v31, -s6, v96, v31
	v_fma_f32 v181, -s7, v10, v181
	v_fma_f32 v180, -s8, v94, v180
	v_fma_f32 v30, -s9, v8, v30
	s_nop 0
	s_nop 0
	v_readlane_b32 s6, v66, s38
	v_readlane_b32 s7, v62, s38
	v_readlane_b32 s8, v14, s11
	v_readlane_b32 s9, v70, s11
	v_fma_f32 v31, -s6, v92, v31
	v_fma_f32 v181, -s7, v4, v181
	v_fma_f32 v180, -s8, v90, v180
	v_fma_f32 v30, -s9, v91, v30
	s_nop 0
	s_nop 0
	v_readlane_b32 s6, v66, s11
	s_nop 1
	v_fma_f32 v31, -s6, v88, v31
	s_nop 0
	s_nop 0
	v_readlane_b32 s6, v62, s11
	s_nop 1
	v_fma_f32 v31, -s6, v89, v31
	s_nop 0
	v_pk_add_f32 v[30:31], v[180:181], v[30:31]
	v_mov_b32_e32 v181, v123
	v_mov_b32_e32 v180, v123
	v_pk_add_f32 v[30:31], v[30:31], v[30:31] op_sel:[0,1] op_sel_hi:[1,0]
	s_nop 0
	s_nop 0
	v_readlane_b32 s6, v142, s27
	v_readlane_b32 s7, v24, s27
	v_readlane_b32 s8, v84, s27
	v_readlane_b32 s9, v82, s43
	v_fma_f32 v119, -s6, v30, v119
	v_fma_f32 v181, -s7, v116, v181
	v_fma_f32 v180, -s8, v26, v180
	v_fma_f32 v118, -s9, v114, v118
	s_nop 0
	s_nop 0
	v_readlane_b32 s6, v78, s43
	v_readlane_b32 s7, v28, s43
	v_readlane_b32 s8, v74, s43
	v_readlane_b32 s9, v82, s27
	v_fma_f32 v119, -s6, v22, v119
	v_fma_f32 v181, -s7, v110, v181
	v_fma_f32 v180, -s8, v16, v180
	v_fma_f32 v118, -s9, v104, v118
	s_nop 0
	s_nop 0
	v_readlane_b32 s6, v78, s27
	v_readlane_b32 s7, v28, s27
	v_readlane_b32 s8, v74, s27
	v_readlane_b32 s9, v14, s43
	v_fma_f32 v119, -s6, v12, v119
	v_fma_f32 v181, -s7, v96, v181
	v_fma_f32 v180, -s8, v10, v180
	v_fma_f32 v118, -s9, v94, v118
	s_nop 0
	s_nop 0
	v_readlane_b32 s6, v70, s43
	v_readlane_b32 s7, v66, s43
	v_readlane_b32 s8, v62, s43
	v_readlane_b32 s9, v14, s27
	v_fma_f32 v119, -s6, v8, v119
	v_fma_f32 v181, -s7, v92, v181
	v_fma_f32 v180, -s8, v4, v180
	v_fma_f32 v118, -s9, v90, v118
	s_nop 0
	s_nop 0
	v_readlane_b32 s6, v70, s27
	s_nop 1
	v_fma_f32 v119, -s6, v91, v119
	s_nop 0
	s_nop 0
	v_readlane_b32 s6, v66, s27
	s_nop 1
	v_fma_f32 v119, -s6, v88, v119
	s_nop 0
	s_nop 0
	v_readlane_b32 s6, v62, s27
	s_nop 1
	v_fma_f32 v119, -s6, v89, v119
	s_nop 0
	v_pk_add_f32 v[118:119], v[180:181], v[118:119]
	v_mov_b32_e32 v181, v123
	v_mov_b32_e32 v180, v123
	v_pk_add_f32 v[118:119], v[118:119], v[118:119] op_sel:[0,1] op_sel_hi:[1,0]
	s_nop 0
	s_nop 0
	v_readlane_b32 s6, v6, s67
	v_readlane_b32 s7, v142, s67
	v_readlane_b32 s8, v24, s67
	v_readlane_b32 s9, v84, s67
	v_fma_f32 v33, -s6, v118, v33
	v_fma_f32 v181, -s7, v30, v181
	v_fma_f32 v180, -s8, v116, v180
	v_fma_f32 v32, -s9, v26, v32
	v_mov_b32_e32 v119, v30
	s_nop 0
	v_readlane_b32 s6, v82, s42
	v_readlane_b32 s7, v78, s42
	v_readlane_b32 s8, v28, s42
	v_readlane_b32 s9, v74, s42
	v_fma_f32 v33, -s6, v114, v33
	v_fma_f32 v181, -s7, v22, v181
	v_fma_f32 v180, -s8, v110, v180
	v_fma_f32 v32, -s9, v16, v32
	s_nop 0
	s_nop 0
	v_readlane_b32 s6, v82, s67
	v_readlane_b32 s7, v78, s67
	v_readlane_b32 s8, v28, s67
	v_readlane_b32 s9, v74, s67
	v_fma_f32 v33, -s6, v104, v33
	v_fma_f32 v181, -s7, v12, v181
	v_fma_f32 v180, -s8, v96, v180
	v_fma_f32 v32, -s9, v10, v32
	s_nop 0
	s_nop 0
	v_readlane_b32 s6, v14, s42
	v_readlane_b32 s7, v70, s42
	v_readlane_b32 s8, v66, s42
	v_readlane_b32 s9, v62, s42
	v_fma_f32 v33, -s6, v94, v33
	v_fma_f32 v181, -s7, v8, v181
	v_fma_f32 v180, -s8, v92, v180
	v_fma_f32 v32, -s9, v4, v32
	s_nop 0
	s_nop 0
	v_readlane_b32 s6, v14, s67
	v_readlane_b32 s7, v70, s67
	v_readlane_b32 s8, v66, s67
	v_readlane_b32 s9, v62, s67
	v_fma_f32 v33, -s6, v90, v33
	v_fma_f32 v181, -s7, v91, v181
	v_fma_f32 v180, -s8, v88, v180
	v_fma_f32 v32, -s9, v89, v32
	s_nop 0
	v_pk_add_f32 v[32:33], v[180:181], v[32:33]
	v_mov_b32_e32 v181, v123
	v_mov_b32_e32 v180, v123
	v_pk_add_f32 v[32:33], v[32:33], v[32:33] op_sel:[0,1] op_sel_hi:[1,0]
	s_nop 0
	s_nop 0
	v_readlane_b32 s6, v84, s46
	v_readlane_b32 s7, v6, s2
	v_readlane_b32 s8, v142, s2
	v_readlane_b32 s9, v24, s2
	v_fma_f32 v129, -s6, v32, v129
	v_fma_f32 v181, -s7, v118, v181
	v_fma_f32 v180, -s8, v30, v180
	v_fma_f32 v128, -s9, v116, v128
	s_nop 0
	s_nop 0
	v_readlane_b32 s6, v84, s2
	v_readlane_b32 s7, v82, s46
	v_readlane_b32 s8, v78, s46
	v_readlane_b32 s9, v28, s46
	v_fma_f32 v129, -s6, v26, v129
	v_fma_f32 v181, -s7, v114, v181
	v_fma_f32 v180, -s8, v22, v180
	v_fma_f32 v128, -s9, v110, v128
	s_nop 0
	s_nop 0
	v_readlane_b32 s6, v74, s46
	v_readlane_b32 s7, v82, s2
	v_readlane_b32 s8, v78, s2
	v_readlane_b32 s9, v28, s2
	v_fma_f32 v129, -s6, v16, v129
	v_fma_f32 v181, -s7, v104, v181
	v_fma_f32 v180, -s8, v12, v180
	v_fma_f32 v128, -s9, v96, v128
	s_nop 0
	s_nop 0
	v_readlane_b32 s6, v74, s2
	v_readlane_b32 s7, v14, s46
	v_readlane_b32 s8, v70, s46
	v_readlane_b32 s9, v66, s46
	v_fma_f32 v129, -s6, v10, v129
	v_fma_f32 v181, -s7, v94, v181
	v_fma_f32 v180, -s8, v8, v180
	v_fma_f32 v128, -s9, v92, v128
	s_nop 0
	s_nop 0
	v_readlane_b32 s6, v62, s46
	v_readlane_b32 s7, v14, s2
	v_readlane_b32 s8, v70, s2
	v_readlane_b32 s9, v66, s2
	v_fma_f32 v129, -s6, v4, v129
	v_fma_f32 v181, -s7, v90, v181
	v_fma_f32 v180, -s8, v91, v180
	v_fma_f32 v128, -s9, v88, v128
	s_nop 0
	s_nop 0
	v_readlane_b32 s6, v62, s2
	s_nop 1
	v_fma_f32 v129, -s6, v89, v129
	s_nop 0
	v_pk_add_f32 v[128:129], v[180:181], v[128:129]
	v_mov_b32_e32 v181, v123
	v_mov_b32_e32 v180, v123
	v_pk_add_f32 v[128:129], v[128:129], v[128:129] op_sel:[0,1] op_sel_hi:[1,0]
	s_nop 0
	s_nop 0
	v_readlane_b32 s6, v24, s37
	v_readlane_b32 s7, v84, s37
	v_readlane_b32 s8, v6, s18
	v_readlane_b32 s9, v142, s18
	v_fma_f32 v65, -s6, v128, v65
	v_fma_f32 v181, -s7, v32, v181
	v_fma_f32 v180, -s8, v118, v180
	v_fma_f32 v64, -s9, v30, v64
	v_mov_b32_e32 v129, v32
	s_nop 0
	v_readlane_b32 s6, v24, s18
	v_readlane_b32 s7, v84, s18
	v_readlane_b32 s8, v82, s37
	v_readlane_b32 s9, v78, s37
	v_fma_f32 v65, -s6, v116, v65
	v_fma_f32 v181, -s7, v26, v181
	v_fma_f32 v180, -s8, v114, v180
	v_fma_f32 v64, -s9, v22, v64
	s_nop 0
	s_nop 0
	v_readlane_b32 s6, v28, s37
	v_readlane_b32 s7, v74, s37
	v_readlane_b32 s8, v82, s18
	v_readlane_b32 s9, v78, s18
	v_fma_f32 v65, -s6, v110, v65
	v_fma_f32 v181, -s7, v16, v181
	v_fma_f32 v180, -s8, v104, v180
	v_fma_f32 v64, -s9, v12, v64
	s_nop 0
	s_nop 0
	v_readlane_b32 s6, v28, s18
	v_readlane_b32 s7, v74, s18
	v_readlane_b32 s8, v14, s37
	v_readlane_b32 s9, v70, s37
	v_fma_f32 v65, -s6, v96, v65
	v_fma_f32 v181, -s7, v10, v181
	v_fma_f32 v180, -s8, v94, v180
	v_fma_f32 v64, -s9, v8, v64
	s_nop 0
	s_nop 0
	v_readlane_b32 s6, v66, s37
	v_readlane_b32 s7, v62, s37
	v_readlane_b32 s8, v14, s18
	v_readlane_b32 s9, v70, s18
	v_fma_f32 v65, -s6, v92, v65
	v_fma_f32 v181, -s7, v4, v181
	v_fma_f32 v180, -s8, v90, v180
	v_fma_f32 v64, -s9, v91, v64
	s_nop 0
	s_nop 0
	v_readlane_b32 s6, v66, s18
	s_nop 1
	v_fma_f32 v65, -s6, v88, v65
	s_nop 0
	s_nop 0
	v_readlane_b32 s6, v62, s18
	s_nop 1
	v_fma_f32 v65, -s6, v89, v65
	s_nop 0
	v_pk_add_f32 v[64:65], v[180:181], v[64:65]
	v_mov_b32_e32 v181, v123
	v_mov_b32_e32 v180, v123
	v_pk_add_f32 v[64:65], v[64:65], v[64:65] op_sel:[0,1] op_sel_hi:[1,0]
	s_nop 0
	s_nop 0
	v_readlane_b32 s6, v142, s40
	v_readlane_b32 s7, v24, s40
	v_readlane_b32 s8, v84, s40
	v_readlane_b32 s9, v6, s19
	v_fma_f32 v131, -s6, v64, v131
	v_fma_f32 v181, -s7, v128, v181
	v_fma_f32 v180, -s8, v32, v180
	v_fma_f32 v130, -s9, v118, v130
	s_nop 0
	s_nop 0
	v_readlane_b32 s6, v142, s19
	v_readlane_b32 s7, v24, s19
	v_readlane_b32 s8, v84, s19
	v_readlane_b32 s9, v82, s40
	v_fma_f32 v131, -s6, v30, v131
	v_fma_f32 v181, -s7, v116, v181
	v_fma_f32 v180, -s8, v26, v180
	v_fma_f32 v130, -s9, v114, v130
	s_nop 0
	s_nop 0
	v_readlane_b32 s6, v78, s40
	v_readlane_b32 s7, v28, s40
	v_readlane_b32 s8, v74, s40
	v_readlane_b32 s9, v82, s19
	v_fma_f32 v131, -s6, v22, v131
	v_fma_f32 v181, -s7, v110, v181
	v_fma_f32 v180, -s8, v16, v180
	v_fma_f32 v130, -s9, v104, v130
	s_nop 0
	s_nop 0
	v_readlane_b32 s6, v78, s19
	v_readlane_b32 s7, v28, s19
	v_readlane_b32 s8, v74, s19
	v_readlane_b32 s9, v14, s40
	v_fma_f32 v131, -s6, v12, v131
	v_fma_f32 v181, -s7, v96, v181
	v_fma_f32 v180, -s8, v10, v180
	v_fma_f32 v130, -s9, v94, v130
	s_nop 0
	s_nop 0
	v_readlane_b32 s6, v70, s40
	v_readlane_b32 s7, v66, s40
	v_readlane_b32 s8, v62, s40
	v_readlane_b32 s9, v14, s19
	v_fma_f32 v131, -s6, v8, v131
	v_fma_f32 v181, -s7, v92, v181
	v_fma_f32 v180, -s8, v4, v180
	v_fma_f32 v130, -s9, v90, v130
	s_nop 0
	s_nop 0
	v_readlane_b32 s6, v70, s19
	s_nop 1
	v_fma_f32 v131, -s6, v91, v131
	s_nop 0
	s_nop 0
	v_readlane_b32 s6, v66, s19
	s_nop 1
	v_fma_f32 v131, -s6, v88, v131
	s_nop 0
	s_nop 0
	v_readlane_b32 s6, v62, s19
	s_nop 1
	v_fma_f32 v131, -s6, v89, v131
	s_nop 0
	v_pk_add_f32 v[130:131], v[180:181], v[130:131]
	v_mov_b32_e32 v181, v123
	v_mov_b32_e32 v180, v123
	v_pk_add_f32 v[130:131], v[130:131], v[130:131] op_sel:[0,1] op_sel_hi:[1,0]
	s_nop 0
	s_nop 0
	v_readlane_b32 s6, v6, s44
	v_readlane_b32 s7, v142, s44
	v_readlane_b32 s8, v24, s44
	v_readlane_b32 s9, v84, s44
	v_fma_f32 v69, -s6, v130, v69
	v_fma_f32 v181, -s7, v64, v181
	v_fma_f32 v180, -s8, v128, v180
	v_fma_f32 v68, -s9, v32, v68
	v_mov_b32_e32 v131, v64
	s_nop 0
	v_readlane_b32 s6, v6, s68
	v_readlane_b32 s7, v142, s68
	v_readlane_b32 s8, v24, s68
	v_readlane_b32 s9, v84, s68
	v_fma_f32 v69, -s6, v118, v69
	v_fma_f32 v181, -s7, v30, v181
	v_fma_f32 v180, -s8, v116, v180
	v_fma_f32 v68, -s9, v26, v68
	s_nop 0
	s_nop 0
	v_readlane_b32 s6, v82, s44
	v_readlane_b32 s7, v78, s44
	v_readlane_b32 s8, v28, s44
	v_readlane_b32 s9, v74, s44
	v_fma_f32 v69, -s6, v114, v69
	v_fma_f32 v181, -s7, v22, v181
	v_fma_f32 v180, -s8, v110, v180
	v_fma_f32 v68, -s9, v16, v68
	s_nop 0
	s_nop 0
	v_readlane_b32 s6, v82, s68
	v_readlane_b32 s7, v78, s68
	v_readlane_b32 s8, v28, s68
	v_readlane_b32 s9, v74, s68
	v_fma_f32 v69, -s6, v104, v69
	v_fma_f32 v181, -s7, v12, v181
	v_fma_f32 v180, -s8, v96, v180
	v_fma_f32 v68, -s9, v10, v68
	s_nop 0
	s_nop 0
	v_readlane_b32 s6, v14, s44
	v_readlane_b32 s7, v70, s44
	v_readlane_b32 s8, v66, s44
	v_readlane_b32 s9, v62, s44
	v_fma_f32 v69, -s6, v94, v69
	v_fma_f32 v181, -s7, v8, v181
	v_fma_f32 v180, -s8, v92, v180
	v_fma_f32 v68, -s9, v4, v68
	s_nop 0
	s_nop 0
	v_readlane_b32 s6, v14, s68
	v_readlane_b32 s7, v70, s68
	v_readlane_b32 s8, v66, s68
	v_readlane_b32 s9, v62, s68
	v_fma_f32 v69, -s6, v90, v69
	v_fma_f32 v181, -s7, v91, v181
	v_fma_f32 v180, -s8, v88, v180
	v_fma_f32 v68, -s9, v89, v68
	s_nop 0
	v_pk_add_f32 v[68:69], v[180:181], v[68:69]
	v_mov_b32_e32 v181, v123
	v_mov_b32_e32 v180, v123
	v_pk_add_f32 v[68:69], v[68:69], v[68:69] op_sel:[0,1] op_sel_hi:[1,0]
	s_nop 0
	s_nop 0
	v_readlane_b32 s6, v140, s3
	v_readlane_b32 s7, v6, s35
	v_readlane_b32 s8, v142, s35
	v_readlane_b32 s9, v24, s35
	v_fma_f32 v133, -s6, v68, v133
	v_fma_f32 v181, -s7, v130, v181
	v_fma_f32 v180, -s8, v64, v180
	v_fma_f32 v132, -s9, v128, v132
	s_nop 0
	s_nop 0
	v_readlane_b32 s6, v84, s35
	v_readlane_b32 s7, v6, s3
	v_readlane_b32 s8, v142, s3
	v_readlane_b32 s9, v24, s3
	v_fma_f32 v133, -s6, v32, v133
	v_fma_f32 v181, -s7, v118, v181
	v_fma_f32 v180, -s8, v30, v180
	v_fma_f32 v132, -s9, v116, v132
	s_nop 0
	s_nop 0
	v_readlane_b32 s6, v84, s3
	v_readlane_b32 s7, v82, s35
	v_readlane_b32 s8, v78, s35
	v_readlane_b32 s9, v28, s35
	v_fma_f32 v133, -s6, v26, v133
	v_fma_f32 v181, -s7, v114, v181
	v_fma_f32 v180, -s8, v22, v180
	v_fma_f32 v132, -s9, v110, v132
	s_nop 0
	s_nop 0
	v_readlane_b32 s6, v74, s35
	v_readlane_b32 s7, v82, s3
	v_readlane_b32 s8, v78, s3
	v_readlane_b32 s9, v28, s3
	v_fma_f32 v133, -s6, v16, v133
	v_fma_f32 v181, -s7, v104, v181
	v_fma_f32 v180, -s8, v12, v180
	v_fma_f32 v132, -s9, v96, v132
	s_nop 0
	s_nop 0
	v_readlane_b32 s6, v74, s3
	v_readlane_b32 s7, v14, s35
	v_readlane_b32 s8, v70, s35
	v_readlane_b32 s9, v66, s35
	v_fma_f32 v133, -s6, v10, v133
	v_fma_f32 v181, -s7, v94, v181
	v_fma_f32 v180, -s8, v8, v180
	v_fma_f32 v132, -s9, v92, v132
	s_nop 0
	s_nop 0
	v_readlane_b32 s6, v62, s35
	v_readlane_b32 s7, v14, s3
	v_readlane_b32 s8, v70, s3
	v_readlane_b32 s9, v66, s3
	v_fma_f32 v133, -s6, v4, v133
	v_fma_f32 v181, -s7, v90, v181
	v_fma_f32 v180, -s8, v91, v180
	v_fma_f32 v132, -s9, v88, v132
	s_nop 0
	s_nop 0
	v_readlane_b32 s6, v62, s3
	s_nop 1
	v_fma_f32 v133, -s6, v89, v133
	s_nop 0
	v_pk_add_f32 v[132:133], v[180:181], v[132:133]
	v_mov_b32_e32 v181, v123
	v_mov_b32_e32 v180, v123
	v_pk_add_f32 v[132:133], v[132:133], v[132:133] op_sel:[0,1] op_sel_hi:[1,0]
	s_nop 0
	s_nop 0
	v_readlane_b32 s6, v144, s16
	v_readlane_b32 s7, v140, s16
	v_readlane_b32 s8, v6, s30
	v_readlane_b32 s9, v142, s30
	v_fma_f32 v73, -s6, v132, v73
	v_fma_f32 v181, -s7, v68, v181
	v_fma_f32 v180, -s8, v130, v180
	v_fma_f32 v72, -s9, v64, v72
	v_mov_b32_e32 v133, v68
	s_nop 0
	v_readlane_b32 s6, v24, s30
	v_readlane_b32 s7, v84, s30
	v_readlane_b32 s8, v6, s16
	v_readlane_b32 s9, v142, s16
	v_fma_f32 v73, -s6, v128, v73
	v_fma_f32 v181, -s7, v32, v181
	v_fma_f32 v180, -s8, v118, v180
	v_fma_f32 v72, -s9, v30, v72
	s_nop 0
	s_nop 0
	v_readlane_b32 s6, v24, s16
	v_readlane_b32 s7, v84, s16
	v_readlane_b32 s8, v82, s30
	v_readlane_b32 s9, v78, s30
	v_fma_f32 v73, -s6, v116, v73
	v_fma_f32 v181, -s7, v26, v181
	v_fma_f32 v180, -s8, v114, v180
	v_fma_f32 v72, -s9, v22, v72
	s_nop 0
	s_nop 0
	v_readlane_b32 s6, v28, s30
	v_readlane_b32 s7, v74, s30
	v_readlane_b32 s8, v82, s16
	v_readlane_b32 s9, v78, s16
	v_fma_f32 v73, -s6, v110, v73
	v_fma_f32 v181, -s7, v16, v181
	v_fma_f32 v180, -s8, v104, v180
	v_fma_f32 v72, -s9, v12, v72
	s_nop 0
	s_nop 0
	v_readlane_b32 s6, v28, s16
	v_readlane_b32 s7, v74, s16
	v_readlane_b32 s8, v14, s30
	v_readlane_b32 s9, v70, s30
	v_fma_f32 v73, -s6, v96, v73
	v_fma_f32 v181, -s7, v10, v181
	v_fma_f32 v180, -s8, v94, v180
	v_fma_f32 v72, -s9, v8, v72
	s_nop 0
	s_nop 0
	v_readlane_b32 s6, v66, s30
	v_readlane_b32 s7, v62, s30
	v_readlane_b32 s8, v14, s16
	v_readlane_b32 s9, v70, s16
	v_fma_f32 v73, -s6, v92, v73
	v_fma_f32 v181, -s7, v4, v181
	v_fma_f32 v180, -s8, v90, v180
	v_fma_f32 v72, -s9, v91, v72
	s_nop 0
	s_nop 0
	v_readlane_b32 s6, v66, s16
	s_nop 1
	v_fma_f32 v73, -s6, v88, v73
	s_nop 0
	s_nop 0
	v_readlane_b32 s6, v62, s16
	s_nop 1
	v_fma_f32 v73, -s6, v89, v73
	s_nop 0
	v_pk_add_f32 v[72:73], v[180:181], v[72:73]
	v_mov_b32_e32 v181, v123
	v_mov_b32_e32 v180, v123
	v_pk_add_f32 v[72:73], v[72:73], v[72:73] op_sel:[0,1] op_sel_hi:[1,0]
	s_nop 0
	s_nop 0
	v_readlane_b32 s6, v146, s17
	v_readlane_b32 s7, v144, s17
	v_readlane_b32 s8, v140, s17
	v_readlane_b32 s9, v6, s36
	v_fma_f32 v135, -s6, v72, v135
	v_fma_f32 v181, -s7, v132, v181
	v_fma_f32 v180, -s8, v68, v180
	v_fma_f32 v134, -s9, v130, v134
	s_nop 0
	s_nop 0
	v_readlane_b32 s6, v142, s36
	v_readlane_b32 s7, v24, s36
	v_readlane_b32 s8, v84, s36
	v_readlane_b32 s9, v6, s17
	v_fma_f32 v135, -s6, v64, v135
	v_fma_f32 v181, -s7, v128, v181
	v_fma_f32 v180, -s8, v32, v180
	v_fma_f32 v134, -s9, v118, v134
	s_nop 0
	s_nop 0
	v_readlane_b32 s6, v142, s17
	v_readlane_b32 s7, v24, s17
	v_readlane_b32 s8, v84, s17
	v_readlane_b32 s9, v82, s36
	v_fma_f32 v135, -s6, v30, v135
	v_fma_f32 v181, -s7, v116, v181
	v_fma_f32 v180, -s8, v26, v180
	v_fma_f32 v134, -s9, v114, v134
	s_nop 0
	s_nop 0
	v_readlane_b32 s6, v78, s36
	v_readlane_b32 s7, v28, s36
	v_readlane_b32 s8, v74, s36
	v_readlane_b32 s9, v82, s17
	v_fma_f32 v135, -s6, v22, v135
	v_fma_f32 v181, -s7, v110, v181
	v_fma_f32 v180, -s8, v16, v180
	v_fma_f32 v134, -s9, v104, v134
	s_nop 0
	s_nop 0
	v_readlane_b32 s6, v78, s17
	v_readlane_b32 s7, v28, s17
	v_readlane_b32 s8, v74, s17
	v_readlane_b32 s9, v14, s36
	v_fma_f32 v135, -s6, v12, v135
	v_fma_f32 v181, -s7, v96, v181
	v_fma_f32 v180, -s8, v10, v180
	v_fma_f32 v134, -s9, v94, v134
	s_nop 0
	s_nop 0
	v_readlane_b32 s6, v70, s36
	v_readlane_b32 s7, v66, s36
	v_readlane_b32 s8, v62, s36
	v_readlane_b32 s9, v14, s17
	v_fma_f32 v135, -s6, v8, v135
	v_fma_f32 v181, -s7, v92, v181
	v_fma_f32 v180, -s8, v4, v180
	v_fma_f32 v134, -s9, v90, v134
	s_nop 0
	s_nop 0
	v_readlane_b32 s6, v70, s17
	s_nop 1
	v_fma_f32 v135, -s6, v91, v135
	s_nop 0
	s_nop 0
	v_readlane_b32 s6, v66, s17
	s_nop 1
	v_fma_f32 v135, -s6, v88, v135
	s_nop 0
	s_nop 0
	v_readlane_b32 s6, v62, s17
	s_nop 1
	v_fma_f32 v135, -s6, v89, v135
	s_nop 0
	v_pk_add_f32 v[134:135], v[180:181], v[134:135]
	v_mov_b32_e32 v181, v123
	v_mov_b32_e32 v180, v123
	v_pk_add_f32 v[134:135], v[134:135], v[134:135] op_sel:[0,1] op_sel_hi:[1,0]
	s_nop 0
	s_nop 0
	v_readlane_b32 s6, v2, s69
	v_readlane_b32 s7, v146, s69
	v_readlane_b32 s8, v144, s69
	v_readlane_b32 s9, v140, s69
	v_fma_f32 v77, -s6, v134, v77
	v_fma_f32 v181, -s7, v72, v181
	v_fma_f32 v180, -s8, v132, v180
	v_fma_f32 v76, -s9, v68, v76
	v_mov_b32_e32 v135, v72
	s_nop 0
	v_readlane_b32 s6, v6, s12
	v_readlane_b32 s7, v142, s12
	v_readlane_b32 s8, v24, s12
	v_readlane_b32 s9, v84, s12
	v_fma_f32 v77, -s6, v130, v77
	v_fma_f32 v181, -s7, v64, v181
	v_fma_f32 v180, -s8, v128, v180
	v_fma_f32 v76, -s9, v32, v76
	s_nop 0
	s_nop 0
	v_readlane_b32 s6, v6, s69
	v_readlane_b32 s7, v142, s69
	v_readlane_b32 s8, v24, s69
	v_readlane_b32 s9, v84, s69
	v_fma_f32 v77, -s6, v118, v77
	v_fma_f32 v181, -s7, v30, v181
	v_fma_f32 v180, -s8, v116, v180
	v_fma_f32 v76, -s9, v26, v76
	s_nop 0
	s_nop 0
	v_readlane_b32 s6, v82, s12
	v_readlane_b32 s7, v78, s12
	v_readlane_b32 s8, v28, s12
	v_readlane_b32 s9, v74, s12
	v_fma_f32 v77, -s6, v114, v77
	v_fma_f32 v181, -s7, v22, v181
	v_fma_f32 v180, -s8, v110, v180
	v_fma_f32 v76, -s9, v16, v76
	s_nop 0
	s_nop 0
	v_readlane_b32 s6, v82, s69
	v_readlane_b32 s7, v78, s69
	v_readlane_b32 s8, v28, s69
	v_readlane_b32 s9, v74, s69
	v_fma_f32 v77, -s6, v104, v77
	v_fma_f32 v181, -s7, v12, v181
	v_fma_f32 v180, -s8, v96, v180
	v_fma_f32 v76, -s9, v10, v76
	s_nop 0
	s_nop 0
	v_readlane_b32 s6, v14, s12
	v_readlane_b32 s7, v70, s12
	v_readlane_b32 s8, v66, s12
	v_readlane_b32 s9, v62, s12
	v_fma_f32 v77, -s6, v94, v77
	v_fma_f32 v181, -s7, v8, v181
	v_fma_f32 v180, -s8, v92, v180
	v_fma_f32 v76, -s9, v4, v76
	s_nop 0
	s_nop 0
	v_readlane_b32 s6, v14, s69
	v_readlane_b32 s7, v70, s69
	v_readlane_b32 s8, v66, s69
	v_readlane_b32 s9, v62, s69
	v_fma_f32 v77, -s6, v90, v77
	v_fma_f32 v181, -s7, v91, v181
	v_fma_f32 v180, -s8, v88, v180
	v_fma_f32 v76, -s9, v89, v76
	s_nop 0
	v_pk_add_f32 v[76:77], v[180:181], v[76:77]
	v_mov_b32_e32 v181, v123
	v_mov_b32_e32 v180, v123
	v_pk_add_f32 v[76:77], v[76:77], v[76:77] op_sel:[0,1] op_sel_hi:[1,0]
	s_nop 0
	s_nop 0
	v_readlane_b32 s6, v140, s15
	v_readlane_b32 s7, v2, s23
	v_readlane_b32 s8, v146, s23
	v_readlane_b32 s9, v144, s23
	v_fma_f32 v137, -s6, v76, v137
	v_fma_f32 v181, -s7, v134, v181
	v_fma_f32 v180, -s8, v72, v180
	v_fma_f32 v136, -s9, v132, v136
	s_nop 0
	s_nop 0
	v_readlane_b32 s6, v140, s23
	v_readlane_b32 s7, v6, s15
	v_readlane_b32 s8, v142, s15
	v_readlane_b32 s9, v24, s15
	v_fma_f32 v137, -s6, v68, v137
	v_fma_f32 v181, -s7, v130, v181
	v_fma_f32 v180, -s8, v64, v180
	v_fma_f32 v136, -s9, v128, v136
	s_nop 0
	s_nop 0
	v_readlane_b32 s6, v84, s15
	v_readlane_b32 s7, v6, s23
	v_readlane_b32 s8, v142, s23
	v_readlane_b32 s9, v24, s23
	v_fma_f32 v137, -s6, v32, v137
	v_fma_f32 v181, -s7, v118, v181
	v_fma_f32 v180, -s8, v30, v180
	v_fma_f32 v136, -s9, v116, v136
	s_nop 0
	s_nop 0
	v_readlane_b32 s6, v84, s23
	v_readlane_b32 s7, v82, s15
	v_readlane_b32 s8, v78, s15
	v_readlane_b32 s9, v28, s15
	v_fma_f32 v137, -s6, v26, v137
	v_fma_f32 v181, -s7, v114, v181
	v_fma_f32 v180, -s8, v22, v180
	v_fma_f32 v136, -s9, v110, v136
	s_nop 0
	s_nop 0
	v_readlane_b32 s6, v74, s15
	v_readlane_b32 s7, v82, s23
	v_readlane_b32 s8, v78, s23
	v_readlane_b32 s9, v28, s23
	v_fma_f32 v137, -s6, v16, v137
	v_fma_f32 v181, -s7, v104, v181
	v_fma_f32 v180, -s8, v12, v180
	v_fma_f32 v136, -s9, v96, v136
	s_nop 0
	s_nop 0
	v_readlane_b32 s6, v74, s23
	v_readlane_b32 s7, v14, s15
	v_readlane_b32 s8, v70, s15
	v_readlane_b32 s9, v66, s15
	v_fma_f32 v137, -s6, v10, v137
	v_fma_f32 v181, -s7, v94, v181
	v_fma_f32 v180, -s8, v8, v180
	v_fma_f32 v136, -s9, v92, v136
	s_nop 0
	s_nop 0
	v_readlane_b32 s6, v62, s15
	v_readlane_b32 s7, v14, s23
	v_readlane_b32 s8, v70, s23
	v_readlane_b32 s9, v66, s23
	v_fma_f32 v137, -s6, v4, v137
	v_fma_f32 v181, -s7, v90, v181
	v_fma_f32 v180, -s8, v91, v180
	v_fma_f32 v136, -s9, v88, v136
	s_nop 0
	s_nop 0
	v_readlane_b32 s6, v62, s23
	s_nop 1
	v_fma_f32 v137, -s6, v89, v137
	s_nop 0
	v_pk_add_f32 v[136:137], v[180:181], v[136:137]
	v_mov_b32_e32 v181, v123
	v_mov_b32_e32 v180, v123
	v_pk_add_f32 v[136:137], v[136:137], v[136:137] op_sel:[0,1] op_sel_hi:[1,0]
	s_nop 0
	s_nop 0
	v_readlane_b32 s6, v144, s26
	v_readlane_b32 s7, v140, s26
	v_readlane_b32 s8, v2, s10
	v_readlane_b32 s9, v146, s10
	v_fma_f32 v81, -s6, v136, v81
	v_fma_f32 v181, -s7, v76, v181
	v_fma_f32 v180, -s8, v134, v180
	v_fma_f32 v80, -s9, v72, v80
	v_mov_b32_e32 v137, v76
	s_nop 0
	v_readlane_b32 s6, v144, s10
	v_readlane_b32 s7, v140, s10
	v_readlane_b32 s8, v6, s26
	v_readlane_b32 s9, v142, s26
	v_fma_f32 v81, -s6, v132, v81
	v_fma_f32 v181, -s7, v68, v181
	v_fma_f32 v180, -s8, v130, v180
	v_fma_f32 v80, -s9, v64, v80
	s_nop 0
	s_nop 0
	v_readlane_b32 s6, v24, s26
	v_readlane_b32 s7, v84, s26
	v_readlane_b32 s8, v6, s10
	v_readlane_b32 s9, v142, s10
	v_fma_f32 v81, -s6, v128, v81
	v_fma_f32 v181, -s7, v32, v181
	v_fma_f32 v180, -s8, v118, v180
	v_fma_f32 v80, -s9, v30, v80
	s_nop 0
	s_nop 0
	v_readlane_b32 s6, v24, s10
	v_readlane_b32 s7, v84, s10
	v_readlane_b32 s8, v82, s26
	v_readlane_b32 s9, v78, s26
	v_fma_f32 v81, -s6, v116, v81
	v_fma_f32 v181, -s7, v26, v181
	v_fma_f32 v180, -s8, v114, v180
	v_fma_f32 v80, -s9, v22, v80
	s_nop 0
	s_nop 0
	v_readlane_b32 s6, v28, s26
	v_readlane_b32 s7, v74, s26
	v_readlane_b32 s8, v82, s10
	v_readlane_b32 s9, v78, s10
	v_fma_f32 v81, -s6, v110, v81
	v_fma_f32 v181, -s7, v16, v181
	v_fma_f32 v180, -s8, v104, v180
	v_fma_f32 v80, -s9, v12, v80
	s_nop 0
	s_nop 0
	v_readlane_b32 s6, v28, s10
	v_readlane_b32 s7, v74, s10
	v_readlane_b32 s8, v14, s26
	v_readlane_b32 s9, v70, s26
	v_fma_f32 v81, -s6, v96, v81
	v_fma_f32 v181, -s7, v10, v181
	v_fma_f32 v180, -s8, v94, v180
	v_fma_f32 v80, -s9, v8, v80
	s_nop 0
	s_nop 0
	v_readlane_b32 s6, v66, s26
	v_readlane_b32 s7, v62, s26
	v_readlane_b32 s8, v14, s10
	v_readlane_b32 s9, v70, s10
	v_fma_f32 v81, -s6, v92, v81
	v_fma_f32 v181, -s7, v4, v181
	v_fma_f32 v180, -s8, v90, v180
	v_fma_f32 v80, -s9, v91, v80
	s_nop 0
	s_nop 0
	v_readlane_b32 s6, v66, s10
	s_nop 1
	v_fma_f32 v81, -s6, v88, v81
	s_nop 0
	s_nop 0
	v_readlane_b32 s6, v62, s10
	s_nop 1
	v_fma_f32 v81, -s6, v89, v81
	s_nop 0
	v_pk_add_f32 v[80:81], v[180:181], v[80:81]
	v_mov_b32_e32 v181, v123
	v_mov_b32_e32 v180, v123
	v_pk_add_f32 v[80:81], v[80:81], v[80:81] op_sel:[0,1] op_sel_hi:[1,0]
	s_nop 0
	s_nop 0
	v_readlane_b32 s6, v146, s13
	v_readlane_b32 s7, v144, s13
	v_readlane_b32 s8, v140, s13
	v_readlane_b32 s9, v2, s31
	v_fma_f32 v139, -s6, v80, v139
	v_fma_f32 v181, -s7, v136, v181
	v_fma_f32 v180, -s8, v76, v180
	v_fma_f32 v138, -s9, v134, v138
	v_mov_b32_e32 v2, v123
	s_nop 0
	v_readlane_b32 s6, v146, s31
	v_readlane_b32 s7, v144, s31
	v_readlane_b32 s8, v140, s31
	v_readlane_b32 s9, v6, s13
	v_fma_f32 v139, -s6, v72, v139
	v_fma_f32 v181, -s7, v132, v181
	v_fma_f32 v180, -s8, v68, v180
	v_fma_f32 v138, -s9, v130, v138
	v_mov_b32_e32 v140, v123
	s_nop 0
	v_readlane_b32 s6, v142, s13
	v_readlane_b32 s7, v24, s13
	v_readlane_b32 s8, v84, s13
	v_readlane_b32 s9, v6, s31
	v_fma_f32 v139, -s6, v64, v139
	v_fma_f32 v181, -s7, v128, v181
	v_fma_f32 v180, -s8, v32, v180
	v_fma_f32 v138, -s9, v118, v138
	v_mov_b32_e32 v144, v123
	s_nop 0
	v_readlane_b32 s6, v142, s31
	v_readlane_b32 s7, v24, s31
	v_readlane_b32 s8, v84, s31
	v_readlane_b32 s9, v82, s13
	v_fma_f32 v139, -s6, v30, v139
	v_fma_f32 v181, -s7, v116, v181
	v_fma_f32 v180, -s8, v26, v180
	v_fma_f32 v138, -s9, v114, v138
	v_mov_b32_e32 v142, v123
	s_nop 0
	v_readlane_b32 s6, v78, s13
	v_readlane_b32 s7, v28, s13
	v_readlane_b32 s8, v74, s13
	v_readlane_b32 s9, v82, s31
	v_fma_f32 v139, -s6, v22, v139
	v_fma_f32 v181, -s7, v110, v181
	v_fma_f32 v180, -s8, v16, v180
	v_fma_f32 v138, -s9, v104, v138
	v_mov_b32_e32 v146, v123
	s_nop 0
	v_readlane_b32 s6, v78, s31
	v_readlane_b32 s7, v28, s31
	v_readlane_b32 s8, v74, s31
	v_readlane_b32 s9, v14, s13
	v_fma_f32 v139, -s6, v12, v139
	v_fma_f32 v181, -s7, v96, v181
	v_fma_f32 v180, -s8, v10, v180
	v_fma_f32 v138, -s9, v94, v138
	v_mov_b32_e32 v84, v123
	s_nop 0
	v_readlane_b32 s6, v70, s13
	v_readlane_b32 s7, v66, s13
	v_readlane_b32 s8, v62, s13
	v_readlane_b32 s9, v14, s31
	v_fma_f32 v139, -s6, v8, v139
	v_fma_f32 v181, -s7, v92, v181
	v_fma_f32 v180, -s8, v4, v180
	v_fma_f32 v138, -s9, v90, v138
	v_mov_b32_e32 v82, v123
	s_nop 0
	v_readlane_b32 s6, v70, s31
	s_nop 1
	v_fma_f32 v139, -s6, v91, v139
	v_mov_b32_e32 v78, v123
	s_nop 0
	v_readlane_b32 s6, v66, s31
	s_nop 1
	v_fma_f32 v139, -s6, v88, v139
	v_mov_b32_e32 v74, v123
	s_nop 0
	v_readlane_b32 s6, v62, s31
	s_nop 1
	v_fma_f32 v139, -s6, v89, v139
	v_mov_b32_e32 v70, v123
	v_pk_add_f32 v[138:139], v[180:181], v[138:139]
	v_mov_b32_e32 v181, v123
	v_mov_b32_e32 v180, v123
	v_pk_add_f32 v[138:139], v[138:139], v[138:139] op_sel:[0,1] op_sel_hi:[1,0]
	v_mov_b32_e32 v66, v123
	v_readlane_b32 s98, v251, 55
	s_nop 3
	s_mul_i32 s98, s98, 9
	s_add_i32 s98, s98, 0x4000
	v_mbcnt_lo_u32_b32 v255, -1, 0
	v_mbcnt_hi_u32_b32 v255, -1, v255
	v_and_b32_e32 v253, 31, v255
	v_lshrrev_b32_e32 v254, 5, v255
	v_cmp_lt_u32_e64 s[96:97], 31, v255
	v_mul_u32_u24_e32 v248, 0x210, v254
	v_lshl_add_u32 v248, v253, 2, v248
	v_add_u32_e32 v248, s98, v248
	v_mul_u32_u24_e32 v249, 0x84, v253
	v_add_u32_e32 v249, s98, v249
	v_lshlrev_b32_e32 v255, 2, v253
	v_add_u32_e32 v255, 0x1080, v255
	v_add_u32_e32 v255, s98, v255
	ds_write_b32 v255, v123
	s_add_i32 s98, s98, 0x1080
	v_mov_b32_e32 v253, s98
	s_nop 1
	v_cndmask_b32_e64 v249, v253, v249, s[96:97]
	v_mov_b32_e32 v244, v134
	v_mov_b32_e32 v245, v138
	s_nop 1
	v_permlane32_swap_b32_e32 v245, v244
	s_nop 1
	v_mfma_f32_32x32x2_f32 v[228:243], v244, v226, 0
	v_mov_b32_e32 v246, v72
	v_mov_b32_e32 v247, v80
	s_nop 1
	v_permlane32_swap_b32_e32 v247, v246
	s_nop 1
	v_mfma_f32_32x32x2_f32 v[228:243], v246, v225, v[228:243]
	v_mov_b32_e32 v244, v132
	v_mov_b32_e32 v245, v136
	s_nop 1
	v_permlane32_swap_b32_e32 v245, v244
	s_nop 1
	v_mfma_f32_32x32x2_f32 v[228:243], v244, v224, v[228:243]
	v_mov_b32_e32 v246, v68
	v_mov_b32_e32 v247, v76
	s_nop 1
	v_permlane32_swap_b32_e32 v247, v246
	s_nop 1
	v_mfma_f32_32x32x2_f32 v[228:243], v246, v223, v[228:243]
	v_mov_b32_e32 v244, v118
	v_mov_b32_e32 v245, v130
	s_nop 1
	v_permlane32_swap_b32_e32 v245, v244
	s_nop 1
	v_mfma_f32_32x32x2_f32 v[228:243], v244, v222, v[228:243]
	v_mov_b32_e32 v246, v30
	v_mov_b32_e32 v247, v64
	s_nop 1
	v_permlane32_swap_b32_e32 v247, v246
	s_nop 1
	v_mfma_f32_32x32x2_f32 v[228:243], v246, v221, v[228:243]
	v_mov_b32_e32 v244, v116
	v_mov_b32_e32 v245, v128
	s_nop 1
	v_permlane32_swap_b32_e32 v245, v244
	s_nop 1
	v_mfma_f32_32x32x2_f32 v[228:243], v244, v220, v[228:243]
	v_mov_b32_e32 v246, v26
	v_mov_b32_e32 v247, v32
	s_nop 1
	v_permlane32_swap_b32_e32 v247, v246
	s_nop 1
	v_mfma_f32_32x32x2_f32 v[228:243], v246, v219, v[228:243]
	v_mov_b32_e32 v244, v104
	v_mov_b32_e32 v245, v114
	s_nop 1
	v_permlane32_swap_b32_e32 v245, v244
	s_nop 1
	v_mfma_f32_32x32x2_f32 v[228:243], v244, v218, v[228:243]
	v_mov_b32_e32 v246, v12
	v_mov_b32_e32 v247, v22
	s_nop 1
	v_permlane32_swap_b32_e32 v247, v246
	s_nop 1
	v_mfma_f32_32x32x2_f32 v[228:243], v246, v217, v[228:243]
	v_mov_b32_e32 v244, v96
	v_mov_b32_e32 v245, v110
	s_nop 1
	v_permlane32_swap_b32_e32 v245, v244
	s_nop 1
	v_mfma_f32_32x32x2_f32 v[228:243], v244, v216, v[228:243]
	v_mov_b32_e32 v246, v10
	v_mov_b32_e32 v247, v16
	s_nop 1
	v_permlane32_swap_b32_e32 v247, v246
	s_nop 1
	v_mfma_f32_32x32x2_f32 v[228:243], v246, v215, v[228:243]
	v_mov_b32_e32 v244, v90
	v_mov_b32_e32 v245, v94
	s_nop 1
	v_permlane32_swap_b32_e32 v245, v244
	s_nop 1
	v_mfma_f32_32x32x2_f32 v[228:243], v244, v214, v[228:243]
	v_mov_b32_e32 v246, v91
	v_mov_b32_e32 v247, v8
	s_nop 1
	v_permlane32_swap_b32_e32 v247, v246
	s_nop 1
	v_mfma_f32_32x32x2_f32 v[228:243], v246, v213, v[228:243]
	v_mov_b32_e32 v244, v88
	v_mov_b32_e32 v245, v92
	s_nop 1
	v_permlane32_swap_b32_e32 v245, v244
	s_nop 1
	v_mfma_f32_32x32x2_f32 v[228:243], v244, v212, v[228:243]
	v_mov_b32_e32 v246, v89
	v_mov_b32_e32 v247, v4
	s_nop 1
	v_permlane32_swap_b32_e32 v247, v246
	s_nop 1
	v_mfma_f32_32x32x2_f32 v[228:243], v246, v211, v[228:243]
	s_mov_b32 s96, 0x9003000
	s_mov_b32 s97, 0
	v_lshl_add_u64 v[244:245], v[98:99], 0, s[96:97]
	global_load_dwordx4 v[212:215], v[244:245], off offset:-4096
	global_load_dwordx4 v[216:219], v[244:245], off offset:-4064
	global_load_dwordx4 v[220:223], v[244:245], off offset:-4032
	global_load_dwordx4 v[224:227], v[244:245], off offset:-4000
	s_nop 15
	ds_write_b32 v248, v228 offset:0
	ds_write_b32 v248, v229 offset:132
	ds_write_b32 v248, v230 offset:264
	ds_write_b32 v248, v231 offset:396
	ds_write_b32 v248, v232 offset:1056
	ds_write_b32 v248, v233 offset:1188
	ds_write_b32 v248, v234 offset:1320
	ds_write_b32 v248, v235 offset:1452
	ds_write_b32 v248, v236 offset:2112
	ds_write_b32 v248, v237 offset:2244
	ds_write_b32 v248, v238 offset:2376
	ds_write_b32 v248, v239 offset:2508
	ds_write_b32 v248, v240 offset:3168
	ds_write_b32 v248, v241 offset:3300
	ds_write_b32 v248, v242 offset:3432
	ds_write_b32 v248, v243 offset:3564
	s_waitcnt lgkmcnt(0)
	ds_read_b32 v246, v249 offset:124
	global_load_dwordx4 v[228:231], v[244:245], off
	global_load_dwordx4 v[232:235], v[244:245], off offset:32
	global_load_dwordx4 v[236:239], v[244:245], off offset:64
	global_load_dwordx4 v[240:243], v[244:245], off offset:96
	s_waitcnt lgkmcnt(0)
	v_sub_f32_e32 v153, v153, v246
	ds_read_b32 v247, v249 offset:120
	s_nop 0
	v_mov_b32_e32 v62, v123
	s_nop 0
	v_mov_b32_e32 v28, v123
	s_nop 0
	v_mov_b32_e32 v24, v123
	s_nop 0
	v_mov_b32_e32 v14, v123
	s_nop 0
	v_mov_b32_e32 v6, v123
	s_nop 0
	v_mov_b32_e32 v139, v80
	s_nop 0
	s_nop 0
	s_nop 0
	s_mov_b32 s20, 30
	v_pk_add_f32 v[152:153], v[180:181], v[152:153]
	v_mov_b32_e32 v181, v123
	v_mov_b32_e32 v180, v123
	v_pk_add_f32 v[152:153], v[152:153], v[152:153] op_sel:[0,1] op_sel_hi:[1,0]
	s_nop 0
	s_waitcnt lgkmcnt(0)
	v_sub_f32_e32 v141, v141, v247
	ds_read_b32 v246, v249 offset:116
	s_nop 0
	v_readlane_b32 s6, v209, s54
	s_nop 1
	v_fma_f32 v141, -s6, v152, v141
	s_nop 0
	s_nop 0
	s_nop 0
	s_nop 0
	s_nop 0
	s_nop 0
	s_nop 0
	s_nop 0
	s_nop 0
	s_nop 0
	s_nop 0
	s_nop 0
	s_nop 0
	s_nop 0
	s_mov_b32 s20, 29
	s_nop 0
	s_nop 1
	s_nop 0
	v_pk_add_f32 v[140:141], v[180:181], v[140:141]
	v_mov_b32_e32 v181, v123
	v_mov_b32_e32 v180, v123
	v_pk_add_f32 v[140:141], v[140:141], v[140:141] op_sel:[0,1] op_sel_hi:[1,0]
	s_nop 0
	s_waitcnt lgkmcnt(0)
	v_sub_f32_e32 v159, v159, v246
	ds_read_b32 v247, v249 offset:112
	s_nop 0
	v_readlane_b32 s6, v207, s55
	v_readlane_b32 s7, v209, s55
	s_nop 0
	v_fma_f32 v159, -s6, v140, v159
	v_fma_f32 v181, -s7, v152, v181
	v_mov_b32_e32 v141, v152
	s_nop 0
	s_nop 0
	s_nop 0
	s_nop 0
	s_nop 0
	s_nop 0
	s_nop 0
	s_nop 0
	s_nop 0
	s_nop 0
	s_nop 0
	s_nop 0
	s_nop 0
	s_mov_b32 s20, 28
	s_nop 0
	s_nop 1
	s_nop 0
	s_nop 0
	s_nop 1
	s_nop 0
	v_pk_add_f32 v[158:159], v[180:181], v[158:159]
	v_mov_b32_e32 v181, v123
	v_mov_b32_e32 v180, v123
	v_pk_add_f32 v[158:159], v[158:159], v[158:159] op_sel:[0,1] op_sel_hi:[1,0]
	s_nop 0
	s_waitcnt lgkmcnt(0)
	v_sub_f32_e32 v143, v143, v247
	ds_read_b32 v246, v249 offset:108
	s_nop 0
	v_readlane_b32 s6, v208, s56
	v_readlane_b32 s7, v207, s56
	v_readlane_b32 s8, v209, s56
	v_fma_f32 v143, -s6, v158, v143
	v_fma_f32 v181, -s7, v140, v181
	v_fma_f32 v180, -s8, v152, v180
	s_nop 0
	s_nop 0
	s_nop 0
	s_nop 0
	s_nop 0
	s_nop 0
	s_nop 0
	s_nop 0
	s_nop 0
	s_nop 0
	s_nop 0
	s_nop 0
	s_nop 0
	s_nop 0
	s_mov_b32 s20, 27
	s_nop 0
	s_nop 1
	s_nop 0
	s_nop 0
	s_nop 1
	s_nop 0
	s_nop 0
	s_nop 1
	s_nop 0
	v_pk_add_f32 v[142:143], v[180:181], v[142:143]
	v_mov_b32_e32 v181, v123
	v_mov_b32_e32 v180, v123
	v_pk_add_f32 v[142:143], v[142:143], v[142:143] op_sel:[0,1] op_sel_hi:[1,0]
	s_nop 0
	s_waitcnt lgkmcnt(0)
	v_sub_f32_e32 v167, v167, v246
	ds_read_b32 v247, v249 offset:104
	s_nop 0
	v_readlane_b32 s6, v205, s57
	v_readlane_b32 s7, v208, s57
	v_readlane_b32 s8, v207, s57
	v_readlane_b32 s9, v209, s57
	v_fma_f32 v167, -s6, v142, v167
	v_fma_f32 v181, -s7, v158, v181
	v_fma_f32 v180, -s8, v140, v180
	v_fma_f32 v166, -s9, v152, v166
	v_mov_b32_e32 v143, v158
	s_nop 0
	s_nop 0
	s_nop 0
	s_nop 0
	s_nop 0
	s_nop 0
	s_nop 0
	s_nop 0
	s_nop 0
	s_nop 0
	s_nop 0
	s_nop 0
	s_nop 0
	s_nop 0
	s_nop 0
	s_nop 0
	v_pk_add_f32 v[166:167], v[180:181], v[166:167]
	v_mov_b32_e32 v181, v123
	v_mov_b32_e32 v180, v123
	v_pk_add_f32 v[166:167], v[166:167], v[166:167] op_sel:[0,1] op_sel_hi:[1,0]
	s_nop 0
	s_waitcnt lgkmcnt(0)
	v_sub_f32_e32 v145, v145, v247
	ds_read_b32 v246, v249 offset:100
	s_nop 0
	v_readlane_b32 s6, v209, s53
	v_readlane_b32 s7, v205, s58
	v_readlane_b32 s8, v208, s58
	v_readlane_b32 s9, v207, s58
	v_fma_f32 v145, -s6, v166, v145
	v_fma_f32 v181, -s7, v142, v181
	v_fma_f32 v180, -s8, v158, v180
	v_fma_f32 v144, -s9, v140, v144
	s_nop 0
	s_nop 0
	v_readlane_b32 s6, v209, s58
	s_nop 1
	v_fma_f32 v145, -s6, v152, v145
	s_nop 0
	s_nop 0
	s_nop 0
	s_nop 0
	s_nop 0
	s_nop 0
	s_nop 0
	s_nop 0
	s_nop 0
	s_nop 0
	s_nop 0
	s_nop 0
	s_nop 0
	s_nop 0
	s_nop 0
	s_nop 0
	s_nop 1
	s_nop 0
	v_pk_add_f32 v[144:145], v[180:181], v[144:145]
	v_mov_b32_e32 v181, v123
	v_mov_b32_e32 v180, v123
	v_pk_add_f32 v[144:145], v[144:145], v[144:145] op_sel:[0,1] op_sel_hi:[1,0]
	s_nop 0
	s_waitcnt lgkmcnt(0)
	v_sub_f32_e32 v171, v171, v246
	ds_read_b32 v247, v249 offset:96
	s_nop 0
	v_readlane_b32 s6, v207, s52
	v_readlane_b32 s7, v209, s52
	v_readlane_b32 s8, v205, s59
	v_readlane_b32 s9, v208, s59
	v_fma_f32 v171, -s6, v144, v171
	v_fma_f32 v181, -s7, v166, v181
	v_fma_f32 v180, -s8, v142, v180
	v_fma_f32 v170, -s9, v158, v170
	v_mov_b32_e32 v145, v166
	s_nop 0
	v_readlane_b32 s6, v207, s59
	v_readlane_b32 s7, v209, s59
	s_nop 0
	v_fma_f32 v171, -s6, v140, v171
	v_fma_f32 v181, -s7, v152, v181
	s_nop 0
	s_nop 0
	s_nop 0
	s_nop 0
	s_nop 0
	s_nop 0
	s_nop 0
	s_nop 0
	s_nop 0
	s_nop 0
	s_nop 0
	s_nop 0
	s_nop 0
	s_nop 0
	s_nop 0
	s_nop 0
	s_nop 1
	s_nop 0
	s_nop 0
	s_nop 1
	s_nop 0
	v_pk_add_f32 v[170:171], v[180:181], v[170:171]
	v_mov_b32_e32 v181, v123
	v_mov_b32_e32 v180, v123
	v_pk_add_f32 v[170:171], v[170:171], v[170:171] op_sel:[0,1] op_sel_hi:[1,0]
	s_nop 0
	s_waitcnt lgkmcnt(0)
	v_sub_f32_e32 v147, v147, v247
	ds_read_b32 v246, v249 offset:92
	s_nop 0
	v_readlane_b32 s6, v208, s51
	v_readlane_b32 s7, v207, s51
	v_readlane_b32 s8, v209, s51
	v_readlane_b32 s9, v205, s60
	v_fma_f32 v147, -s6, v170, v147
	v_fma_f32 v181, -s7, v144, v181
	v_fma_f32 v180, -s8, v166, v180
	v_fma_f32 v146, -s9, v142, v146
	s_nop 0
	s_nop 0
	v_readlane_b32 s6, v208, s60
	v_readlane_b32 s7, v207, s60
	v_readlane_b32 s8, v209, s60
	v_fma_f32 v147, -s6, v158, v147
	v_fma_f32 v181, -s7, v140, v181
	v_fma_f32 v180, -s8, v152, v180
	s_nop 0
	s_nop 0
	s_nop 0
	s_nop 0
	s_nop 0
	s_nop 0
	s_nop 0
	s_nop 0
	s_nop 0
	s_nop 0
	s_nop 0
	s_nop 0
	s_nop 0
	s_nop 0
	s_nop 0
	s_nop 0
	s_nop 1
	s_nop 0
	s_nop 0
	s_nop 1
	s_nop 0
	s_nop 0
	s_nop 1
	s_nop 0
	v_pk_add_f32 v[146:147], v[180:181], v[146:147]
	v_mov_b32_e32 v181, v123
	v_mov_b32_e32 v180, v123
	v_pk_add_f32 v[146:147], v[146:147], v[146:147] op_sel:[0,1] op_sel_hi:[1,0]
	s_nop 0
	s_waitcnt lgkmcnt(0)
	v_sub_f32_e32 v175, v175, v246
	ds_read_b32 v247, v249 offset:88
	s_nop 0
	v_readlane_b32 s6, v205, s70
	v_readlane_b32 s7, v208, s70
	v_readlane_b32 s8, v207, s70
	v_readlane_b32 s9, v209, s70
	v_fma_f32 v175, -s6, v146, v175
	v_fma_f32 v181, -s7, v170, v181
	v_fma_f32 v180, -s8, v144, v180
	v_fma_f32 v174, -s9, v166, v174
	v_mov_b32_e32 v147, v170
	s_nop 0
	v_readlane_b32 s6, v205, s61
	v_readlane_b32 s7, v208, s61
	v_readlane_b32 s8, v207, s61
	v_readlane_b32 s9, v209, s61
	v_fma_f32 v175, -s6, v142, v175
	v_fma_f32 v181, -s7, v158, v181
	v_fma_f32 v180, -s8, v140, v180
	v_fma_f32 v174, -s9, v152, v174
	s_nop 0
	s_nop 0
	s_nop 0
	s_nop 0
	s_nop 0
	s_nop 0
	s_nop 0
	s_nop 0
	s_nop 0
	s_nop 0
	s_nop 0
	s_nop 0
	s_nop 0
	s_nop 0
	s_nop 0
	s_nop 0
	s_nop 0
	v_pk_add_f32 v[174:175], v[180:181], v[174:175]
	v_mov_b32_e32 v181, v123
	v_mov_b32_e32 v180, v123
	v_pk_add_f32 v[174:175], v[174:175], v[174:175] op_sel:[0,1] op_sel_hi:[1,0]
	s_nop 0
	s_waitcnt lgkmcnt(0)
	v_sub_f32_e32 v149, v149, v247
	ds_read_b32 v246, v249 offset:84
	s_nop 0
	v_readlane_b32 s6, v206, s62
	v_readlane_b32 s7, v205, s71
	v_readlane_b32 s8, v208, s71
	v_readlane_b32 s9, v207, s71
	v_fma_f32 v149, -s6, v174, v149
	v_fma_f32 v181, -s7, v146, v181
	v_fma_f32 v180, -s8, v170, v180
	v_fma_f32 v148, -s9, v144, v148
	s_nop 0
	s_nop 0
	v_readlane_b32 s6, v209, s71
	v_readlane_b32 s7, v205, s62
	v_readlane_b32 s8, v208, s62
	v_readlane_b32 s9, v207, s62
	v_fma_f32 v149, -s6, v166, v149
	v_fma_f32 v181, -s7, v142, v181
	v_fma_f32 v180, -s8, v158, v180
	v_fma_f32 v148, -s9, v140, v148
	s_nop 0
	s_nop 0
	v_readlane_b32 s6, v209, s62
	s_nop 1
	v_fma_f32 v149, -s6, v152, v149
	s_nop 0
	s_nop 0
	s_nop 0
	s_nop 0
	s_nop 0
	s_nop 0
	s_nop 0
	s_nop 0
	s_nop 0
	s_nop 0
	s_nop 0
	s_nop 0
	s_nop 0
	s_nop 0
	s_nop 0
	s_nop 0
	s_nop 1
	s_nop 0
	v_pk_add_f32 v[148:149], v[180:181], v[148:149]
	v_mov_b32_e32 v181, v123
	v_mov_b32_e32 v180, v123
	v_pk_add_f32 v[148:149], v[148:149], v[148:149] op_sel:[0,1] op_sel_hi:[1,0]
	s_nop 0
	s_waitcnt lgkmcnt(0)
	v_sub_f32_e32 v179, v179, v246
	ds_read_b32 v247, v249 offset:80
	s_nop 0
	v_readlane_b32 s6, v203, s63
	v_readlane_b32 s7, v206, s63
	v_readlane_b32 s8, v205, s72
	v_readlane_b32 s9, v208, s72
	v_fma_f32 v179, -s6, v148, v179
	v_fma_f32 v181, -s7, v174, v181
	v_fma_f32 v180, -s8, v146, v180
	v_fma_f32 v178, -s9, v170, v178
	v_mov_b32_e32 v149, v174
	s_nop 0
	v_readlane_b32 s6, v207, s72
	v_readlane_b32 s7, v209, s72
	v_readlane_b32 s8, v205, s63
	v_readlane_b32 s9, v208, s63
	v_fma_f32 v179, -s6, v144, v179
	v_fma_f32 v181, -s7, v166, v181
	v_fma_f32 v180, -s8, v142, v180
	v_fma_f32 v178, -s9, v158, v178
	s_nop 0
	s_nop 0
	v_readlane_b32 s6, v207, s63
	v_readlane_b32 s7, v209, s63
	s_nop 0
	v_fma_f32 v179, -s6, v140, v179
	v_fma_f32 v181, -s7, v152, v181
	s_nop 0
	s_nop 0
	s_nop 0
	s_nop 0
	s_nop 0
	s_nop 0
	s_nop 0
	s_nop 0
	s_nop 0
	s_nop 0
	s_nop 0
	s_nop 0
	s_nop 0
	s_nop 0
	s_nop 0
	s_nop 0
	s_nop 1
	s_nop 0
	s_nop 0
	s_nop 1
	s_nop 0
	v_pk_add_f32 v[178:179], v[180:181], v[178:179]
	v_mov_b32_e32 v181, v123
	v_mov_b32_e32 v180, v123
	v_pk_add_f32 v[178:179], v[178:179], v[178:179] op_sel:[0,1] op_sel_hi:[1,0]
	s_nop 0
	s_waitcnt lgkmcnt(0)
	v_sub_f32_e32 v151, v151, v247
	ds_read_b32 v246, v249 offset:76
	s_nop 0
	v_readlane_b32 s6, v204, s22
	v_readlane_b32 s7, v203, s22
	v_readlane_b32 s8, v206, s22
	v_readlane_b32 s9, v205, s73
	v_fma_f32 v151, -s6, v178, v151
	v_fma_f32 v181, -s7, v148, v181
	v_fma_f32 v180, -s8, v174, v180
	v_fma_f32 v150, -s9, v146, v150
	s_nop 0
	s_nop 0
	v_readlane_b32 s6, v208, s73
	v_readlane_b32 s7, v207, s73
	v_readlane_b32 s8, v209, s73
	v_readlane_b32 s9, v205, s22
	v_fma_f32 v151, -s6, v170, v151
	v_fma_f32 v181, -s7, v144, v181
	v_fma_f32 v180, -s8, v166, v180
	v_fma_f32 v150, -s9, v142, v150
	s_nop 0
	s_nop 0
	v_readlane_b32 s6, v208, s22
	v_readlane_b32 s7, v207, s22
	v_readlane_b32 s8, v209, s22
	v_fma_f32 v151, -s6, v158, v151
	v_fma_f32 v181, -s7, v140, v181
	v_fma_f32 v180, -s8, v152, v180
	s_nop 0
	s_nop 0
	s_nop 0
	s_nop 0
	s_nop 0
	s_nop 0
	s_nop 0
	s_nop 0
	s_nop 0
	s_nop 0
	s_nop 0
	s_nop 0
	s_nop 0
	s_nop 0
	s_nop 0
	s_nop 0
	s_nop 1
	s_nop 0
	s_nop 0
	s_nop 1
	s_nop 0
	s_nop 0
	s_nop 1
	s_nop 0
	v_pk_add_f32 v[150:151], v[180:181], v[150:151]
	v_mov_b32_e32 v181, v123
	v_mov_b32_e32 v180, v123
	v_pk_add_f32 v[150:151], v[150:151], v[150:151] op_sel:[0,1] op_sel_hi:[1,0]
	s_nop 0
	s_waitcnt lgkmcnt(0)
	v_sub_f32_e32 v177, v177, v246
	ds_read_b32 v247, v249 offset:72
	s_nop 0
	v_readlane_b32 s6, v201, s64
	v_readlane_b32 s7, v204, s64
	v_readlane_b32 s8, v203, s64
	v_readlane_b32 s9, v206, s64
	v_fma_f32 v177, -s6, v150, v177
	v_fma_f32 v181, -s7, v178, v181
	v_fma_f32 v180, -s8, v148, v180
	v_fma_f32 v176, -s9, v174, v176
	v_mov_b32_e32 v151, v178
	s_nop 0
	v_readlane_b32 s6, v205, s50
	v_readlane_b32 s7, v208, s50
	v_readlane_b32 s8, v207, s50
	v_readlane_b32 s9, v209, s50
	v_fma_f32 v177, -s6, v146, v177
	v_fma_f32 v181, -s7, v170, v181
	v_fma_f32 v180, -s8, v144, v180
	v_fma_f32 v176, -s9, v166, v176
	s_nop 0
	s_nop 0
	v_readlane_b32 s6, v205, s64
	v_readlane_b32 s7, v208, s64
	v_readlane_b32 s8, v207, s64
	v_readlane_b32 s9, v209, s64
	v_fma_f32 v177, -s6, v142, v177
	v_fma_f32 v181, -s7, v158, v181
	v_fma_f32 v180, -s8, v140, v180
	v_fma_f32 v176, -s9, v152, v176
	s_nop 0
	s_nop 0
	s_nop 0
	s_nop 0
	s_nop 0
	s_nop 0
	s_nop 0
	s_nop 0
	s_nop 0
	s_nop 0
	s_nop 0
	s_nop 0
	s_nop 0
	s_nop 0
	s_nop 0
	s_nop 0
	s_nop 0
	v_pk_add_f32 v[176:177], v[180:181], v[176:177]
	v_mov_b32_e32 v181, v123
	v_mov_b32_e32 v180, v123
	v_pk_add_f32 v[176:177], v[176:177], v[176:177] op_sel:[0,1] op_sel_hi:[1,0]
	s_nop 0
	s_waitcnt lgkmcnt(0)
	v_sub_f32_e32 v157, v157, v247
	ds_read_b32 v246, v249 offset:68
	s_nop 0
	v_readlane_b32 s6, v206, s49
	v_readlane_b32 s7, v201, s65
	v_readlane_b32 s8, v204, s65
	v_readlane_b32 s9, v203, s65
	v_fma_f32 v157, -s6, v176, v157
	v_fma_f32 v181, -s7, v150, v181
	v_fma_f32 v180, -s8, v178, v180
	v_fma_f32 v156, -s9, v148, v156
	s_nop 0
	s_nop 0
	v_readlane_b32 s6, v206, s65
	v_readlane_b32 s7, v205, s49
	v_readlane_b32 s8, v208, s49
	v_readlane_b32 s9, v207, s49
	v_fma_f32 v157, -s6, v174, v157
	v_fma_f32 v181, -s7, v146, v181
	v_fma_f32 v180, -s8, v170, v180
	v_fma_f32 v156, -s9, v144, v156
	s_nop 0
	s_nop 0
	v_readlane_b32 s6, v209, s49
	v_readlane_b32 s7, v205, s65
	v_readlane_b32 s8, v208, s65
	v_readlane_b32 s9, v207, s65
	v_fma_f32 v157, -s6, v166, v157
	v_fma_f32 v181, -s7, v142, v181
	v_fma_f32 v180, -s8, v158, v180
	v_fma_f32 v156, -s9, v140, v156
	s_nop 0
	s_nop 0
	v_readlane_b32 s6, v209, s65
	s_nop 1
	v_fma_f32 v157, -s6, v152, v157
	s_nop 0
	s_nop 0
	s_nop 0
	s_nop 0
	s_nop 0
	s_nop 0
	s_nop 0
	s_nop 0
	s_nop 0
	s_nop 0
	s_nop 0
	s_nop 0
	s_nop 0
	s_nop 0
	s_nop 0
	s_nop 0
	s_nop 1
	s_nop 0
	v_pk_add_f32 v[156:157], v[180:181], v[156:157]
	v_mov_b32_e32 v181, v123
	v_mov_b32_e32 v180, v123
	v_pk_add_f32 v[156:157], v[156:157], v[156:157] op_sel:[0,1] op_sel_hi:[1,0]
	s_nop 0
	s_waitcnt lgkmcnt(0)
	v_sub_f32_e32 v173, v173, v246
	ds_read_b32 v247, v249 offset:64
	s_nop 0
	v_readlane_b32 s6, v203, s48
	v_readlane_b32 s7, v206, s48
	v_readlane_b32 s8, v201, s21
	v_readlane_b32 s9, v204, s21
	v_fma_f32 v173, -s6, v156, v173
	v_fma_f32 v181, -s7, v176, v181
	v_fma_f32 v180, -s8, v150, v180
	v_fma_f32 v172, -s9, v178, v172
	v_mov_b32_e32 v157, v176
	s_nop 0
	v_readlane_b32 s6, v203, s21
	v_readlane_b32 s7, v206, s21
	v_readlane_b32 s8, v205, s48
	v_readlane_b32 s9, v208, s48
	v_fma_f32 v173, -s6, v148, v173
	v_fma_f32 v181, -s7, v174, v181
	v_fma_f32 v180, -s8, v146, v180
	v_fma_f32 v172, -s9, v170, v172
	s_nop 0
	s_nop 0
	v_readlane_b32 s6, v207, s48
	v_readlane_b32 s7, v209, s48
	v_readlane_b32 s8, v205, s21
	v_readlane_b32 s9, v208, s21
	v_fma_f32 v173, -s6, v144, v173
	v_fma_f32 v181, -s7, v166, v181
	v_fma_f32 v180, -s8, v142, v180
	v_fma_f32 v172, -s9, v158, v172
	s_nop 0
	s_nop 0
	v_readlane_b32 s6, v207, s21
	v_readlane_b32 s7, v209, s21
	s_nop 0
	v_fma_f32 v173, -s6, v140, v173
	v_fma_f32 v181, -s7, v152, v181
	s_nop 0
	s_nop 0
	s_nop 0
	s_nop 0
	s_nop 0
	s_nop 0
	s_nop 0
	s_nop 0
	s_nop 0
	s_nop 0
	s_nop 0
	s_nop 0
	s_nop 0
	s_nop 0
	s_nop 0
	s_nop 0
	s_nop 1
	s_nop 0
	s_nop 0
	s_nop 1
	s_nop 0
	v_pk_add_f32 v[172:173], v[180:181], v[172:173]
	v_mov_b32_e32 v181, v123
	v_mov_b32_e32 v180, v123
	v_pk_add_f32 v[172:173], v[172:173], v[172:173] op_sel:[0,1] op_sel_hi:[1,0]
	s_nop 0
	s_waitcnt lgkmcnt(0)
	v_sub_f32_e32 v165, v165, v247
	ds_read_b32 v246, v249 offset:60
	s_nop 0
	v_readlane_b32 s6, v204, s47
	v_readlane_b32 s7, v203, s47
	v_readlane_b32 s8, v206, s47
	v_readlane_b32 s9, v201, s34
	v_fma_f32 v165, -s6, v172, v165
	v_fma_f32 v181, -s7, v156, v181
	v_fma_f32 v180, -s8, v176, v180
	v_fma_f32 v164, -s9, v150, v164
	s_nop 0
	s_nop 0
	v_readlane_b32 s6, v204, s34
	v_readlane_b32 s7, v203, s34
	v_readlane_b32 s8, v206, s34
	v_readlane_b32 s9, v205, s47
	v_fma_f32 v165, -s6, v178, v165
	v_fma_f32 v181, -s7, v148, v181
	v_fma_f32 v180, -s8, v174, v180
	v_fma_f32 v164, -s9, v146, v164
	s_nop 0
	s_nop 0
	v_readlane_b32 s6, v208, s47
	v_readlane_b32 s7, v207, s47
	v_readlane_b32 s8, v209, s47
	v_readlane_b32 s9, v205, s34
	v_fma_f32 v165, -s6, v170, v165
	v_fma_f32 v181, -s7, v144, v181
	v_fma_f32 v180, -s8, v166, v180
	v_fma_f32 v164, -s9, v142, v164
	s_nop 0
	s_nop 0
	v_readlane_b32 s6, v208, s34
	v_readlane_b32 s7, v207, s34
	v_readlane_b32 s8, v209, s34
	v_fma_f32 v165, -s6, v158, v165
	v_fma_f32 v181, -s7, v140, v181
	v_fma_f32 v180, -s8, v152, v180
	s_nop 0
	s_nop 0
	s_nop 0
	s_nop 0
	s_nop 0
	s_nop 0
	s_nop 0
	s_nop 0
	s_nop 0
	s_nop 0
	s_nop 0
	s_nop 0
	s_nop 0
	s_nop 0
	s_nop 0
	s_nop 0
	s_nop 1
	s_nop 0
	s_nop 0
	s_nop 1
	s_nop 0
	s_nop 0
	s_nop 1
	s_nop 0
	v_pk_add_f32 v[164:165], v[180:181], v[164:165]
	v_mov_b32_e32 v181, v123
	v_mov_b32_e32 v180, v123
	v_pk_add_f32 v[164:165], v[164:165], v[164:165] op_sel:[0,1] op_sel_hi:[1,0]
	s_nop 0
	s_waitcnt lgkmcnt(0)
	v_sub_f32_e32 v169, v169, v246
	ds_read_b32 v247, v249 offset:56
	s_nop 0
	v_readlane_b32 s6, v201, s45
	v_readlane_b32 s7, v204, s45
	v_readlane_b32 s8, v203, s45
	v_readlane_b32 s9, v206, s45
	v_fma_f32 v169, -s6, v164, v169
	v_fma_f32 v181, -s7, v172, v181
	v_fma_f32 v180, -s8, v156, v180
	v_fma_f32 v168, -s9, v176, v168
	v_mov_b32_e32 v165, v172
	s_nop 0
	v_readlane_b32 s6, v201, s66
	v_readlane_b32 s7, v204, s66
	v_readlane_b32 s8, v203, s66
	v_readlane_b32 s9, v206, s66
	v_fma_f32 v169, -s6, v150, v169
	v_fma_f32 v181, -s7, v178, v181
	v_fma_f32 v180, -s8, v148, v180
	v_fma_f32 v168, -s9, v174, v168
	s_nop 0
	s_nop 0
	v_readlane_b32 s6, v205, s45
	v_readlane_b32 s7, v208, s45
	v_readlane_b32 s8, v207, s45
	v_readlane_b32 s9, v209, s45
	v_fma_f32 v169, -s6, v146, v169
	v_fma_f32 v181, -s7, v170, v181
	v_fma_f32 v180, -s8, v144, v180
	v_fma_f32 v168, -s9, v166, v168
	s_nop 0
	s_nop 0
	v_readlane_b32 s6, v205, s66
	v_readlane_b32 s7, v208, s66
	v_readlane_b32 s8, v207, s66
	v_readlane_b32 s9, v209, s66
	v_fma_f32 v169, -s6, v142, v169
	v_fma_f32 v181, -s7, v158, v181
	v_fma_f32 v180, -s8, v140, v180
	v_fma_f32 v168, -s9, v152, v168
	s_nop 0
	s_nop 0
	s_nop 0
	s_nop 0
	s_nop 0
	s_nop 0
	s_nop 0
	s_nop 0
	s_nop 0
	s_nop 0
	s_nop 0
	s_nop 0
	s_nop 0
	s_nop 0
	s_nop 0
	s_nop 0
	s_nop 0
	v_pk_add_f32 v[168:169], v[180:181], v[168:169]
	s_nop 0
	v_pk_add_f32 v[180:181], v[168:169], v[168:169] op_sel:[0,1] op_sel_hi:[1,0]
	v_mov_b32_e32 v169, v123
	v_mov_b32_e32 v168, v123
	s_waitcnt lgkmcnt(0)
	v_sub_f32_e32 v163, v163, v247
	ds_read_b32 v246, v249 offset:52
	s_nop 0
	v_readlane_b32 s6, v202, s14
	v_readlane_b32 s7, v201, s39
	v_readlane_b32 s8, v204, s39
	v_readlane_b32 s9, v203, s39
	v_fma_f32 v163, -s6, v180, v163
	v_fma_f32 v169, -s7, v164, v169
	v_fma_f32 v168, -s8, v172, v168
	v_fma_f32 v162, -s9, v156, v162
	s_nop 0
	s_nop 0
	v_readlane_b32 s6, v206, s39
	v_readlane_b32 s7, v201, s14
	v_readlane_b32 s8, v204, s14
	v_readlane_b32 s9, v203, s14
	v_fma_f32 v163, -s6, v176, v163
	v_fma_f32 v169, -s7, v150, v169
	v_fma_f32 v168, -s8, v178, v168
	v_fma_f32 v162, -s9, v148, v162
	s_nop 0
	s_nop 0
	v_readlane_b32 s6, v206, s14
	v_readlane_b32 s7, v205, s39
	v_readlane_b32 s8, v208, s39
	v_readlane_b32 s9, v207, s39
	v_fma_f32 v163, -s6, v174, v163
	v_fma_f32 v169, -s7, v146, v169
	v_fma_f32 v168, -s8, v170, v168
	v_fma_f32 v162, -s9, v144, v162
	s_nop 0
	s_nop 0
	v_readlane_b32 s6, v209, s39
	v_readlane_b32 s7, v205, s14
	v_readlane_b32 s8, v208, s14
	v_readlane_b32 s9, v207, s14
	v_fma_f32 v163, -s6, v166, v163
	v_fma_f32 v169, -s7, v142, v169
	v_fma_f32 v168, -s8, v158, v168
	v_fma_f32 v162, -s9, v140, v162
	s_nop 0
	s_nop 0
	v_readlane_b32 s6, v209, s14
	s_nop 1
	v_fma_f32 v163, -s6, v152, v163
	s_nop 0
	s_nop 0
	s_nop 0
	s_nop 0
	s_nop 0
	s_nop 0
	s_nop 0
	s_nop 0
	s_nop 0
	s_nop 0
	s_nop 0
	s_nop 0
	s_nop 0
	s_nop 0
	s_nop 0
	s_nop 0
	s_nop 1
	s_nop 0
	v_pk_add_f32 v[162:163], v[168:169], v[162:163]
	v_mov_b32_e32 v169, v123
	v_mov_b32_e32 v168, v123
	v_pk_add_f32 v[162:163], v[162:163], v[162:163] op_sel:[0,1] op_sel_hi:[1,0]
	s_nop 0
	s_waitcnt lgkmcnt(0)
	v_sub_f32_e32 v161, v161, v246
	ds_read_b32 v247, v249 offset:48
	s_nop 0
	v_readlane_b32 s6, v199, s11
	v_readlane_b32 s7, v202, s11
	v_readlane_b32 s8, v201, s38
	v_readlane_b32 s9, v204, s38
	v_fma_f32 v161, -s6, v162, v161
	v_fma_f32 v169, -s7, v180, v169
	v_fma_f32 v168, -s8, v164, v168
	v_fma_f32 v160, -s9, v172, v160
	v_mov_b32_e32 v163, v180
	s_nop 0
	v_readlane_b32 s6, v203, s38
	v_readlane_b32 s7, v206, s38
	v_readlane_b32 s8, v201, s11
	v_readlane_b32 s9, v204, s11
	v_fma_f32 v161, -s6, v156, v161
	v_fma_f32 v169, -s7, v176, v169
	v_fma_f32 v168, -s8, v150, v168
	v_fma_f32 v160, -s9, v178, v160
	s_nop 0
	s_nop 0
	v_readlane_b32 s6, v203, s11
	v_readlane_b32 s7, v206, s11
	v_readlane_b32 s8, v205, s38
	v_readlane_b32 s9, v208, s38
	v_fma_f32 v161, -s6, v148, v161
	v_fma_f32 v169, -s7, v174, v169
	v_fma_f32 v168, -s8, v146, v168
	v_fma_f32 v160, -s9, v170, v160
	s_nop 0
	s_nop 0
	v_readlane_b32 s6, v207, s38
	v_readlane_b32 s7, v209, s38
	v_readlane_b32 s8, v205, s11
	v_readlane_b32 s9, v208, s11
	v_fma_f32 v161, -s6, v144, v161
	v_fma_f32 v169, -s7, v166, v169
	v_fma_f32 v168, -s8, v142, v168
	v_fma_f32 v160, -s9, v158, v160
	s_nop 0
	s_nop 0
	v_readlane_b32 s6, v207, s11
	v_readlane_b32 s7, v209, s11
	s_nop 0
	v_fma_f32 v161, -s6, v140, v161
	v_fma_f32 v169, -s7, v152, v169
	s_nop 0
	s_nop 0
	s_nop 0
	s_nop 0
	s_nop 0
	s_nop 0
	s_nop 0
	s_nop 0
	s_nop 0
	s_nop 0
	s_nop 0
	s_nop 0
	s_nop 0
	s_nop 0
	s_nop 0
	s_nop 0
	s_nop 1
	s_nop 0
	s_nop 0
	s_nop 1
	s_nop 0
	v_pk_add_f32 v[160:161], v[168:169], v[160:161]
	s_nop 0
	v_pk_add_f32 v[184:185], v[160:161], v[160:161] op_sel:[0,1] op_sel_hi:[1,0]
	v_mov_b32_e32 v161, v123
	v_mov_b32_e32 v160, v123
	s_waitcnt lgkmcnt(0)
	v_sub_f32_e32 v155, v155, v247
	ds_read_b32 v246, v249 offset:44
	s_nop 0
	v_readlane_b32 s6, v200, s27
	v_readlane_b32 s7, v199, s27
	v_readlane_b32 s8, v202, s27
	v_readlane_b32 s9, v201, s43
	v_fma_f32 v155, -s6, v184, v155
	v_fma_f32 v161, -s7, v162, v161
	v_fma_f32 v160, -s8, v180, v160
	v_fma_f32 v154, -s9, v164, v154
	s_nop 0
	s_nop 0
	v_readlane_b32 s6, v204, s43
	v_readlane_b32 s7, v203, s43
	v_readlane_b32 s8, v206, s43
	v_readlane_b32 s9, v201, s27
	v_fma_f32 v155, -s6, v172, v155
	v_fma_f32 v161, -s7, v156, v161
	v_fma_f32 v160, -s8, v176, v160
	v_fma_f32 v154, -s9, v150, v154
	s_nop 0
	s_nop 0
	v_readlane_b32 s6, v204, s27
	v_readlane_b32 s7, v203, s27
	v_readlane_b32 s8, v206, s27
	v_readlane_b32 s9, v205, s43
	v_fma_f32 v155, -s6, v178, v155
	v_fma_f32 v161, -s7, v148, v161
	v_fma_f32 v160, -s8, v174, v160
	v_fma_f32 v154, -s9, v146, v154
	s_nop 0
	s_nop 0
	v_readlane_b32 s6, v208, s43
	v_readlane_b32 s7, v207, s43
	v_readlane_b32 s8, v209, s43
	v_readlane_b32 s9, v205, s27
	v_fma_f32 v155, -s6, v170, v155
	v_fma_f32 v161, -s7, v144, v161
	v_fma_f32 v160, -s8, v166, v160
	v_fma_f32 v154, -s9, v142, v154
	s_nop 0
	s_nop 0
	v_readlane_b32 s6, v208, s27
	v_readlane_b32 s7, v207, s27
	v_readlane_b32 s8, v209, s27
	v_fma_f32 v155, -s6, v158, v155
	v_fma_f32 v161, -s7, v140, v161
	v_fma_f32 v160, -s8, v152, v160
	s_nop 0
	s_nop 0
	s_nop 0
	s_nop 0
	s_nop 0
	s_nop 0
	s_nop 0
	s_nop 0
	s_nop 0
	s_nop 0
	s_nop 0
	s_nop 0
	s_nop 0
	s_nop 0
	s_nop 0
	s_nop 0
	s_nop 1
	s_nop 0
	s_nop 0
	s_nop 1
	s_nop 0
	s_nop 0
	s_nop 1
	s_nop 0
	v_pk_add_f32 v[154:155], v[160:161], v[154:155]
	v_mov_b32_e32 v161, v123
	v_mov_b32_e32 v160, v123
	v_pk_add_f32 v[154:155], v[154:155], v[154:155] op_sel:[0,1] op_sel_hi:[1,0]
	s_nop 0
	s_waitcnt lgkmcnt(0)
	v_sub_f32_e32 v85, v85, v246
	ds_read_b32 v247, v249 offset:40
	s_nop 0
	v_readlane_b32 s6, v197, s67
	v_readlane_b32 s7, v200, s67
	v_readlane_b32 s8, v199, s67
	v_readlane_b32 s9, v202, s67
	v_fma_f32 v85, -s6, v154, v85
	v_fma_f32 v161, -s7, v184, v161
	v_fma_f32 v160, -s8, v162, v160
	v_fma_f32 v84, -s9, v180, v84
	v_mov_b32_e32 v155, v184
	s_nop 0
	v_readlane_b32 s6, v201, s42
	v_readlane_b32 s7, v204, s42
	v_readlane_b32 s8, v203, s42
	v_readlane_b32 s9, v206, s42
	v_fma_f32 v85, -s6, v164, v85
	v_fma_f32 v161, -s7, v172, v161
	v_fma_f32 v160, -s8, v156, v160
	v_fma_f32 v84, -s9, v176, v84
	s_nop 0
	s_nop 0
	v_readlane_b32 s6, v201, s67
	v_readlane_b32 s7, v204, s67
	v_readlane_b32 s8, v203, s67
	v_readlane_b32 s9, v206, s67
	v_fma_f32 v85, -s6, v150, v85
	v_fma_f32 v161, -s7, v178, v161
	v_fma_f32 v160, -s8, v148, v160
	v_fma_f32 v84, -s9, v174, v84
	s_nop 0
	s_nop 0
	v_readlane_b32 s6, v205, s42
	v_readlane_b32 s7, v208, s42
	v_readlane_b32 s8, v207, s42
	v_readlane_b32 s9, v209, s42
	v_fma_f32 v85, -s6, v146, v85
	v_fma_f32 v161, -s7, v170, v161
	v_fma_f32 v160, -s8, v144, v160
	v_fma_f32 v84, -s9, v166, v84
	s_nop 0
	s_nop 0
	v_readlane_b32 s6, v205, s67
	v_readlane_b32 s7, v208, s67
	v_readlane_b32 s8, v207, s67
	v_readlane_b32 s9, v209, s67
	v_fma_f32 v85, -s6, v142, v85
	v_fma_f32 v161, -s7, v158, v161
	v_fma_f32 v160, -s8, v140, v160
	v_fma_f32 v84, -s9, v152, v84
	s_nop 0
	s_nop 0
	s_nop 0
	s_nop 0
	s_nop 0
	s_nop 0
	s_nop 0
	s_nop 0
	s_nop 0
	s_nop 0
	s_nop 0
	s_nop 0
	s_nop 0
	s_nop 0
	s_nop 0
	s_nop 0
	s_nop 0
	v_pk_add_f32 v[84:85], v[160:161], v[84:85]
	v_mov_b32_e32 v161, v123
	v_mov_b32_e32 v160, v123
	v_pk_add_f32 v[84:85], v[84:85], v[84:85] op_sel:[0,1] op_sel_hi:[1,0]
	s_nop 0
	s_waitcnt lgkmcnt(0)
	v_sub_f32_e32 v83, v83, v247
	ds_read_b32 v246, v249 offset:36
	s_nop 0
	v_readlane_b32 s6, v202, s46
	v_readlane_b32 s7, v197, s2
	v_readlane_b32 s8, v200, s2
	v_readlane_b32 s9, v199, s2
	v_fma_f32 v83, -s6, v84, v83
	v_fma_f32 v161, -s7, v154, v161
	v_fma_f32 v160, -s8, v184, v160
	v_fma_f32 v82, -s9, v162, v82
	s_nop 0
	s_nop 0
	v_readlane_b32 s6, v202, s2
	v_readlane_b32 s7, v201, s46
	v_readlane_b32 s8, v204, s46
	v_readlane_b32 s9, v203, s46
	v_fma_f32 v83, -s6, v180, v83
	v_fma_f32 v161, -s7, v164, v161
	v_fma_f32 v160, -s8, v172, v160
	v_fma_f32 v82, -s9, v156, v82
	s_nop 0
	s_nop 0
	v_readlane_b32 s6, v206, s46
	v_readlane_b32 s7, v201, s2
	v_readlane_b32 s8, v204, s2
	v_readlane_b32 s9, v203, s2
	v_fma_f32 v83, -s6, v176, v83
	v_fma_f32 v161, -s7, v150, v161
	v_fma_f32 v160, -s8, v178, v160
	v_fma_f32 v82, -s9, v148, v82
	s_nop 0
	s_nop 0
	v_readlane_b32 s6, v206, s2
	v_readlane_b32 s7, v205, s46
	v_readlane_b32 s8, v208, s46
	v_readlane_b32 s9, v207, s46
	v_fma_f32 v83, -s6, v174, v83
	v_fma_f32 v161, -s7, v146, v161
	v_fma_f32 v160, -s8, v170, v160
	v_fma_f32 v82, -s9, v144, v82
	s_nop 0
	s_nop 0
	v_readlane_b32 s6, v209, s46
	v_readlane_b32 s7, v205, s2
	v_readlane_b32 s8, v208, s2
	v_readlane_b32 s9, v207, s2
	v_fma_f32 v83, -s6, v166, v83
	v_fma_f32 v161, -s7, v142, v161
	v_fma_f32 v160, -s8, v158, v160
	v_fma_f32 v82, -s9, v140, v82
	s_nop 0
	s_nop 0
	v_readlane_b32 s6, v209, s2
	s_nop 1
	v_fma_f32 v83, -s6, v152, v83
	s_nop 0
	s_nop 0
	s_nop 0
	s_nop 0
	s_nop 0
	s_nop 0
	s_nop 0
	s_nop 0
	s_nop 0
	s_nop 0
	s_nop 0
	s_nop 0
	s_nop 0
	s_nop 0
	s_nop 0
	s_nop 0
	s_nop 1
	s_nop 0
	v_pk_add_f32 v[82:83], v[160:161], v[82:83]
	s_nop 0
	v_pk_add_f32 v[160:161], v[82:83], v[82:83] op_sel:[0,1] op_sel_hi:[1,0]
	v_mov_b32_e32 v83, v123
	v_mov_b32_e32 v82, v123
	s_waitcnt lgkmcnt(0)
	v_sub_f32_e32 v79, v79, v246
	ds_read_b32 v247, v249 offset:32
	s_nop 0
	v_readlane_b32 s6, v199, s37
	v_readlane_b32 s7, v202, s37
	v_readlane_b32 s8, v197, s18
	v_readlane_b32 s9, v200, s18
	v_fma_f32 v79, -s6, v160, v79
	v_fma_f32 v83, -s7, v84, v83
	v_fma_f32 v82, -s8, v154, v82
	v_fma_f32 v78, -s9, v184, v78
	v_mov_b32_e32 v161, v84
	s_nop 0
	v_readlane_b32 s6, v199, s18
	v_readlane_b32 s7, v202, s18
	v_readlane_b32 s8, v201, s37
	v_readlane_b32 s9, v204, s37
	v_fma_f32 v79, -s6, v162, v79
	v_fma_f32 v83, -s7, v180, v83
	v_fma_f32 v82, -s8, v164, v82
	v_fma_f32 v78, -s9, v172, v78
	s_nop 0
	s_nop 0
	v_readlane_b32 s6, v203, s37
	v_readlane_b32 s7, v206, s37
	v_readlane_b32 s8, v201, s18
	v_readlane_b32 s9, v204, s18
	v_fma_f32 v79, -s6, v156, v79
	v_fma_f32 v83, -s7, v176, v83
	v_fma_f32 v82, -s8, v150, v82
	v_fma_f32 v78, -s9, v178, v78
	s_nop 0
	s_nop 0
	v_readlane_b32 s6, v203, s18
	v_readlane_b32 s7, v206, s18
	v_readlane_b32 s8, v205, s37
	v_readlane_b32 s9, v208, s37
	v_fma_f32 v79, -s6, v148, v79
	v_fma_f32 v83, -s7, v174, v83
	v_fma_f32 v82, -s8, v146, v82
	v_fma_f32 v78, -s9, v170, v78
	s_nop 0
	s_nop 0
	v_readlane_b32 s6, v207, s37
	v_readlane_b32 s7, v209, s37
	v_readlane_b32 s8, v205, s18
	v_readlane_b32 s9, v208, s18
	v_fma_f32 v79, -s6, v144, v79
	v_fma_f32 v83, -s7, v166, v83
	v_fma_f32 v82, -s8, v142, v82
	v_fma_f32 v78, -s9, v158, v78
	s_nop 0
	s_nop 0
	v_readlane_b32 s6, v207, s18
	v_readlane_b32 s7, v209, s18
	s_nop 0
	v_fma_f32 v79, -s6, v140, v79
	v_fma_f32 v83, -s7, v152, v83
	s_nop 0
	s_nop 0
	s_nop 0
	s_nop 0
	s_nop 0
	s_nop 0
	s_nop 0
	s_nop 0
	s_nop 0
	s_nop 0
	s_nop 0
	s_nop 0
	s_nop 0
	s_nop 0
	s_nop 0
	s_nop 0
	s_nop 1
	s_nop 0
	s_nop 0
	s_nop 1
	s_nop 0
	v_pk_add_f32 v[78:79], v[82:83], v[78:79]
	v_mov_b32_e32 v83, v123
	v_mov_b32_e32 v82, v123
	v_pk_add_f32 v[78:79], v[78:79], v[78:79] op_sel:[0,1] op_sel_hi:[1,0]
	s_nop 0
	s_waitcnt lgkmcnt(0)
	v_sub_f32_e32 v75, v75, v247
	ds_read_b32 v246, v249 offset:28
	s_nop 0
	v_readlane_b32 s6, v200, s40
	v_readlane_b32 s7, v199, s40
	v_readlane_b32 s8, v202, s40
	v_readlane_b32 s9, v197, s19
	v_fma_f32 v75, -s6, v78, v75
	v_fma_f32 v83, -s7, v160, v83
	v_fma_f32 v82, -s8, v84, v82
	v_fma_f32 v74, -s9, v154, v74
	s_nop 0
	s_nop 0
	v_readlane_b32 s6, v200, s19
	v_readlane_b32 s7, v199, s19
	v_readlane_b32 s8, v202, s19
	v_readlane_b32 s9, v201, s40
	v_fma_f32 v75, -s6, v184, v75
	v_fma_f32 v83, -s7, v162, v83
	v_fma_f32 v82, -s8, v180, v82
	v_fma_f32 v74, -s9, v164, v74
	s_nop 0
	s_nop 0
	v_readlane_b32 s6, v204, s40
	v_readlane_b32 s7, v203, s40
	v_readlane_b32 s8, v206, s40
	v_readlane_b32 s9, v201, s19
	v_fma_f32 v75, -s6, v172, v75
	v_fma_f32 v83, -s7, v156, v83
	v_fma_f32 v82, -s8, v176, v82
	v_fma_f32 v74, -s9, v150, v74
	s_nop 0
	s_nop 0
	v_readlane_b32 s6, v204, s19
	v_readlane_b32 s7, v203, s19
	v_readlane_b32 s8, v206, s19
	v_readlane_b32 s9, v205, s40
	v_fma_f32 v75, -s6, v178, v75
	v_fma_f32 v83, -s7, v148, v83
	v_fma_f32 v82, -s8, v174, v82
	v_fma_f32 v74, -s9, v146, v74
	s_nop 0
	s_nop 0
	v_readlane_b32 s6, v208, s40
	v_readlane_b32 s7, v207, s40
	v_readlane_b32 s8, v209, s40
	v_readlane_b32 s9, v205, s19
	v_fma_f32 v75, -s6, v170, v75
	v_fma_f32 v83, -s7, v144, v83
	v_fma_f32 v82, -s8, v166, v82
	v_fma_f32 v74, -s9, v142, v74
	s_nop 0
	s_nop 0
	v_readlane_b32 s6, v208, s19
	v_readlane_b32 s7, v207, s19
	v_readlane_b32 s8, v209, s19
	v_fma_f32 v75, -s6, v158, v75
	v_fma_f32 v83, -s7, v140, v83
	v_fma_f32 v82, -s8, v152, v82
	s_nop 0
	s_nop 0
	s_nop 0
	s_nop 0
	s_nop 0
	s_nop 0
	s_nop 0
	s_nop 0
	s_nop 0
	s_nop 0
	s_nop 0
	s_nop 0
	s_nop 0
	s_nop 0
	s_nop 0
	s_nop 0
	s_nop 1
	s_nop 0
	s_nop 0
	s_nop 1
	s_nop 0
	s_nop 0
	s_nop 1
	s_nop 0
	v_pk_add_f32 v[74:75], v[82:83], v[74:75]
	s_nop 0
	v_pk_add_f32 v[168:169], v[74:75], v[74:75] op_sel:[0,1] op_sel_hi:[1,0]
	v_mov_b32_e32 v75, v123
	v_mov_b32_e32 v74, v123
	s_waitcnt lgkmcnt(0)
	v_sub_f32_e32 v71, v71, v246
	ds_read_b32 v247, v249 offset:24
	s_nop 0
	v_readlane_b32 s6, v197, s44
	v_readlane_b32 s7, v200, s44
	v_readlane_b32 s8, v199, s44
	v_readlane_b32 s9, v202, s44
	v_fma_f32 v71, -s6, v168, v71
	v_fma_f32 v75, -s7, v78, v75
	v_fma_f32 v74, -s8, v160, v74
	v_fma_f32 v70, -s9, v84, v70
	v_mov_b32_e32 v169, v78
	s_nop 0
	v_readlane_b32 s6, v197, s68
	v_readlane_b32 s7, v200, s68
	v_readlane_b32 s8, v199, s68
	v_readlane_b32 s9, v202, s68
	v_fma_f32 v71, -s6, v154, v71
	v_fma_f32 v75, -s7, v184, v75
	v_fma_f32 v74, -s8, v162, v74
	v_fma_f32 v70, -s9, v180, v70
	s_nop 0
	s_nop 0
	v_readlane_b32 s6, v201, s44
	v_readlane_b32 s7, v204, s44
	v_readlane_b32 s8, v203, s44
	v_readlane_b32 s9, v206, s44
	v_fma_f32 v71, -s6, v164, v71
	v_fma_f32 v75, -s7, v172, v75
	v_fma_f32 v74, -s8, v156, v74
	v_fma_f32 v70, -s9, v176, v70
	s_nop 0
	s_nop 0
	v_readlane_b32 s6, v201, s68
	v_readlane_b32 s7, v204, s68
	v_readlane_b32 s8, v203, s68
	v_readlane_b32 s9, v206, s68
	v_fma_f32 v71, -s6, v150, v71
	v_fma_f32 v75, -s7, v178, v75
	v_fma_f32 v74, -s8, v148, v74
	v_fma_f32 v70, -s9, v174, v70
	s_nop 0
	s_nop 0
	v_readlane_b32 s6, v205, s44
	v_readlane_b32 s7, v208, s44
	v_readlane_b32 s8, v207, s44
	v_readlane_b32 s9, v209, s44
	v_fma_f32 v71, -s6, v146, v71
	v_fma_f32 v75, -s7, v170, v75
	v_fma_f32 v74, -s8, v144, v74
	v_fma_f32 v70, -s9, v166, v70
	s_nop 0
	s_nop 0
	v_readlane_b32 s6, v205, s68
	v_readlane_b32 s7, v208, s68
	v_readlane_b32 s8, v207, s68
	v_readlane_b32 s9, v209, s68
	v_fma_f32 v71, -s6, v142, v71
	v_fma_f32 v75, -s7, v158, v75
	v_fma_f32 v74, -s8, v140, v74
	v_fma_f32 v70, -s9, v152, v70
	s_nop 0
	s_nop 0
	s_nop 0
	s_nop 0
	s_nop 0
	s_nop 0
	s_nop 0
	s_nop 0
	s_nop 0
	s_nop 0
	s_nop 0
	s_nop 0
	s_nop 0
	s_nop 0
	s_nop 0
	s_nop 0
	s_nop 0
	v_pk_add_f32 v[70:71], v[74:75], v[70:71]
	v_mov_b32_e32 v75, v123
	v_mov_b32_e32 v74, v123
	v_pk_add_f32 v[70:71], v[70:71], v[70:71] op_sel:[0,1] op_sel_hi:[1,0]
	s_nop 0
	s_waitcnt lgkmcnt(0)
	v_sub_f32_e32 v67, v67, v247
	ds_read_b32 v246, v249 offset:20
	s_nop 0
	v_readlane_b32 s6, v198, s3
	v_readlane_b32 s7, v197, s35
	v_readlane_b32 s8, v200, s35
	v_readlane_b32 s9, v199, s35
	v_fma_f32 v67, -s6, v70, v67
	v_fma_f32 v75, -s7, v168, v75
	v_fma_f32 v74, -s8, v78, v74
	v_fma_f32 v66, -s9, v160, v66
	s_nop 0
	s_nop 0
	v_readlane_b32 s6, v202, s35
	v_readlane_b32 s7, v197, s3
	v_readlane_b32 s8, v200, s3
	v_readlane_b32 s9, v199, s3
	v_fma_f32 v67, -s6, v84, v67
	v_fma_f32 v75, -s7, v154, v75
	v_fma_f32 v74, -s8, v184, v74
	v_fma_f32 v66, -s9, v162, v66
	s_nop 0
	s_nop 0
	v_readlane_b32 s6, v202, s3
	v_readlane_b32 s7, v201, s35
	v_readlane_b32 s8, v204, s35
	v_readlane_b32 s9, v203, s35
	v_fma_f32 v67, -s6, v180, v67
	v_fma_f32 v75, -s7, v164, v75
	v_fma_f32 v74, -s8, v172, v74
	v_fma_f32 v66, -s9, v156, v66
	s_nop 0
	s_nop 0
	v_readlane_b32 s6, v206, s35
	v_readlane_b32 s7, v201, s3
	v_readlane_b32 s8, v204, s3
	v_readlane_b32 s9, v203, s3
	v_fma_f32 v67, -s6, v176, v67
	v_fma_f32 v75, -s7, v150, v75
	v_fma_f32 v74, -s8, v178, v74
	v_fma_f32 v66, -s9, v148, v66
	s_nop 0
	s_nop 0
	v_readlane_b32 s6, v206, s3
	v_readlane_b32 s7, v205, s35
	v_readlane_b32 s8, v208, s35
	v_readlane_b32 s9, v207, s35
	v_fma_f32 v67, -s6, v174, v67
	v_fma_f32 v75, -s7, v146, v75
	v_fma_f32 v74, -s8, v170, v74
	v_fma_f32 v66, -s9, v144, v66
	s_nop 0
	s_nop 0
	v_readlane_b32 s6, v209, s35
	v_readlane_b32 s7, v205, s3
	v_readlane_b32 s8, v208, s3
	v_readlane_b32 s9, v207, s3
	v_fma_f32 v67, -s6, v166, v67
	v_fma_f32 v75, -s7, v142, v75
	v_fma_f32 v74, -s8, v158, v74
	v_fma_f32 v66, -s9, v140, v66
	s_nop 0
	s_nop 0
	v_readlane_b32 s6, v209, s3
	s_nop 1
	v_fma_f32 v67, -s6, v152, v67
	s_nop 0
	s_nop 0
	s_nop 0
	s_nop 0
	s_nop 0
	s_nop 0
	s_nop 0
	s_nop 0
	s_nop 0
	s_nop 0
	s_nop 0
	s_nop 0
	s_nop 0
	s_nop 0
	s_nop 0
	s_nop 0
	s_nop 1
	s_nop 0
	v_pk_add_f32 v[66:67], v[74:75], v[66:67]
	s_nop 0
	v_pk_add_f32 v[182:183], v[66:67], v[66:67] op_sel:[0,1] op_sel_hi:[1,0]
	v_mov_b32_e32 v67, v123
	v_mov_b32_e32 v66, v123
	s_waitcnt lgkmcnt(0)
	v_sub_f32_e32 v63, v63, v246
	ds_read_b32 v247, v249 offset:16
	s_nop 0
	v_readlane_b32 s6, v195, s16
	v_readlane_b32 s7, v198, s16
	v_readlane_b32 s8, v197, s30
	v_readlane_b32 s9, v200, s30
	v_fma_f32 v63, -s6, v182, v63
	v_fma_f32 v67, -s7, v70, v67
	v_fma_f32 v66, -s8, v168, v66
	v_fma_f32 v62, -s9, v78, v62
	v_mov_b32_e32 v183, v70
	s_nop 0
	v_readlane_b32 s6, v199, s30
	v_readlane_b32 s7, v202, s30
	v_readlane_b32 s8, v197, s16
	v_readlane_b32 s9, v200, s16
	v_fma_f32 v63, -s6, v160, v63
	v_fma_f32 v67, -s7, v84, v67
	v_fma_f32 v66, -s8, v154, v66
	v_fma_f32 v62, -s9, v184, v62
	s_nop 0
	s_nop 0
	v_readlane_b32 s6, v199, s16
	v_readlane_b32 s7, v202, s16
	v_readlane_b32 s8, v201, s30
	v_readlane_b32 s9, v204, s30
	v_fma_f32 v63, -s6, v162, v63
	v_fma_f32 v67, -s7, v180, v67
	v_fma_f32 v66, -s8, v164, v66
	v_fma_f32 v62, -s9, v172, v62
	s_nop 0
	s_nop 0
	v_readlane_b32 s6, v203, s30
	v_readlane_b32 s7, v206, s30
	v_readlane_b32 s8, v201, s16
	v_readlane_b32 s9, v204, s16
	v_fma_f32 v63, -s6, v156, v63
	v_fma_f32 v67, -s7, v176, v67
	v_fma_f32 v66, -s8, v150, v66
	v_fma_f32 v62, -s9, v178, v62
	s_nop 0
	s_nop 0
	v_readlane_b32 s6, v203, s16
	v_readlane_b32 s7, v206, s16
	v_readlane_b32 s8, v205, s30
	v_readlane_b32 s9, v208, s30
	v_fma_f32 v63, -s6, v148, v63
	v_fma_f32 v67, -s7, v174, v67
	v_fma_f32 v66, -s8, v146, v66
	v_fma_f32 v62, -s9, v170, v62
	s_nop 0
	s_nop 0
	v_readlane_b32 s6, v207, s30
	v_readlane_b32 s7, v209, s30
	v_readlane_b32 s8, v205, s16
	v_readlane_b32 s9, v208, s16
	v_fma_f32 v63, -s6, v144, v63
	v_fma_f32 v67, -s7, v166, v67
	v_fma_f32 v66, -s8, v142, v66
	v_fma_f32 v62, -s9, v158, v62
	s_nop 0
	s_nop 0
	v_readlane_b32 s6, v207, s16
	v_readlane_b32 s7, v209, s16
	s_nop 0
	v_fma_f32 v63, -s6, v140, v63
	v_fma_f32 v67, -s7, v152, v67
	s_nop 0
	s_nop 0
	s_nop 0
	s_nop 0
	s_nop 0
	s_nop 0
	s_nop 0
	s_nop 0
	s_nop 0
	s_nop 0
	s_nop 0
	s_nop 0
	s_nop 0
	s_nop 0
	s_nop 0
	s_nop 0
	s_nop 1
	s_nop 0
	s_nop 0
	s_nop 1
	s_nop 0
	v_pk_add_f32 v[62:63], v[66:67], v[62:63]
	v_mov_b32_e32 v67, v123
	v_mov_b32_e32 v66, v123
	v_pk_add_f32 v[62:63], v[62:63], v[62:63] op_sel:[0,1] op_sel_hi:[1,0]
	s_nop 0
	s_waitcnt lgkmcnt(0)
	v_sub_f32_e32 v29, v29, v247
	ds_read_b32 v246, v249 offset:12
	s_nop 0
	v_readlane_b32 s6, v196, s17
	v_readlane_b32 s7, v195, s17
	v_readlane_b32 s8, v198, s17
	v_readlane_b32 s9, v197, s36
	v_fma_f32 v29, -s6, v62, v29
	v_fma_f32 v67, -s7, v182, v67
	v_fma_f32 v66, -s8, v70, v66
	v_fma_f32 v28, -s9, v168, v28
	s_nop 0
	s_nop 0
	v_readlane_b32 s6, v200, s36
	v_readlane_b32 s7, v199, s36
	v_readlane_b32 s8, v202, s36
	v_readlane_b32 s9, v197, s17
	v_fma_f32 v29, -s6, v78, v29
	v_fma_f32 v67, -s7, v160, v67
	v_fma_f32 v66, -s8, v84, v66
	v_fma_f32 v28, -s9, v154, v28
	s_nop 0
	s_nop 0
	v_readlane_b32 s6, v200, s17
	v_readlane_b32 s7, v199, s17
	v_readlane_b32 s8, v202, s17
	v_readlane_b32 s9, v201, s36
	v_fma_f32 v29, -s6, v184, v29
	v_fma_f32 v67, -s7, v162, v67
	v_fma_f32 v66, -s8, v180, v66
	v_fma_f32 v28, -s9, v164, v28
	s_nop 0
	s_nop 0
	v_readlane_b32 s6, v204, s36
	v_readlane_b32 s7, v203, s36
	v_readlane_b32 s8, v206, s36
	v_readlane_b32 s9, v201, s17
	v_fma_f32 v29, -s6, v172, v29
	v_fma_f32 v67, -s7, v156, v67
	v_fma_f32 v66, -s8, v176, v66
	v_fma_f32 v28, -s9, v150, v28
	s_nop 0
	s_nop 0
	v_readlane_b32 s6, v204, s17
	v_readlane_b32 s7, v203, s17
	v_readlane_b32 s8, v206, s17
	v_readlane_b32 s9, v205, s36
	v_fma_f32 v29, -s6, v178, v29
	v_fma_f32 v67, -s7, v148, v67
	v_fma_f32 v66, -s8, v174, v66
	v_fma_f32 v28, -s9, v146, v28
	s_nop 0
	s_nop 0
	v_readlane_b32 s6, v208, s36
	v_readlane_b32 s7, v207, s36
	v_readlane_b32 s8, v209, s36
	v_readlane_b32 s9, v205, s17
	v_fma_f32 v29, -s6, v170, v29
	v_fma_f32 v67, -s7, v144, v67
	v_fma_f32 v66, -s8, v166, v66
	v_fma_f32 v28, -s9, v142, v28
	s_nop 0
	s_nop 0
	v_readlane_b32 s6, v208, s17
	v_readlane_b32 s7, v207, s17
	v_readlane_b32 s8, v209, s17
	v_fma_f32 v29, -s6, v158, v29
	v_fma_f32 v67, -s7, v140, v67
	v_fma_f32 v66, -s8, v152, v66
	s_nop 0
	s_nop 0
	s_nop 0
	s_nop 0
	s_nop 0
	s_nop 0
	s_nop 0
	s_nop 0
	s_nop 0
	s_nop 0
	s_nop 0
	s_nop 0
	s_nop 0
	s_nop 0
	s_nop 0
	s_nop 0
	s_nop 1
	s_nop 0
	s_nop 0
	s_nop 1
	s_nop 0
	s_nop 0
	s_nop 1
	s_nop 0
	v_pk_add_f32 v[28:29], v[66:67], v[28:29]
	s_nop 0
	v_pk_add_f32 v[186:187], v[28:29], v[28:29] op_sel:[0,1] op_sel_hi:[1,0]
	v_mov_b32_e32 v29, v123
	v_mov_b32_e32 v28, v123
	s_waitcnt lgkmcnt(0)
	v_sub_f32_e32 v25, v25, v246
	ds_read_b32 v247, v249 offset:8
	s_nop 0
	v_readlane_b32 s6, v194, s69
	v_readlane_b32 s7, v196, s69
	v_readlane_b32 s8, v195, s69
	v_readlane_b32 s9, v198, s69
	v_fma_f32 v25, -s6, v186, v25
	v_fma_f32 v29, -s7, v62, v29
	v_fma_f32 v28, -s8, v182, v28
	v_fma_f32 v24, -s9, v70, v24
	v_mov_b32_e32 v187, v62
	s_nop 0
	v_readlane_b32 s6, v197, s12
	v_readlane_b32 s7, v200, s12
	v_readlane_b32 s8, v199, s12
	v_readlane_b32 s9, v202, s12
	v_fma_f32 v25, -s6, v168, v25
	v_fma_f32 v29, -s7, v78, v29
	v_fma_f32 v28, -s8, v160, v28
	v_fma_f32 v24, -s9, v84, v24
	s_nop 0
	s_nop 0
	v_readlane_b32 s6, v197, s69
	v_readlane_b32 s7, v200, s69
	v_readlane_b32 s8, v199, s69
	v_readlane_b32 s9, v202, s69
	v_fma_f32 v25, -s6, v154, v25
	v_fma_f32 v29, -s7, v184, v29
	v_fma_f32 v28, -s8, v162, v28
	v_fma_f32 v24, -s9, v180, v24
	s_nop 0
	s_nop 0
	v_readlane_b32 s6, v201, s12
	v_readlane_b32 s7, v204, s12
	v_readlane_b32 s8, v203, s12
	v_readlane_b32 s9, v206, s12
	v_fma_f32 v25, -s6, v164, v25
	v_fma_f32 v29, -s7, v172, v29
	v_fma_f32 v28, -s8, v156, v28
	v_fma_f32 v24, -s9, v176, v24
	s_nop 0
	s_nop 0
	v_readlane_b32 s6, v201, s69
	v_readlane_b32 s7, v204, s69
	v_readlane_b32 s8, v203, s69
	v_readlane_b32 s9, v206, s69
	v_fma_f32 v25, -s6, v150, v25
	v_fma_f32 v29, -s7, v178, v29
	v_fma_f32 v28, -s8, v148, v28
	v_fma_f32 v24, -s9, v174, v24
	s_nop 0
	s_nop 0
	v_readlane_b32 s6, v205, s12
	v_readlane_b32 s7, v208, s12
	v_readlane_b32 s8, v207, s12
	v_readlane_b32 s9, v209, s12
	v_fma_f32 v25, -s6, v146, v25
	v_fma_f32 v29, -s7, v170, v29
	v_fma_f32 v28, -s8, v144, v28
	v_fma_f32 v24, -s9, v166, v24
	s_nop 0
	s_nop 0
	v_readlane_b32 s6, v205, s69
	v_readlane_b32 s7, v208, s69
	v_readlane_b32 s8, v207, s69
	v_readlane_b32 s9, v209, s69
	v_fma_f32 v25, -s6, v142, v25
	v_fma_f32 v29, -s7, v158, v29
	v_fma_f32 v28, -s8, v140, v28
	v_fma_f32 v24, -s9, v152, v24
	s_nop 0
	s_nop 0
	s_nop 0
	s_nop 0
	s_nop 0
	s_nop 0
	s_nop 0
	s_nop 0
	s_nop 0
	s_nop 0
	s_nop 0
	s_nop 0
	s_nop 0
	s_nop 0
	s_nop 0
	s_nop 0
	s_nop 0
	v_pk_add_f32 v[24:25], v[28:29], v[24:25]
	v_mov_b32_e32 v29, v123
	v_mov_b32_e32 v28, v123
	v_pk_add_f32 v[24:25], v[24:25], v[24:25] op_sel:[0,1] op_sel_hi:[1,0]
	s_nop 0
	s_waitcnt lgkmcnt(0)
	v_sub_f32_e32 v15, v15, v247
	ds_read_b32 v246, v249 offset:4
	s_nop 0
	v_readlane_b32 s6, v198, s15
	v_readlane_b32 s7, v194, s23
	v_readlane_b32 s8, v196, s23
	v_readlane_b32 s9, v195, s23
	v_fma_f32 v15, -s6, v24, v15
	v_fma_f32 v29, -s7, v186, v29
	v_fma_f32 v28, -s8, v62, v28
	v_fma_f32 v14, -s9, v182, v14
	s_nop 0
	s_nop 0
	v_readlane_b32 s6, v198, s23
	v_readlane_b32 s7, v197, s15
	v_readlane_b32 s8, v200, s15
	v_readlane_b32 s9, v199, s15
	v_fma_f32 v15, -s6, v70, v15
	v_fma_f32 v29, -s7, v168, v29
	v_fma_f32 v28, -s8, v78, v28
	v_fma_f32 v14, -s9, v160, v14
	s_nop 0
	s_nop 0
	v_readlane_b32 s6, v202, s15
	v_readlane_b32 s7, v197, s23
	v_readlane_b32 s8, v200, s23
	v_readlane_b32 s9, v199, s23
	v_fma_f32 v15, -s6, v84, v15
	v_fma_f32 v29, -s7, v154, v29
	v_fma_f32 v28, -s8, v184, v28
	v_fma_f32 v14, -s9, v162, v14
	s_nop 0
	s_nop 0
	v_readlane_b32 s6, v202, s23
	v_readlane_b32 s7, v201, s15
	v_readlane_b32 s8, v204, s15
	v_readlane_b32 s9, v203, s15
	v_fma_f32 v15, -s6, v180, v15
	v_fma_f32 v29, -s7, v164, v29
	v_fma_f32 v28, -s8, v172, v28
	v_fma_f32 v14, -s9, v156, v14
	s_nop 0
	s_nop 0
	v_readlane_b32 s6, v206, s15
	v_readlane_b32 s7, v201, s23
	v_readlane_b32 s8, v204, s23
	v_readlane_b32 s9, v203, s23
	v_fma_f32 v15, -s6, v176, v15
	v_fma_f32 v29, -s7, v150, v29
	v_fma_f32 v28, -s8, v178, v28
	v_fma_f32 v14, -s9, v148, v14
	s_nop 0
	s_nop 0
	v_readlane_b32 s6, v206, s23
	v_readlane_b32 s7, v205, s15
	v_readlane_b32 s8, v208, s15
	v_readlane_b32 s9, v207, s15
	v_fma_f32 v15, -s6, v174, v15
	v_fma_f32 v29, -s7, v146, v29
	v_fma_f32 v28, -s8, v170, v28
	v_fma_f32 v14, -s9, v144, v14
	s_nop 0
	s_nop 0
	v_readlane_b32 s6, v209, s15
	v_readlane_b32 s7, v205, s23
	v_readlane_b32 s8, v208, s23
	v_readlane_b32 s9, v207, s23
	v_fma_f32 v15, -s6, v166, v15
	v_fma_f32 v29, -s7, v142, v29
	v_fma_f32 v28, -s8, v158, v28
	v_fma_f32 v14, -s9, v140, v14
	s_nop 0
	s_nop 0
	v_readlane_b32 s6, v209, s23
	s_nop 1
	v_fma_f32 v15, -s6, v152, v15
	s_nop 0
	s_nop 0
	s_nop 0
	s_nop 0
	s_nop 0
	s_nop 0
	s_nop 0
	s_nop 0
	s_nop 0
	s_nop 0
	s_nop 0
	s_nop 0
	s_nop 0
	s_nop 0
	s_nop 0
	s_nop 0
	s_nop 1
	s_nop 0
	v_pk_add_f32 v[14:15], v[28:29], v[14:15]
	s_nop 0
	v_pk_add_f32 v[188:189], v[14:15], v[14:15] op_sel:[0,1] op_sel_hi:[1,0]
	v_mov_b32_e32 v15, v123
	v_mov_b32_e32 v14, v123
	s_waitcnt lgkmcnt(0)
	v_sub_f32_e32 v7, v7, v246
	ds_read_b32 v247, v249 offset:0
	s_nop 0
	v_readlane_b32 s6, v195, s26
	v_readlane_b32 s7, v198, s26
	v_readlane_b32 s8, v194, s10
	v_readlane_b32 s9, v196, s10
	v_fma_f32 v7, -s6, v188, v7
	v_fma_f32 v15, -s7, v24, v15
	v_fma_f32 v14, -s8, v186, v14
	v_fma_f32 v6, -s9, v62, v6
	v_mov_b32_e32 v189, v24
	s_nop 0
	v_readlane_b32 s6, v195, s10
	v_readlane_b32 s7, v198, s10
	v_readlane_b32 s8, v197, s26
	v_readlane_b32 s9, v200, s26
	v_fma_f32 v7, -s6, v182, v7
	v_fma_f32 v15, -s7, v70, v15
	v_fma_f32 v14, -s8, v168, v14
	v_fma_f32 v6, -s9, v78, v6
	s_nop 0
	s_nop 0
	v_readlane_b32 s6, v199, s26
	v_readlane_b32 s7, v202, s26
	v_readlane_b32 s8, v197, s10
	v_readlane_b32 s9, v200, s10
	v_fma_f32 v7, -s6, v160, v7
	v_fma_f32 v15, -s7, v84, v15
	v_fma_f32 v14, -s8, v154, v14
	v_fma_f32 v6, -s9, v184, v6
	s_nop 0
	s_nop 0
	v_readlane_b32 s6, v199, s10
	v_readlane_b32 s7, v202, s10
	v_readlane_b32 s8, v201, s26
	v_readlane_b32 s9, v204, s26
	v_fma_f32 v7, -s6, v162, v7
	v_fma_f32 v15, -s7, v180, v15
	v_fma_f32 v14, -s8, v164, v14
	v_fma_f32 v6, -s9, v172, v6
	s_nop 0
	s_nop 0
	v_readlane_b32 s6, v203, s26
	v_readlane_b32 s7, v206, s26
	v_readlane_b32 s8, v201, s10
	v_readlane_b32 s9, v204, s10
	v_fma_f32 v7, -s6, v156, v7
	v_fma_f32 v15, -s7, v176, v15
	v_fma_f32 v14, -s8, v150, v14
	v_fma_f32 v6, -s9, v178, v6
	s_nop 0
	s_nop 0
	v_readlane_b32 s6, v203, s10
	v_readlane_b32 s7, v206, s10
	v_readlane_b32 s8, v205, s26
	v_readlane_b32 s9, v208, s26
	v_fma_f32 v7, -s6, v148, v7
	v_fma_f32 v15, -s7, v174, v15
	v_fma_f32 v14, -s8, v146, v14
	v_fma_f32 v6, -s9, v170, v6
	s_nop 0
	s_nop 0
	v_readlane_b32 s6, v207, s26
	v_readlane_b32 s7, v209, s26
	v_readlane_b32 s8, v205, s10
	v_readlane_b32 s9, v208, s10
	v_fma_f32 v7, -s6, v144, v7
	v_fma_f32 v15, -s7, v166, v15
	v_fma_f32 v14, -s8, v142, v14
	v_fma_f32 v6, -s9, v158, v6
	s_nop 0
	s_nop 0
	v_readlane_b32 s6, v207, s10
	v_readlane_b32 s7, v209, s10
	s_nop 0
	v_fma_f32 v7, -s6, v140, v7
	v_fma_f32 v15, -s7, v152, v15
	s_nop 0
	s_nop 0
	s_nop 0
	s_nop 0
	s_nop 0
	s_nop 0
	s_nop 0
	s_nop 0
	s_nop 0
	s_nop 0
	s_nop 0
	s_nop 0
	s_nop 0
	s_nop 0
	s_nop 0
	s_nop 0
	s_nop 1
	s_nop 0
	s_nop 0
	s_nop 1
	s_nop 0
	v_pk_add_f32 v[6:7], v[14:15], v[6:7]
	v_mov_b32_e32 v15, v123
	v_mov_b32_e32 v14, v123
	v_pk_add_f32 v[6:7], v[6:7], v[6:7] op_sel:[0,1] op_sel_hi:[1,0]
	s_nop 0
	s_waitcnt lgkmcnt(0)
	v_sub_f32_e32 v3, v3, v247
	s_nop 0
	v_readlane_b32 s6, v196, s13
	v_readlane_b32 s7, v195, s13
	v_readlane_b32 s8, v198, s13
	v_readlane_b32 s9, v194, s31
	v_fma_f32 v3, -s6, v6, v3
	v_fma_f32 v15, -s7, v188, v15
	v_fma_f32 v14, -s8, v24, v14
	v_fma_f32 v2, -s9, v186, v2
	s_nop 0
	s_nop 0
	v_readlane_b32 s6, v196, s31
	v_readlane_b32 s7, v195, s31
	v_readlane_b32 s8, v198, s31
	v_readlane_b32 s9, v197, s13
	v_fma_f32 v3, -s6, v62, v3
	v_fma_f32 v15, -s7, v182, v15
	v_fma_f32 v14, -s8, v70, v14
	v_fma_f32 v2, -s9, v168, v2
	s_nop 0
	s_nop 0
	v_readlane_b32 s6, v200, s13
	v_readlane_b32 s7, v199, s13
	v_readlane_b32 s8, v202, s13
	v_readlane_b32 s9, v197, s31
	v_fma_f32 v3, -s6, v78, v3
	v_fma_f32 v15, -s7, v160, v15
	v_fma_f32 v14, -s8, v84, v14
	v_fma_f32 v2, -s9, v154, v2
	s_nop 0
	s_nop 0
	v_readlane_b32 s6, v200, s31
	v_readlane_b32 s7, v199, s31
	v_readlane_b32 s8, v202, s31
	v_readlane_b32 s9, v201, s13
	v_fma_f32 v3, -s6, v184, v3
	v_fma_f32 v15, -s7, v162, v15
	v_fma_f32 v14, -s8, v180, v14
	v_fma_f32 v2, -s9, v164, v2
	s_nop 0
	s_nop 0
	v_readlane_b32 s6, v204, s13
	v_readlane_b32 s7, v203, s13
	v_readlane_b32 s8, v206, s13
	v_readlane_b32 s9, v201, s31
	v_fma_f32 v3, -s6, v172, v3
	v_fma_f32 v15, -s7, v156, v15
	v_fma_f32 v14, -s8, v176, v14
	v_fma_f32 v2, -s9, v150, v2
	s_nop 0
	s_nop 0
	v_readlane_b32 s6, v204, s31
	v_readlane_b32 s7, v203, s31
	v_readlane_b32 s8, v206, s31
	v_readlane_b32 s9, v205, s13
	v_fma_f32 v3, -s6, v178, v3
	v_fma_f32 v15, -s7, v148, v15
	v_fma_f32 v14, -s8, v174, v14
	v_fma_f32 v2, -s9, v146, v2
	s_nop 0
	s_nop 0
	v_readlane_b32 s6, v208, s13
	v_readlane_b32 s7, v207, s13
	v_readlane_b32 s8, v209, s13
	v_readlane_b32 s9, v205, s31
	v_fma_f32 v3, -s6, v170, v3
	v_fma_f32 v15, -s7, v144, v15
	v_fma_f32 v14, -s8, v166, v14
	v_fma_f32 v2, -s9, v142, v2
	s_nop 0
	s_nop 0
	v_readlane_b32 s6, v208, s31
	v_readlane_b32 s7, v207, s31
	v_readlane_b32 s8, v209, s31
	v_fma_f32 v3, -s6, v158, v3
	v_fma_f32 v15, -s7, v140, v15
	v_fma_f32 v14, -s8, v152, v14
	s_nop 0
	s_nop 0
	s_nop 0
	s_nop 0
	s_nop 0
	s_nop 0
	s_nop 0
	s_nop 0
	s_nop 0
	s_nop 0
	s_nop 0
	s_nop 0
	s_nop 0
	s_nop 0
	s_nop 0
	s_nop 0
	s_nop 1
	s_nop 0
	s_nop 0
	s_nop 1
	s_nop 0
	s_nop 0
	s_nop 1
	s_nop 0
	v_pk_add_f32 v[2:3], v[14:15], v[2:3]
	s_nop 0
	v_pk_add_f32 v[152:153], v[2:3], v[2:3] op_sel:[0,1] op_sel_hi:[1,0]
	v_readlane_b32 s6, v193, 0
	v_readlane_b32 s7, v193, 1
	v_mov_b32_e32 v153, v6
	s_nop 0
	v_pk_mul_f32 v[2:3], v[152:153], s[6:7]
	v_readlane_b32 s6, v193, 8
	v_readlane_b32 s7, v193, 9
	v_cvt_pk_bf16_f32 v62, v2, v3
	s_nop 0
	v_pk_mul_f32 v[4:5], v[168:169], s[6:7]
	v_readlane_b32 s6, v193, 2
	v_readlane_b32 s7, v193, 3
	v_cvt_pk_bf16_f32 v66, v4, v5
	s_nop 1
	v_permlane32_swap_b32_e32 v62, v66
	v_pk_mul_f32 v[6:7], v[188:189], s[6:7]
	v_readlane_b32 s6, v193, 10
	v_readlane_b32 s7, v193, 11
	v_cvt_pk_bf16_f32 v63, v6, v7
	s_nop 0
	v_pk_mul_f32 v[8:9], v[160:161], s[6:7]
	v_readlane_b32 s6, v193, 4
	v_readlane_b32 s7, v193, 5
	v_cvt_pk_bf16_f32 v67, v8, v9
	s_nop 1
	v_permlane32_swap_b32_e32 v63, v67
	v_pk_mul_f32 v[10:11], v[186:187], s[6:7]
	v_readlane_b32 s6, v193, 12
	v_readlane_b32 s7, v193, 13
	v_cvt_pk_bf16_f32 v64, v10, v11
	s_nop 0
	v_pk_mul_f32 v[12:13], v[154:155], s[6:7]
	v_readlane_b32 s6, v193, 6
	v_readlane_b32 s7, v193, 7
	v_cvt_pk_bf16_f32 v68, v12, v13
	s_nop 1
	v_permlane32_swap_b32_e32 v64, v68
	v_pk_mul_f32 v[14:15], v[182:183], s[6:7]
	v_readlane_b32 s6, v193, 14
	v_readlane_b32 s7, v193, 15
	v_cvt_pk_bf16_f32 v65, v14, v15
	s_nop 0
	v_pk_mul_f32 v[16:17], v[162:163], s[6:7]
	v_readlane_b32 s6, v193, 16
	v_readlane_b32 s7, v193, 17
	v_cvt_pk_bf16_f32 v69, v16, v17
	s_nop 1
	v_permlane32_swap_b32_e32 v65, v69
	v_pk_mul_f32 v[2:3], v[164:165], s[6:7]
	v_readlane_b32 s6, v193, 24
	v_readlane_b32 s7, v193, 25
	v_cvt_pk_bf16_f32 v70, v2, v3
	s_nop 0
	v_pk_mul_f32 v[4:5], v[146:147], s[6:7]
	v_readlane_b32 s6, v193, 18
	v_readlane_b32 s7, v193, 19
	v_cvt_pk_bf16_f32 v74, v4, v5
	s_nop 1
	v_permlane32_swap_b32_e32 v70, v74
	v_pk_mul_f32 v[6:7], v[156:157], s[6:7]
	v_readlane_b32 s6, v193, 26
	v_readlane_b32 s7, v193, 27
	v_cvt_pk_bf16_f32 v71, v6, v7
	s_nop 0
	v_pk_mul_f32 v[8:9], v[144:145], s[6:7]
	v_readlane_b32 s6, v193, 20
	v_readlane_b32 s7, v193, 21
	v_cvt_pk_bf16_f32 v75, v8, v9
	s_nop 1
	v_permlane32_swap_b32_e32 v71, v75
	v_pk_mul_f32 v[10:11], v[150:151], s[6:7]
	v_readlane_b32 s6, v193, 28
	v_readlane_b32 s7, v193, 29
	v_cvt_pk_bf16_f32 v72, v10, v11
	s_nop 0
	v_pk_mul_f32 v[12:13], v[142:143], s[6:7]
	v_readlane_b32 s6, v193, 22
	v_readlane_b32 s7, v193, 23
	v_cvt_pk_bf16_f32 v76, v12, v13
	s_nop 1
	v_permlane32_swap_b32_e32 v72, v76
	v_pk_mul_f32 v[14:15], v[148:149], s[6:7]
	v_readlane_b32 s6, v193, 30
	v_readlane_b32 s7, v193, 31
	v_cvt_pk_bf16_f32 v73, v14, v15
	s_nop 0
	v_pk_mul_f32 v[16:17], v[140:141], s[6:7]
	v_readlane_b32 s6, v193, 32
	v_readlane_b32 s7, v193, 33
	v_cvt_pk_bf16_f32 v77, v16, v17
	s_nop 1
	v_permlane32_swap_b32_e32 v73, v77
	v_pk_mul_f32 v[2:3], v[138:139], s[6:7]
	v_readlane_b32 s6, v193, 40
	v_readlane_b32 s7, v193, 41
	v_cvt_pk_bf16_f32 v2, v2, v3
	s_nop 0
	v_pk_mul_f32 v[4:5], v[130:131], s[6:7]
	v_readlane_b32 s6, v193, 34
	v_readlane_b32 s7, v193, 35
	v_cvt_pk_bf16_f32 v78, v4, v5
	s_nop 1
	v_permlane32_swap_b32_e32 v2, v78
	v_pk_mul_f32 v[6:7], v[136:137], s[6:7]
	v_readlane_b32 s6, v193, 42
	v_readlane_b32 s7, v193, 43
	v_cvt_pk_bf16_f32 v3, v6, v7
	s_nop 0
	v_pk_mul_f32 v[8:9], v[128:129], s[6:7]
	v_readlane_b32 s6, v193, 36
	v_readlane_b32 s7, v193, 37
	v_cvt_pk_bf16_f32 v79, v8, v9
	s_nop 1
	v_permlane32_swap_b32_e32 v3, v79
	v_pk_mul_f32 v[10:11], v[134:135], s[6:7]
	v_readlane_b32 s6, v193, 44
	v_readlane_b32 s7, v193, 45
	v_cvt_pk_bf16_f32 v6, v10, v11
	s_nop 0
	v_pk_mul_f32 v[12:13], v[118:119], s[6:7]
	v_readlane_b32 s6, v193, 38
	v_readlane_b32 s7, v193, 39
	v_cvt_pk_bf16_f32 v80, v12, v13
	s_nop 1
	v_permlane32_swap_b32_e32 v6, v80
	v_pk_mul_f32 v[14:15], v[132:133], s[6:7]
	v_readlane_b32 s6, v193, 46
	v_readlane_b32 s7, v193, 47
	v_cvt_pk_bf16_f32 v7, v14, v15
	s_nop 0
	v_pk_mul_f32 v[16:17], v[116:117], s[6:7]
	v_readlane_b32 s6, v193, 48
	v_readlane_b32 s7, v193, 49
	v_cvt_pk_bf16_f32 v81, v16, v17
	s_nop 1
	v_permlane32_swap_b32_e32 v7, v81
	v_pk_mul_f32 v[2:3], v[114:115], s[6:7]
	v_readlane_b32 s6, v193, 56
	v_readlane_b32 s7, v193, 57
	v_cvt_pk_bf16_f32 v2, v2, v3
	s_nop 0
	v_pk_mul_f32 v[4:5], v[94:95], s[6:7]
	v_readlane_b32 s6, v193, 50
	v_readlane_b32 s7, v193, 51
	v_cvt_pk_bf16_f32 v82, v4, v5
	s_nop 1
	v_permlane32_swap_b32_e32 v2, v82
	v_pk_mul_f32 v[6:7], v[110:111], s[6:7]
	v_readlane_b32 s6, v193, 58
	v_readlane_b32 s7, v193, 59
	v_cvt_pk_bf16_f32 v3, v6, v7
	s_nop 0
	v_pk_mul_f32 v[8:9], v[92:93], s[6:7]
	v_readlane_b32 s6, v193, 52
	v_readlane_b32 s7, v193, 53
	v_cvt_pk_bf16_f32 v83, v8, v9
	s_nop 1
	v_permlane32_swap_b32_e32 v3, v83
	v_pk_mul_f32 v[10:11], v[104:105], s[6:7]
	v_readlane_b32 s6, v193, 60
	v_readlane_b32 s7, v193, 61
	v_cvt_pk_bf16_f32 v6, v10, v11
	s_nop 0
	v_pk_mul_f32 v[12:13], v[90:91], s[6:7]
	v_readlane_b32 s6, v193, 54
	v_readlane_b32 s7, v193, 55
	v_cvt_pk_bf16_f32 v84, v12, v13
	s_nop 1
	v_permlane32_swap_b32_e32 v6, v84
	v_pk_mul_f32 v[14:15], v[96:97], s[6:7]
	v_readlane_b32 s6, v193, 62
	v_readlane_b32 s7, v193, 63
	v_cvt_pk_bf16_f32 v7, v14, v15
	s_nop 0
	v_pk_mul_f32 v[16:17], v[88:89], s[6:7]
	s_mov_b32 s7, 0x26400000
	v_cvt_pk_bf16_f32 v85, v16, v17
	s_nop 1
	v_permlane32_swap_b32_e32 v7, v85
	s_waitcnt vmcnt(5)
	v_mfma_f32_32x32x16_bf16 v[2:17], v[62:65], v[18:21], 0
	s_mov_b32 s6, 0x9002000
	v_mfma_f32_32x32x16_bf16 v[18:33], v[66:69], v[18:21], 0
	v_mfma_f32_32x32x16_bf16 v[18:33], v[74:77], v[58:61], v[18:33]
	v_mfma_f32_32x32x16_bf16 v[18:33], v[78:81], v[54:57], v[18:33]
	v_mfma_f32_32x32x16_bf16 v[2:17], v[70:73], v[58:61], v[2:17]
	s_waitcnt vmcnt(4)
	v_mfma_f32_32x32x16_bf16 v[18:33], v[82:85], v[50:53], v[18:33]
	v_add_co_u32_e32 v50, vcc, s7, v126
	s_nop 8
	v_cvt_pk_bf16_f32 v2, v2, v3
	v_cvt_pk_bf16_f32 v3, v4, v5
	v_cvt_pk_bf16_f32 v4, v6, v7
	v_cvt_pk_bf16_f32 v5, v8, v9
	v_addc_co_u32_e32 v51, vcc, 0, v127, vcc
	global_store_dwordx4 v[50:51], v[2:5], off
	v_add_co_u32_e32 v6, vcc, s7, v120
	s_nop 0
	v_cvt_pk_bf16_f32 v2, v10, v11
	v_cvt_pk_bf16_f32 v3, v12, v13
	v_cvt_pk_bf16_f32 v4, v14, v15
	v_cvt_pk_bf16_f32 v5, v16, v17
	global_store_dwordx4 v[50:51], v[2:5], off offset:16
	v_addc_co_u32_e32 v7, vcc, 0, v121, vcc
	s_nop 0
	v_cvt_pk_bf16_f32 v2, v18, v19
	v_cvt_pk_bf16_f32 v3, v20, v21
	v_cvt_pk_bf16_f32 v4, v22, v23
	v_cvt_pk_bf16_f32 v5, v24, v25
	global_store_dwordx4 v[6:7], v[2:5], off
	s_nop 1
	v_cvt_pk_bf16_f32 v2, v26, v27
	v_cvt_pk_bf16_f32 v3, v28, v29
	v_cvt_pk_bf16_f32 v4, v30, v31
	v_cvt_pk_bf16_f32 v5, v32, v33
	global_store_dwordx4 v[6:7], v[2:5], off offset:16
	s_waitcnt vmcnt(7)
	v_mfma_f32_32x32x16_bf16 v[18:33], v[62:65], v[46:49], 0
	v_mfma_f32_32x32x16_bf16 v[2:17], v[66:69], v[46:49], 0
	s_waitcnt vmcnt(6)
	v_mfma_f32_32x32x16_bf16 v[2:17], v[74:77], v[42:45], v[2:17]
	s_waitcnt vmcnt(5)
	v_mfma_f32_32x32x16_bf16 v[2:17], v[78:81], v[38:41], v[2:17]
	s_waitcnt vmcnt(4)
	v_mfma_f32_32x32x16_bf16 v[2:17], v[82:85], v[34:37], v[2:17]
	v_mfma_f32_32x32x16_bf16 v[18:33], v[70:73], v[42:45], v[18:33]
	s_nop 10
	v_cvt_pk_bf16_f32 v2, v2, v3
	v_cvt_pk_bf16_f32 v3, v4, v5
	v_cvt_pk_bf16_f32 v4, v6, v7
	v_add_co_u32_e32 v6, vcc, s7, v112
	v_cvt_pk_bf16_f32 v5, v8, v9
	s_nop 0
	v_addc_co_u32_e32 v7, vcc, 0, v113, vcc
	v_cvt_pk_bf16_f32 v18, v18, v19
	v_cvt_pk_bf16_f32 v19, v20, v21
	v_cvt_pk_bf16_f32 v20, v22, v23
	v_cvt_pk_bf16_f32 v21, v24, v25
	v_add_co_u32_e32 v38, vcc, s6, v98
	global_store_dwordx4 v[50:51], v[18:21], off offset:2048
	s_nop 0
	v_addc_co_u32_e32 v39, vcc, 0, v99, vcc
	v_cvt_pk_bf16_f32 v18, v26, v27
	v_cvt_pk_bf16_f32 v19, v28, v29
	v_cvt_pk_bf16_f32 v20, v30, v31
	v_cvt_pk_bf16_f32 v21, v32, v33
	s_mov_b32 s6, 0x9003000
	global_store_dwordx4 v[50:51], v[18:21], off offset:2064
	global_store_dwordx4 v[6:7], v[2:5], off
	v_add_co_u32_e32 v40, vcc, s6, v98
	s_nop 0
	v_cvt_pk_bf16_f32 v2, v10, v11
	v_cvt_pk_bf16_f32 v3, v12, v13
	v_cvt_pk_bf16_f32 v4, v14, v15
	v_cvt_pk_bf16_f32 v5, v16, v17
	global_store_dwordx4 v[6:7], v[2:5], off offset:16
	v_addc_co_u32_e32 v41, vcc, 0, v99, vcc
	s_nop 0
	s_nop 0
	s_nop 0
	v_mfma_f32_32x32x16_bf16 v[18:33], v[62:65], v[212:215], 0
	v_mfma_f32_32x32x16_bf16 v[2:17], v[66:69], v[212:215], 0
	s_nop 0
	v_mfma_f32_32x32x16_bf16 v[18:33], v[70:73], v[216:219], v[18:33]
	v_mfma_f32_32x32x16_bf16 v[2:17], v[74:77], v[216:219], v[2:17]
	s_nop 0
	s_nop 9
	v_cvt_pk_bf16_f32 v18, v18, v19
	v_cvt_pk_bf16_f32 v19, v20, v21
	v_cvt_pk_bf16_f32 v20, v22, v23
	v_add_co_u32_e32 v22, vcc, s7, v108
	v_cvt_pk_bf16_f32 v21, v24, v25
	s_nop 0
	v_mfma_f32_32x32x16_bf16 v[2:17], v[78:81], v[220:223], v[2:17]
	s_nop 0
	v_addc_co_u32_e32 v23, vcc, 0, v109, vcc
	global_store_dwordx4 v[22:23], v[18:21], off
	s_nop 1
	v_cvt_pk_bf16_f32 v18, v26, v27
	s_nop 0
	v_mfma_f32_32x32x16_bf16 v[2:17], v[82:85], v[224:227], v[2:17]
	v_cvt_pk_bf16_f32 v19, v28, v29
	v_cvt_pk_bf16_f32 v20, v30, v31
	v_cvt_pk_bf16_f32 v21, v32, v33
	global_store_dwordx4 v[22:23], v[18:21], off offset:16
	s_nop 7
	v_cvt_pk_bf16_f32 v2, v2, v3
	v_cvt_pk_bf16_f32 v3, v4, v5
	v_cvt_pk_bf16_f32 v4, v6, v7
	v_add_co_u32_e32 v6, vcc, s7, v106
	v_cvt_pk_bf16_f32 v5, v8, v9
	s_nop 0
	v_addc_co_u32_e32 v7, vcc, 0, v107, vcc
	global_store_dwordx4 v[6:7], v[2:5], off
	s_nop 1
	v_cvt_pk_bf16_f32 v2, v10, v11
	v_cvt_pk_bf16_f32 v3, v12, v13
	v_cvt_pk_bf16_f32 v4, v14, v15
	v_cvt_pk_bf16_f32 v5, v16, v17
	global_store_dwordx4 v[6:7], v[2:5], off offset:16
	s_nop 0
	s_nop 0
	s_nop 0
	s_nop 0
	v_mfma_f32_32x32x16_bf16 v[18:33], v[62:65], v[228:231], 0
	v_mfma_f32_32x32x16_bf16 v[2:17], v[66:69], v[228:231], 0
	s_nop 0
	v_mfma_f32_32x32x16_bf16 v[18:33], v[70:73], v[232:235], v[18:33]
	v_mfma_f32_32x32x16_bf16 v[2:17], v[74:77], v[232:235], v[2:17]
	s_nop 0
	s_nop 9
	v_cvt_pk_bf16_f32 v18, v18, v19
	v_cvt_pk_bf16_f32 v19, v20, v21
	v_cvt_pk_bf16_f32 v20, v22, v23
	v_add_co_u32_e32 v22, vcc, s7, v102
	v_cvt_pk_bf16_f32 v21, v24, v25
	s_nop 0
	v_mfma_f32_32x32x16_bf16 v[2:17], v[78:81], v[236:239], v[2:17]
	s_nop 0
	v_addc_co_u32_e32 v23, vcc, 0, v103, vcc
	global_store_dwordx4 v[22:23], v[18:21], off
	s_nop 1
	v_cvt_pk_bf16_f32 v18, v26, v27
	s_nop 0
	v_mfma_f32_32x32x16_bf16 v[2:17], v[82:85], v[240:243], v[2:17]
	v_cvt_pk_bf16_f32 v19, v28, v29
	v_cvt_pk_bf16_f32 v20, v30, v31
	v_cvt_pk_bf16_f32 v21, v32, v33
	global_store_dwordx4 v[22:23], v[18:21], off offset:16
	s_nop 7
	v_cvt_pk_bf16_f32 v2, v2, v3
	v_cvt_pk_bf16_f32 v3, v4, v5
	v_cvt_pk_bf16_f32 v4, v6, v7
	v_add_co_u32_e32 v6, vcc, s7, v100
	v_cvt_pk_bf16_f32 v5, v8, v9
	s_nop 0
	v_addc_co_u32_e32 v7, vcc, 0, v101, vcc
	global_store_dwordx4 v[6:7], v[2:5], off
	s_nop 1
	v_cvt_pk_bf16_f32 v2, v10, v11
	v_cvt_pk_bf16_f32 v3, v12, v13
	v_cvt_pk_bf16_f32 v4, v14, v15
	v_cvt_pk_bf16_f32 v5, v16, v17
	global_store_dwordx4 v[6:7], v[2:5], off offset:16
	s_lshl_b64 s[96:97], s[4:5], 20
	v_readlane_b32 s98, v250, 3
	s_add_u32 s96, s98, s96
	v_readlane_b32 s98, v250, 4
	s_addc_u32 s97, s98, s97
	v_readlane_b32 s98, v250, 13
	s_lshl_b32 s98, s98, 14
	s_add_u32 s96, s96, s98
	s_addc_u32 s97, s97, 0
	s_add_u32 s96, s96, 0x1000
	s_addc_u32 s97, s97, 0
	v_lshl_add_u64 v[246:247], s[96:97], 0, v[86:87]
	v_lshl_add_u64 v[246:247], v[246:247], 0, v[122:123]
	s_mov_b32 s96, 0x2000
	s_mov_b32 s97, 0
	v_lshl_add_u64 v[248:249], v[246:247], 0, s[96:97]
	global_load_dwordx4 v[224:227], v[246:247], off offset:-4096
	global_load_dwordx4 v[228:231], v[246:247], off offset:-4064
	global_load_dwordx4 v[212:215], v[246:247], off offset:-4032
	global_load_dwordx4 v[216:219], v[246:247], off offset:-4000
	global_load_dwordx4 v[220:223], v[246:247], off
	global_load_dwordx4 v[234:237], v[246:247], off offset:32
	global_load_dwordx4 v[238:241], v[246:247], off offset:64
	global_load_dwordx4 v[242:245], v[246:247], off offset:96
	global_load_dwordx4 v[70:73], v[248:249], off offset:-4096
	global_load_dwordx4 v[74:77], v[248:249], off offset:-4064
	global_load_dwordx4 v[78:81], v[248:249], off offset:-4032
	global_load_dwordx4 v[82:85], v[248:249], off offset:-4000
	global_load_dwordx4 v[98:101], v[248:249], off
	global_load_dwordx4 v[106:109], v[248:249], off offset:32
	global_load_dwordx4 v[194:197], v[248:249], off offset:64
	global_load_dwordx4 v[198:201], v[248:249], off offset:96
	v_readlane_b32 s6, v210, 0
	v_readlane_b32 s7, v210, 1
	s_lshl_b64 s[4:5], s[4:5], 20
	v_readlane_b32 s8, v250, 17
	v_pk_mul_f32 v[2:3], v[152:153], s[6:7]
	v_readlane_b32 s6, v210, 8
	v_readlane_b32 s7, v210, 9
	v_cvt_pk_bf16_f32 v34, v2, v3
	s_nop 0
	v_pk_mul_f32 v[4:5], v[168:169], s[6:7]
	v_readlane_b32 s6, v210, 2
	v_readlane_b32 s7, v210, 3
	v_cvt_pk_bf16_f32 v38, v4, v5
	s_nop 1
	v_permlane32_swap_b32_e32 v34, v38
	v_pk_mul_f32 v[6:7], v[188:189], s[6:7]
	v_readlane_b32 s6, v210, 10
	v_readlane_b32 s7, v210, 11
	v_cvt_pk_bf16_f32 v35, v6, v7
	s_nop 0
	v_pk_mul_f32 v[8:9], v[160:161], s[6:7]
	v_readlane_b32 s6, v210, 4
	v_readlane_b32 s7, v210, 5
	v_cvt_pk_bf16_f32 v39, v8, v9
	s_nop 1
	v_permlane32_swap_b32_e32 v35, v39
	v_pk_mul_f32 v[10:11], v[186:187], s[6:7]
	v_readlane_b32 s6, v210, 12
	v_readlane_b32 s7, v210, 13
	v_cvt_pk_bf16_f32 v36, v10, v11
	s_nop 0
	v_pk_mul_f32 v[12:13], v[154:155], s[6:7]
	v_readlane_b32 s6, v210, 6
	v_readlane_b32 s7, v210, 7
	v_cvt_pk_bf16_f32 v40, v12, v13
	s_nop 1
	v_permlane32_swap_b32_e32 v36, v40
	v_pk_mul_f32 v[14:15], v[182:183], s[6:7]
	v_readlane_b32 s6, v210, 14
	v_readlane_b32 s7, v210, 15
	v_cvt_pk_bf16_f32 v37, v14, v15
	s_nop 0
	v_pk_mul_f32 v[16:17], v[162:163], s[6:7]
	v_readlane_b32 s6, v210, 16
	v_readlane_b32 s7, v210, 17
	v_cvt_pk_bf16_f32 v41, v16, v17
	s_nop 1
	v_permlane32_swap_b32_e32 v37, v41
	v_pk_mul_f32 v[2:3], v[164:165], s[6:7]
	v_readlane_b32 s6, v210, 24
	v_readlane_b32 s7, v210, 25
	v_cvt_pk_bf16_f32 v42, v2, v3
	s_nop 0
	v_pk_mul_f32 v[4:5], v[146:147], s[6:7]
	v_readlane_b32 s6, v210, 18
	v_readlane_b32 s7, v210, 19
	v_cvt_pk_bf16_f32 v46, v4, v5
	s_nop 1
	v_permlane32_swap_b32_e32 v42, v46
	v_pk_mul_f32 v[6:7], v[156:157], s[6:7]
	v_readlane_b32 s6, v210, 26
	v_readlane_b32 s7, v210, 27
	v_cvt_pk_bf16_f32 v43, v6, v7
	s_nop 0
	v_pk_mul_f32 v[8:9], v[144:145], s[6:7]
	v_readlane_b32 s6, v210, 20
	v_readlane_b32 s7, v210, 21
	v_cvt_pk_bf16_f32 v47, v8, v9
	s_nop 1
	v_permlane32_swap_b32_e32 v43, v47
	v_pk_mul_f32 v[10:11], v[150:151], s[6:7]
	v_readlane_b32 s6, v210, 28
	v_readlane_b32 s7, v210, 29
	v_cvt_pk_bf16_f32 v44, v10, v11
	s_nop 0
	v_pk_mul_f32 v[12:13], v[142:143], s[6:7]
	v_readlane_b32 s6, v210, 22
	v_readlane_b32 s7, v210, 23
	v_cvt_pk_bf16_f32 v48, v12, v13
	s_nop 1
	v_permlane32_swap_b32_e32 v44, v48
	v_pk_mul_f32 v[14:15], v[148:149], s[6:7]
	v_readlane_b32 s6, v210, 30
	v_readlane_b32 s7, v210, 31
	v_cvt_pk_bf16_f32 v45, v14, v15
	s_nop 0
	v_pk_mul_f32 v[16:17], v[140:141], s[6:7]
	v_readlane_b32 s6, v210, 32
	v_readlane_b32 s7, v210, 33
	v_cvt_pk_bf16_f32 v49, v16, v17
	s_nop 1
	v_permlane32_swap_b32_e32 v45, v49
	v_pk_mul_f32 v[2:3], v[138:139], s[6:7]
	v_readlane_b32 s6, v210, 40
	v_readlane_b32 s7, v210, 41
	v_cvt_pk_bf16_f32 v2, v2, v3
	s_nop 0
	v_pk_mul_f32 v[4:5], v[130:131], s[6:7]
	v_readlane_b32 s6, v210, 34
	v_readlane_b32 s7, v210, 35
	v_cvt_pk_bf16_f32 v50, v4, v5
	s_nop 1
	v_permlane32_swap_b32_e32 v2, v50
	v_pk_mul_f32 v[6:7], v[136:137], s[6:7]
	v_readlane_b32 s6, v210, 42
	v_readlane_b32 s7, v210, 43
	v_cvt_pk_bf16_f32 v3, v6, v7
	s_nop 0
	v_pk_mul_f32 v[8:9], v[128:129], s[6:7]
	v_readlane_b32 s6, v210, 36
	v_readlane_b32 s7, v210, 37
	v_cvt_pk_bf16_f32 v51, v8, v9
	s_nop 1
	v_permlane32_swap_b32_e32 v3, v51
	v_pk_mul_f32 v[10:11], v[134:135], s[6:7]
	v_readlane_b32 s6, v210, 44
	v_readlane_b32 s7, v210, 45
	v_cvt_pk_bf16_f32 v6, v10, v11
	s_nop 0
	v_pk_mul_f32 v[12:13], v[118:119], s[6:7]
	v_readlane_b32 s6, v210, 38
	v_readlane_b32 s7, v210, 39
	v_cvt_pk_bf16_f32 v52, v12, v13
	s_nop 1
	v_permlane32_swap_b32_e32 v6, v52
	v_pk_mul_f32 v[14:15], v[132:133], s[6:7]
	v_readlane_b32 s6, v210, 46
	v_readlane_b32 s7, v210, 47
	v_cvt_pk_bf16_f32 v7, v14, v15
	s_nop 0
	v_pk_mul_f32 v[16:17], v[116:117], s[6:7]
	v_readlane_b32 s6, v210, 48
	v_readlane_b32 s7, v210, 49
	v_cvt_pk_bf16_f32 v53, v16, v17
	s_nop 1
	v_permlane32_swap_b32_e32 v7, v53
	v_pk_mul_f32 v[2:3], v[114:115], s[6:7]
	v_readlane_b32 s6, v210, 56
	v_readlane_b32 s7, v210, 57
	v_cvt_pk_bf16_f32 v2, v2, v3
	s_nop 0
	v_pk_mul_f32 v[4:5], v[94:95], s[6:7]
	v_readlane_b32 s6, v210, 50
	v_readlane_b32 s7, v210, 51
	v_cvt_pk_bf16_f32 v54, v4, v5
	s_nop 1
	v_permlane32_swap_b32_e32 v2, v54
	v_pk_mul_f32 v[6:7], v[110:111], s[6:7]
	v_readlane_b32 s6, v210, 58
	v_readlane_b32 s7, v210, 59
	v_cvt_pk_bf16_f32 v3, v6, v7
	v_lshlrev_b32_e32 v2, 8, v192
	v_pk_mul_f32 v[8:9], v[92:93], s[6:7]
	v_readlane_b32 s6, v210, 52
	v_readlane_b32 s7, v210, 53
	v_cvt_pk_bf16_f32 v55, v8, v9
	s_nop 1
	v_permlane32_swap_b32_e32 v3, v55
	v_pk_mul_f32 v[10:11], v[104:105], s[6:7]
	v_readlane_b32 s6, v210, 60
	v_readlane_b32 s7, v210, 61
	v_mov_b32_e32 v3, v123
	v_lshl_add_u64 v[2:3], v[2:3], 0, v[124:125]
	v_pk_mul_f32 v[12:13], v[90:91], s[6:7]
	v_readlane_b32 s6, v210, 54
	v_readlane_b32 s7, v210, 55
	v_lshl_add_u64 v[64:65], s[0:1], 0, v[2:3]
	v_cvt_pk_bf16_f32 v6, v10, v11
	v_pk_mul_f32 v[14:15], v[96:97], s[6:7]
	v_readlane_b32 s6, v210, 62
	v_readlane_b32 s7, v210, 63
	v_cvt_pk_bf16_f32 v7, v14, v15
	v_cvt_pk_bf16_f32 v56, v12, v13
	v_pk_mul_f32 v[16:17], v[88:89], s[6:7]
	v_readlane_b32 s6, v250, 3
	s_add_u32 s4, s6, s4
	v_readlane_b32 s6, v250, 4
	s_addc_u32 s5, s6, s5
	v_readlane_b32 s6, v250, 13
	s_lshl_b32 s6, s6, 14
	s_add_u32 s4, s4, s6
	s_addc_u32 s5, s5, 0
	v_lshl_add_u64 v[62:63], s[4:5], 0, v[86:87]
	v_lshl_add_u64 v[66:67], v[62:63], 0, v[122:123]
	v_mov_b32_e32 v142, 0x1000
	v_mov_b32_e32 v143, 0
	v_lshl_add_u64 v[130:131], v[66:67], 0, v[142:143]
	v_lshl_add_u64 v[134:135], v[130:131], 0, v[142:143]
	v_lshl_add_u64 v[138:139], v[134:135], 0, v[142:143]
	s_nop 0
	s_nop 0
	s_nop 0
	s_nop 0
	s_nop 0
	s_nop 0
	s_nop 0
	s_nop 0
	s_nop 0
	s_nop 0
	v_cvt_pk_bf16_f32 v57, v16, v17
	v_permlane32_swap_b32_e32 v6, v56
	s_nop 0
	v_permlane32_swap_b32_e32 v7, v57
	s_nop 0
	s_waitcnt vmcnt(15)
	v_mfma_f32_32x32x16_bf16 v[18:33], v[224:227], v[34:37], 0
	s_mov_b32 s0, 0x2e400000
	v_readlane_b32 s7, v250, 15
	v_mfma_f32_32x32x16_bf16 v[2:17], v[224:227], v[38:41], 0
	s_nop 0
	s_waitcnt vmcnt(14)
	v_mfma_f32_32x32x16_bf16 v[18:33], v[228:231], v[42:45], v[18:33]
	v_mfma_f32_32x32x16_bf16 v[2:17], v[228:231], v[46:49], v[2:17]
	s_nop 0
	s_nop 9
	v_cvt_pk_bf16_f32 v18, v18, v19
	v_cvt_pk_bf16_f32 v19, v20, v21
	s_nop 0
	s_waitcnt vmcnt(13)
	v_mfma_f32_32x32x16_bf16 v[2:17], v[212:215], v[50:53], v[2:17]
	s_nop 0
	s_nop 0
	s_waitcnt vmcnt(12)
	v_mfma_f32_32x32x16_bf16 v[2:17], v[216:219], v[54:57], v[2:17]
	v_add_co_u32_e32 v58, vcc, s0, v64
	s_mov_b32 s0, 0x2e402000
	s_nop 0
	v_addc_co_u32_e32 v59, vcc, 0, v65, vcc
	v_add_co_u32_e32 v60, vcc, s0, v64
	s_nop 6
	v_cvt_pk_bf16_f32 v2, v2, v3
	v_cvt_pk_bf16_f32 v3, v4, v5
	v_addc_co_u32_e32 v61, vcc, 0, v65, vcc
	global_store_dwordx2 v[60:61], v[2:3], off
	v_cvt_pk_bf16_f32 v2, v22, v23
	v_cvt_pk_bf16_f32 v3, v24, v25
	global_store_dwordx2 v[58:59], v[2:3], off offset:16
	v_cvt_pk_bf16_f32 v2, v6, v7
	v_cvt_pk_bf16_f32 v3, v8, v9
	global_store_dwordx2 v[60:61], v[2:3], off offset:16
	v_cvt_pk_bf16_f32 v2, v26, v27
	v_cvt_pk_bf16_f32 v3, v28, v29
	global_store_dwordx2 v[58:59], v[2:3], off offset:32
	v_cvt_pk_bf16_f32 v2, v10, v11
	v_cvt_pk_bf16_f32 v3, v12, v13
	global_store_dwordx2 v[60:61], v[2:3], off offset:32
	v_cvt_pk_bf16_f32 v2, v30, v31
	v_cvt_pk_bf16_f32 v3, v32, v33
	global_store_dwordx2 v[58:59], v[2:3], off offset:48
	v_cvt_pk_bf16_f32 v2, v14, v15
	v_cvt_pk_bf16_f32 v3, v16, v17
	global_store_dwordx2 v[60:61], v[2:3], off offset:48
	v_or_b32_e32 v2, 0x1000, v122
	v_mov_b32_e32 v3, v123
	global_store_dwordx2 v[58:59], v[18:19], off
	v_lshl_add_u64 v[68:69], v[62:63], 0, v[2:3]
	s_nop 0
	s_nop 0
	s_nop 0
	s_nop 0
	s_nop 0
	s_nop 0
	s_nop 0
	s_waitcnt vmcnt(19)
	v_mfma_f32_32x32x16_bf16 v[18:33], v[220:223], v[34:37], 0
	v_readlane_b32 s0, v250, 9
	v_readlane_b32 s1, v250, 10
	s_add_i32 s33, s33, s0
	v_readlane_b32 s0, v250, 5
	v_readlane_b32 s1, v250, 6
	s_add_u32 s24, s24, s0
	s_addc_u32 s25, s25, s1
	v_mfma_f32_32x32x16_bf16 v[2:17], v[220:223], v[38:41], 0
	v_readlane_b32 s0, v250, 7
	v_readlane_b32 s1, v250, 8
	s_add_u32 s28, s28, s0
	s_addc_u32 s29, s29, s1
	v_readlane_b32 s0, v250, 11
	v_readlane_b32 s1, v250, 12
	s_add_u32 s7, s7, s0
	s_nop 0
	s_waitcnt vmcnt(18)
	v_mfma_f32_32x32x16_bf16 v[18:33], v[234:237], v[42:45], v[18:33]
	s_addc_u32 s8, s8, s1
	s_cmpk_lt_i32 s33, 0x2000
	v_mfma_f32_32x32x16_bf16 v[2:17], v[234:237], v[46:49], v[2:17]
	s_nop 0
	s_nop 7
	v_cvt_pk_bf16_f32 v18, v18, v19
	v_cvt_pk_bf16_f32 v19, v20, v21
	s_nop 0
	s_waitcnt vmcnt(17)
	v_mfma_f32_32x32x16_bf16 v[2:17], v[238:241], v[50:53], v[2:17]
	s_nop 0
	s_nop 0
	global_store_dwordx2 v[58:59], v[18:19], off offset:64
	s_nop 0
	s_waitcnt vmcnt(17)
	v_mfma_f32_32x32x16_bf16 v[2:17], v[242:245], v[54:57], v[2:17]
	s_nop 11
	v_cvt_pk_bf16_f32 v2, v2, v3
	v_cvt_pk_bf16_f32 v3, v4, v5
	global_store_dwordx2 v[60:61], v[2:3], off offset:64
	v_cvt_pk_bf16_f32 v2, v22, v23
	v_cvt_pk_bf16_f32 v3, v24, v25
	global_store_dwordx2 v[58:59], v[2:3], off offset:80
	v_cvt_pk_bf16_f32 v2, v6, v7
	v_cvt_pk_bf16_f32 v3, v8, v9
	global_store_dwordx2 v[60:61], v[2:3], off offset:80
	v_cvt_pk_bf16_f32 v2, v26, v27
	v_cvt_pk_bf16_f32 v3, v28, v29
	global_store_dwordx2 v[58:59], v[2:3], off offset:96
	v_cvt_pk_bf16_f32 v2, v10, v11
	v_cvt_pk_bf16_f32 v3, v12, v13
	global_store_dwordx2 v[60:61], v[2:3], off offset:96
	v_cvt_pk_bf16_f32 v2, v30, v31
	v_cvt_pk_bf16_f32 v3, v32, v33
	global_store_dwordx2 v[58:59], v[2:3], off offset:112
	v_cvt_pk_bf16_f32 v2, v14, v15
	v_cvt_pk_bf16_f32 v3, v16, v17
	global_store_dwordx2 v[60:61], v[2:3], off offset:112
	v_or_b32_e32 v2, 0x2000, v122
	v_mov_b32_e32 v3, v123
	v_lshl_add_u64 v[68:69], v[62:63], 0, v[2:3]
	s_nop 0
	s_nop 0
	s_nop 0
	s_nop 0
	s_nop 0
	s_nop 0
	s_nop 0
	s_waitcnt vmcnt(23)
	v_mfma_f32_32x32x16_bf16 v[18:33], v[70:73], v[34:37], 0
	v_or_b32_e32 v122, 0x3000, v122
	v_lshl_add_u64 v[62:63], v[62:63], 0, v[122:123]
	v_mfma_f32_32x32x16_bf16 v[2:17], v[70:73], v[38:41], 0
	s_nop 0
	s_waitcnt vmcnt(22)
	v_mfma_f32_32x32x16_bf16 v[18:33], v[74:77], v[42:45], v[18:33]
	v_mfma_f32_32x32x16_bf16 v[2:17], v[74:77], v[46:49], v[2:17]
	s_nop 0
	s_nop 9
	v_cvt_pk_bf16_f32 v18, v18, v19
	v_cvt_pk_bf16_f32 v19, v20, v21
	s_nop 0
	s_waitcnt vmcnt(21)
	v_mfma_f32_32x32x16_bf16 v[2:17], v[78:81], v[50:53], v[2:17]
	s_nop 0
	s_nop 0
	global_store_dwordx2 v[58:59], v[18:19], off offset:128
	s_nop 0
	s_waitcnt vmcnt(21)
	v_mfma_f32_32x32x16_bf16 v[2:17], v[82:85], v[54:57], v[2:17]
	s_nop 11
	v_cvt_pk_bf16_f32 v2, v2, v3
	v_cvt_pk_bf16_f32 v3, v4, v5
	global_store_dwordx2 v[60:61], v[2:3], off offset:128
	v_cvt_pk_bf16_f32 v2, v22, v23
	v_cvt_pk_bf16_f32 v3, v24, v25
	global_store_dwordx2 v[58:59], v[2:3], off offset:144
	v_cvt_pk_bf16_f32 v2, v6, v7
	v_cvt_pk_bf16_f32 v3, v8, v9
	global_store_dwordx2 v[60:61], v[2:3], off offset:144
	v_cvt_pk_bf16_f32 v2, v26, v27
	v_cvt_pk_bf16_f32 v3, v28, v29
	global_store_dwordx2 v[58:59], v[2:3], off offset:160
	v_cvt_pk_bf16_f32 v2, v10, v11
	v_cvt_pk_bf16_f32 v3, v12, v13
	global_store_dwordx2 v[60:61], v[2:3], off offset:160
	v_cvt_pk_bf16_f32 v2, v30, v31
	v_cvt_pk_bf16_f32 v3, v32, v33
	global_store_dwordx2 v[58:59], v[2:3], off offset:176
	v_cvt_pk_bf16_f32 v2, v14, v15
	v_cvt_pk_bf16_f32 v3, v16, v17
	global_store_dwordx2 v[60:61], v[2:3], off offset:176
	s_nop 0
	s_nop 0
	s_waitcnt vmcnt(27)
	v_mfma_f32_32x32x16_bf16 v[18:33], v[98:101], v[34:37], 0
	s_nop 0
	v_mfma_f32_32x32x16_bf16 v[2:17], v[98:101], v[38:41], 0
	s_nop 0
	s_waitcnt vmcnt(26)
	v_mfma_f32_32x32x16_bf16 v[18:33], v[106:109], v[42:45], v[18:33]
	s_nop 11
	v_cvt_pk_bf16_f32 v18, v18, v19
	v_mfma_f32_32x32x16_bf16 v[2:17], v[106:109], v[46:49], v[2:17]
	s_nop 0
	v_cvt_pk_bf16_f32 v19, v20, v21
	s_nop 0
	s_waitcnt vmcnt(25)
	v_mfma_f32_32x32x16_bf16 v[2:17], v[194:197], v[50:53], v[2:17]
	s_nop 0
	s_nop 0
	global_store_dwordx2 v[58:59], v[18:19], off offset:192
	s_nop 0
	s_waitcnt vmcnt(25)
	v_mfma_f32_32x32x16_bf16 v[2:17], v[198:201], v[54:57], v[2:17]
	s_nop 11
	v_cvt_pk_bf16_f32 v2, v2, v3
	v_cvt_pk_bf16_f32 v3, v4, v5
	global_store_dwordx2 v[60:61], v[2:3], off offset:192
	v_cvt_pk_bf16_f32 v2, v22, v23
	v_cvt_pk_bf16_f32 v3, v24, v25
	global_store_dwordx2 v[58:59], v[2:3], off offset:208
	v_cvt_pk_bf16_f32 v2, v6, v7
	v_cvt_pk_bf16_f32 v3, v8, v9
	global_store_dwordx2 v[60:61], v[2:3], off offset:208
	v_cvt_pk_bf16_f32 v2, v26, v27
	v_cvt_pk_bf16_f32 v3, v28, v29
	global_store_dwordx2 v[58:59], v[2:3], off offset:224
	v_cvt_pk_bf16_f32 v2, v10, v11
	v_cvt_pk_bf16_f32 v3, v12, v13
	global_store_dwordx2 v[60:61], v[2:3], off offset:224
	v_cvt_pk_bf16_f32 v2, v30, v31
	v_cvt_pk_bf16_f32 v3, v32, v33
	global_store_dwordx2 v[58:59], v[2:3], off offset:240
	v_cvt_pk_bf16_f32 v2, v14, v15
	v_cvt_pk_bf16_f32 v3, v16, v17
	global_store_dwordx2 v[60:61], v[2:3], off offset:240
	s_waitcnt lgkmcnt(0)
	s_cbranch_scc0 .LBB0_782
